# all remaining epilogue load ladders batched too (FFN-0 down, attention w_o, SwiGLU rowss, lora-2 bias once per tile) and conversion scale loads hoisted with the weight loads
# baseline (speedup 1.0000x reference)
.LBB0_27:
	s_mul_i32 s2, s17, 0x50
	s_mul_hi_u32 s3, s16, 0x50
	s_add_i32 s3, s3, s2
	s_mul_i32 s2, s16, 0x50
	s_add_u32 s36, s0, s2
	s_addc_u32 s37, s1, s3
	s_load_dword s2, s[36:37], 0x150
	s_load_dword s50, s[36:37], 0x160
	s_load_dword s4, s[36:37], 0x168
	s_load_dwordx4 s[16:19], s[36:37], 0x140
	s_load_dwordx4 s[12:15], s[36:37], 0x120
	s_load_dwordx2 s[40:41], s[36:37], 0x130
	s_waitcnt lgkmcnt(0)
	s_ashr_i32 s3, s2, 31
	s_lshr_b32 s3, s3, 27
	s_add_i32 s2, s2, s3
	s_ashr_i32 s2, s2, 5
	s_abs_i32 s3, s2
	v_cvt_f32_u32_e32 v32, s3
	s_sub_i32 s31, 0, s3
	s_sub_i32 s4, s43, s4
	s_abs_i32 s5, s4
	v_rcp_iflag_f32_e32 v32, v32
	s_xor_b32 s19, s4, s2
	s_ashr_i32 s19, s19, 31
	v_mov_b32_e32 v33, s13
	v_mul_f32_e32 v32, 0x4f7ffffe, v32
	v_cvt_u32_f32_e32 v32, v32
	s_nop 0
	v_readfirstlane_b32 s38, v32
	s_mul_i32 s31, s31, s38
	s_mul_hi_u32 s31, s38, s31
	s_add_i32 s38, s38, s31
	s_mul_hi_u32 s31, s5, s38
	s_mul_i32 s38, s31, s3
	s_sub_i32 s5, s5, s38
	s_add_i32 s39, s31, 1
	s_sub_i32 s38, s5, s3
	s_cmp_ge_u32 s5, s3
	s_cselect_b32 s31, s39, s31
	s_cselect_b32 s5, s38, s5
	s_add_i32 s38, s31, 1
	s_cmp_ge_u32 s5, s3
	s_cselect_b32 s3, s38, s31
	s_xor_b32 s3, s3, s19
	s_sub_i32 s3, s3, s19
	s_mul_i32 s2, s3, s2
	s_sub_i32 s49, s4, s2
	s_lshl_b32 s31, s49, 5
	s_lshl_b32 s38, s3, 6
	v_or_b32_e32 v34, s31, v89
	v_mov_b32_e32 v32, s12
	v_ashrrev_i32_e32 v35, 31, v34
	s_cmp_lg_u64 s[14:15], 0
	v_cmp_gt_i32_e64 s[4:5], s18, v34
	v_lshl_add_u64 v[32:33], v[34:35], 2, v[32:33]
	s_cselect_b64 s[2:3], -1, 0
	v_add_u32_e32 v34, s38, v66
	v_cmp_gt_i32_e32 vcc, s17, v34
	v_cndmask_b32_e64 v36, 0, 1, s[2:3]
	s_and_b64 s[18:19], s[4:5], vcc
	v_mov_b32_e32 v35, 0
	v_cmp_ne_u32_e64 s[2:3], 1, v36
	s_cmp_lg_u64 s[14:15], 0
	s_cselect_b32 s92, 1, 0
	s_cmp_gt_i32 s50, 1
	s_cselect_b32 s93, 1, 0
	v_mov_b32_e32 v236, v34
	v_ashrrev_i32_e32 v237, 31, v34
	v_lshl_add_u64 v[238:239], v[236:237], 2, s[14:15]
	v_lshl_add_u64 v[240:241], v[236:237], 2, s[40:41]
	v_add_u32_e32 v232, 0, v34
	v_cmp_gt_i32_e32 vcc, s17, v232
	s_nop 0
	s_and_b64 s[94:95], s[4:5], vcc
	s_and_saveexec_b64 s[96:97], s[94:95]
	s_cbranch_execz .Lcvpf0_0
	v_mad_i64_i32 v[234:235], s[98:99], s16, v232, 0
	v_lshl_add_u64 v[234:235], v[234:235], 2, v[32:33]
	global_load_dword v200, v[234:235], off
	s_cmp_lg_u32 s92, 0
	s_cbranch_scc0 .Lcvpa0_0
	global_load_dword v128, v[238:239], off
.Lcvpa0_0:
	s_cmp_lg_u32 s93, 0
	s_cbranch_scc0 .Lcvpf0_0
	global_load_dword v160, v[240:241], off
.Lcvpf0_0:
	s_or_b64 exec, exec, s[96:97]
	v_add_u32_e32 v232, 2, v34
	v_cmp_gt_i32_e32 vcc, s17, v232
	s_nop 0
	s_and_b64 s[94:95], s[4:5], vcc
	s_and_saveexec_b64 s[96:97], s[94:95]
	s_cbranch_execz .Lcvpf0_1
	v_mad_i64_i32 v[234:235], s[98:99], s16, v232, 0
	v_lshl_add_u64 v[234:235], v[234:235], 2, v[32:33]
	global_load_dword v201, v[234:235], off
	s_cmp_lg_u32 s92, 0
	s_cbranch_scc0 .Lcvpa0_1
	global_load_dword v129, v[238:239], off offset:8
.Lcvpa0_1:
	s_cmp_lg_u32 s93, 0
	s_cbranch_scc0 .Lcvpf0_1
	global_load_dword v161, v[240:241], off offset:8
.Lcvpf0_1:
	s_or_b64 exec, exec, s[96:97]
	v_add_u32_e32 v232, 4, v34
	v_cmp_gt_i32_e32 vcc, s17, v232
	s_nop 0
	s_and_b64 s[94:95], s[4:5], vcc
	s_and_saveexec_b64 s[96:97], s[94:95]
	s_cbranch_execz .Lcvpf0_2
	v_mad_i64_i32 v[234:235], s[98:99], s16, v232, 0
	v_lshl_add_u64 v[234:235], v[234:235], 2, v[32:33]
	global_load_dword v202, v[234:235], off
	s_cmp_lg_u32 s92, 0
	s_cbranch_scc0 .Lcvpa0_2
	global_load_dword v130, v[238:239], off offset:16
.Lcvpa0_2:
	s_cmp_lg_u32 s93, 0
	s_cbranch_scc0 .Lcvpf0_2
	global_load_dword v162, v[240:241], off offset:16
.Lcvpf0_2:
	s_or_b64 exec, exec, s[96:97]
	v_add_u32_e32 v232, 6, v34
	v_cmp_gt_i32_e32 vcc, s17, v232
	s_nop 0
	s_and_b64 s[94:95], s[4:5], vcc
	s_and_saveexec_b64 s[96:97], s[94:95]
	s_cbranch_execz .Lcvpf0_3
	v_mad_i64_i32 v[234:235], s[98:99], s16, v232, 0
	v_lshl_add_u64 v[234:235], v[234:235], 2, v[32:33]
	global_load_dword v203, v[234:235], off
	s_cmp_lg_u32 s92, 0
	s_cbranch_scc0 .Lcvpa0_3
	global_load_dword v131, v[238:239], off offset:24
.Lcvpa0_3:
	s_cmp_lg_u32 s93, 0
	s_cbranch_scc0 .Lcvpf0_3
	global_load_dword v163, v[240:241], off offset:24
.Lcvpf0_3:
	s_or_b64 exec, exec, s[96:97]
	v_add_u32_e32 v232, 8, v34
	v_cmp_gt_i32_e32 vcc, s17, v232
	s_nop 0
	s_and_b64 s[94:95], s[4:5], vcc
	s_and_saveexec_b64 s[96:97], s[94:95]
	s_cbranch_execz .Lcvpf0_4
	v_mad_i64_i32 v[234:235], s[98:99], s16, v232, 0
	v_lshl_add_u64 v[234:235], v[234:235], 2, v[32:33]
	global_load_dword v204, v[234:235], off
	s_cmp_lg_u32 s92, 0
	s_cbranch_scc0 .Lcvpa0_4
	global_load_dword v132, v[238:239], off offset:32
.Lcvpa0_4:
	s_cmp_lg_u32 s93, 0
	s_cbranch_scc0 .Lcvpf0_4
	global_load_dword v164, v[240:241], off offset:32
.Lcvpf0_4:
	s_or_b64 exec, exec, s[96:97]
	v_add_u32_e32 v232, 10, v34
	v_cmp_gt_i32_e32 vcc, s17, v232
	s_nop 0
	s_and_b64 s[94:95], s[4:5], vcc
	s_and_saveexec_b64 s[96:97], s[94:95]
	s_cbranch_execz .Lcvpf0_5
	v_mad_i64_i32 v[234:235], s[98:99], s16, v232, 0
	v_lshl_add_u64 v[234:235], v[234:235], 2, v[32:33]
	global_load_dword v205, v[234:235], off
	s_cmp_lg_u32 s92, 0
	s_cbranch_scc0 .Lcvpa0_5
	global_load_dword v133, v[238:239], off offset:40
.Lcvpa0_5:
	s_cmp_lg_u32 s93, 0
	s_cbranch_scc0 .Lcvpf0_5
	global_load_dword v165, v[240:241], off offset:40
.Lcvpf0_5:
	s_or_b64 exec, exec, s[96:97]
	v_add_u32_e32 v232, 12, v34
	v_cmp_gt_i32_e32 vcc, s17, v232
	s_nop 0
	s_and_b64 s[94:95], s[4:5], vcc
	s_and_saveexec_b64 s[96:97], s[94:95]
	s_cbranch_execz .Lcvpf0_6
	v_mad_i64_i32 v[234:235], s[98:99], s16, v232, 0
	v_lshl_add_u64 v[234:235], v[234:235], 2, v[32:33]
	global_load_dword v206, v[234:235], off
	s_cmp_lg_u32 s92, 0
	s_cbranch_scc0 .Lcvpa0_6
	global_load_dword v134, v[238:239], off offset:48
.Lcvpa0_6:
	s_cmp_lg_u32 s93, 0
	s_cbranch_scc0 .Lcvpf0_6
	global_load_dword v166, v[240:241], off offset:48
.Lcvpf0_6:
	s_or_b64 exec, exec, s[96:97]
	v_add_u32_e32 v232, 14, v34
	v_cmp_gt_i32_e32 vcc, s17, v232
	s_nop 0
	s_and_b64 s[94:95], s[4:5], vcc
	s_and_saveexec_b64 s[96:97], s[94:95]
	s_cbranch_execz .Lcvpf0_7
	v_mad_i64_i32 v[234:235], s[98:99], s16, v232, 0
	v_lshl_add_u64 v[234:235], v[234:235], 2, v[32:33]
	global_load_dword v207, v[234:235], off
	s_cmp_lg_u32 s92, 0
	s_cbranch_scc0 .Lcvpa0_7
	global_load_dword v135, v[238:239], off offset:56
.Lcvpa0_7:
	s_cmp_lg_u32 s93, 0
	s_cbranch_scc0 .Lcvpf0_7
	global_load_dword v167, v[240:241], off offset:56
.Lcvpf0_7:
	s_or_b64 exec, exec, s[96:97]
	v_add_u32_e32 v232, 16, v34
	v_cmp_gt_i32_e32 vcc, s17, v232
	s_nop 0
	s_and_b64 s[94:95], s[4:5], vcc
	s_and_saveexec_b64 s[96:97], s[94:95]
	s_cbranch_execz .Lcvpf0_8
	v_mad_i64_i32 v[234:235], s[98:99], s16, v232, 0
	v_lshl_add_u64 v[234:235], v[234:235], 2, v[32:33]
	global_load_dword v208, v[234:235], off
	s_cmp_lg_u32 s92, 0
	s_cbranch_scc0 .Lcvpa0_8
	global_load_dword v136, v[238:239], off offset:64
.Lcvpa0_8:
	s_cmp_lg_u32 s93, 0
	s_cbranch_scc0 .Lcvpf0_8
	global_load_dword v168, v[240:241], off offset:64
.Lcvpf0_8:
	s_or_b64 exec, exec, s[96:97]
	v_add_u32_e32 v232, 18, v34
	v_cmp_gt_i32_e32 vcc, s17, v232
	s_nop 0
	s_and_b64 s[94:95], s[4:5], vcc
	s_and_saveexec_b64 s[96:97], s[94:95]
	s_cbranch_execz .Lcvpf0_9
	v_mad_i64_i32 v[234:235], s[98:99], s16, v232, 0
	v_lshl_add_u64 v[234:235], v[234:235], 2, v[32:33]
	global_load_dword v209, v[234:235], off
	s_cmp_lg_u32 s92, 0
	s_cbranch_scc0 .Lcvpa0_9
	global_load_dword v137, v[238:239], off offset:72
.Lcvpa0_9:
	s_cmp_lg_u32 s93, 0
	s_cbranch_scc0 .Lcvpf0_9
	global_load_dword v169, v[240:241], off offset:72
.Lcvpf0_9:
	s_or_b64 exec, exec, s[96:97]
	v_add_u32_e32 v232, 20, v34
	v_cmp_gt_i32_e32 vcc, s17, v232
	s_nop 0
	s_and_b64 s[94:95], s[4:5], vcc
	s_and_saveexec_b64 s[96:97], s[94:95]
	s_cbranch_execz .Lcvpf0_10
	v_mad_i64_i32 v[234:235], s[98:99], s16, v232, 0
	v_lshl_add_u64 v[234:235], v[234:235], 2, v[32:33]
	global_load_dword v210, v[234:235], off
	s_cmp_lg_u32 s92, 0
	s_cbranch_scc0 .Lcvpa0_10
	global_load_dword v138, v[238:239], off offset:80
.Lcvpa0_10:
	s_cmp_lg_u32 s93, 0
	s_cbranch_scc0 .Lcvpf0_10
	global_load_dword v170, v[240:241], off offset:80
.Lcvpf0_10:
	s_or_b64 exec, exec, s[96:97]
	v_add_u32_e32 v232, 22, v34
	v_cmp_gt_i32_e32 vcc, s17, v232
	s_nop 0
	s_and_b64 s[94:95], s[4:5], vcc
	s_and_saveexec_b64 s[96:97], s[94:95]
	s_cbranch_execz .Lcvpf0_11
	v_mad_i64_i32 v[234:235], s[98:99], s16, v232, 0
	v_lshl_add_u64 v[234:235], v[234:235], 2, v[32:33]
	global_load_dword v211, v[234:235], off
	s_cmp_lg_u32 s92, 0
	s_cbranch_scc0 .Lcvpa0_11
	global_load_dword v139, v[238:239], off offset:88
.Lcvpa0_11:
	s_cmp_lg_u32 s93, 0
	s_cbranch_scc0 .Lcvpf0_11
	global_load_dword v171, v[240:241], off offset:88
.Lcvpf0_11:
	s_or_b64 exec, exec, s[96:97]
	v_add_u32_e32 v232, 24, v34
	v_cmp_gt_i32_e32 vcc, s17, v232
	s_nop 0
	s_and_b64 s[94:95], s[4:5], vcc
	s_and_saveexec_b64 s[96:97], s[94:95]
	s_cbranch_execz .Lcvpf0_12
	v_mad_i64_i32 v[234:235], s[98:99], s16, v232, 0
	v_lshl_add_u64 v[234:235], v[234:235], 2, v[32:33]
	global_load_dword v212, v[234:235], off
	s_cmp_lg_u32 s92, 0
	s_cbranch_scc0 .Lcvpa0_12
	global_load_dword v140, v[238:239], off offset:96
.Lcvpa0_12:
	s_cmp_lg_u32 s93, 0
	s_cbranch_scc0 .Lcvpf0_12
	global_load_dword v172, v[240:241], off offset:96
.Lcvpf0_12:
	s_or_b64 exec, exec, s[96:97]
	v_add_u32_e32 v232, 26, v34
	v_cmp_gt_i32_e32 vcc, s17, v232
	s_nop 0
	s_and_b64 s[94:95], s[4:5], vcc
	s_and_saveexec_b64 s[96:97], s[94:95]
	s_cbranch_execz .Lcvpf0_13
	v_mad_i64_i32 v[234:235], s[98:99], s16, v232, 0
	v_lshl_add_u64 v[234:235], v[234:235], 2, v[32:33]
	global_load_dword v213, v[234:235], off
	s_cmp_lg_u32 s92, 0
	s_cbranch_scc0 .Lcvpa0_13
	global_load_dword v141, v[238:239], off offset:104
.Lcvpa0_13:
	s_cmp_lg_u32 s93, 0
	s_cbranch_scc0 .Lcvpf0_13
	global_load_dword v173, v[240:241], off offset:104
.Lcvpf0_13:
	s_or_b64 exec, exec, s[96:97]
	v_add_u32_e32 v232, 28, v34
	v_cmp_gt_i32_e32 vcc, s17, v232
	s_nop 0
	s_and_b64 s[94:95], s[4:5], vcc
	s_and_saveexec_b64 s[96:97], s[94:95]
	s_cbranch_execz .Lcvpf0_14
	v_mad_i64_i32 v[234:235], s[98:99], s16, v232, 0
	v_lshl_add_u64 v[234:235], v[234:235], 2, v[32:33]
	global_load_dword v214, v[234:235], off
	s_cmp_lg_u32 s92, 0
	s_cbranch_scc0 .Lcvpa0_14
	global_load_dword v142, v[238:239], off offset:112
.Lcvpa0_14:
	s_cmp_lg_u32 s93, 0
	s_cbranch_scc0 .Lcvpf0_14
	global_load_dword v174, v[240:241], off offset:112
.Lcvpf0_14:
	s_or_b64 exec, exec, s[96:97]
	v_add_u32_e32 v232, 30, v34
	v_cmp_gt_i32_e32 vcc, s17, v232
	s_nop 0
	s_and_b64 s[94:95], s[4:5], vcc
	s_and_saveexec_b64 s[96:97], s[94:95]
	s_cbranch_execz .Lcvpf0_15
	v_mad_i64_i32 v[234:235], s[98:99], s16, v232, 0
	v_lshl_add_u64 v[234:235], v[234:235], 2, v[32:33]
	global_load_dword v215, v[234:235], off
	s_cmp_lg_u32 s92, 0
	s_cbranch_scc0 .Lcvpa0_15
	global_load_dword v143, v[238:239], off offset:120
.Lcvpa0_15:
	s_cmp_lg_u32 s93, 0
	s_cbranch_scc0 .Lcvpf0_15
	global_load_dword v175, v[240:241], off offset:120
.Lcvpf0_15:
	s_or_b64 exec, exec, s[96:97]
	v_add_u32_e32 v232, 32, v34
	v_cmp_gt_i32_e32 vcc, s17, v232
	s_nop 0
	s_and_b64 s[94:95], s[4:5], vcc
	s_and_saveexec_b64 s[96:97], s[94:95]
	s_cbranch_execz .Lcvpf0_16
	v_mad_i64_i32 v[234:235], s[98:99], s16, v232, 0
	v_lshl_add_u64 v[234:235], v[234:235], 2, v[32:33]
	global_load_dword v216, v[234:235], off
	s_cmp_lg_u32 s92, 0
	s_cbranch_scc0 .Lcvpa0_16
	global_load_dword v144, v[238:239], off offset:128
.Lcvpa0_16:
	s_cmp_lg_u32 s93, 0
	s_cbranch_scc0 .Lcvpf0_16
	global_load_dword v176, v[240:241], off offset:128
.Lcvpf0_16:
	s_or_b64 exec, exec, s[96:97]
	v_add_u32_e32 v232, 34, v34
	v_cmp_gt_i32_e32 vcc, s17, v232
	s_nop 0
	s_and_b64 s[94:95], s[4:5], vcc
	s_and_saveexec_b64 s[96:97], s[94:95]
	s_cbranch_execz .Lcvpf0_17
	v_mad_i64_i32 v[234:235], s[98:99], s16, v232, 0
	v_lshl_add_u64 v[234:235], v[234:235], 2, v[32:33]
	global_load_dword v217, v[234:235], off
	s_cmp_lg_u32 s92, 0
	s_cbranch_scc0 .Lcvpa0_17
	global_load_dword v145, v[238:239], off offset:136
.Lcvpa0_17:
	s_cmp_lg_u32 s93, 0
	s_cbranch_scc0 .Lcvpf0_17
	global_load_dword v177, v[240:241], off offset:136
.Lcvpf0_17:
	s_or_b64 exec, exec, s[96:97]
	v_add_u32_e32 v232, 36, v34
	v_cmp_gt_i32_e32 vcc, s17, v232
	s_nop 0
	s_and_b64 s[94:95], s[4:5], vcc
	s_and_saveexec_b64 s[96:97], s[94:95]
	s_cbranch_execz .Lcvpf0_18
	v_mad_i64_i32 v[234:235], s[98:99], s16, v232, 0
	v_lshl_add_u64 v[234:235], v[234:235], 2, v[32:33]
	global_load_dword v218, v[234:235], off
	s_cmp_lg_u32 s92, 0
	s_cbranch_scc0 .Lcvpa0_18
	global_load_dword v146, v[238:239], off offset:144
.Lcvpa0_18:
	s_cmp_lg_u32 s93, 0
	s_cbranch_scc0 .Lcvpf0_18
	global_load_dword v178, v[240:241], off offset:144
.Lcvpf0_18:
	s_or_b64 exec, exec, s[96:97]
	v_add_u32_e32 v232, 38, v34
	v_cmp_gt_i32_e32 vcc, s17, v232
	s_nop 0
	s_and_b64 s[94:95], s[4:5], vcc
	s_and_saveexec_b64 s[96:97], s[94:95]
	s_cbranch_execz .Lcvpf0_19
	v_mad_i64_i32 v[234:235], s[98:99], s16, v232, 0
	v_lshl_add_u64 v[234:235], v[234:235], 2, v[32:33]
	global_load_dword v219, v[234:235], off
	s_cmp_lg_u32 s92, 0
	s_cbranch_scc0 .Lcvpa0_19
	global_load_dword v147, v[238:239], off offset:152
.Lcvpa0_19:
	s_cmp_lg_u32 s93, 0
	s_cbranch_scc0 .Lcvpf0_19
	global_load_dword v179, v[240:241], off offset:152
.Lcvpf0_19:
	s_or_b64 exec, exec, s[96:97]
	v_add_u32_e32 v232, 40, v34
	v_cmp_gt_i32_e32 vcc, s17, v232
	s_nop 0
	s_and_b64 s[94:95], s[4:5], vcc
	s_and_saveexec_b64 s[96:97], s[94:95]
	s_cbranch_execz .Lcvpf0_20
	v_mad_i64_i32 v[234:235], s[98:99], s16, v232, 0
	v_lshl_add_u64 v[234:235], v[234:235], 2, v[32:33]
	global_load_dword v220, v[234:235], off
	s_cmp_lg_u32 s92, 0
	s_cbranch_scc0 .Lcvpa0_20
	global_load_dword v148, v[238:239], off offset:160
.Lcvpa0_20:
	s_cmp_lg_u32 s93, 0
	s_cbranch_scc0 .Lcvpf0_20
	global_load_dword v180, v[240:241], off offset:160
.Lcvpf0_20:
	s_or_b64 exec, exec, s[96:97]
	v_add_u32_e32 v232, 42, v34
	v_cmp_gt_i32_e32 vcc, s17, v232
	s_nop 0
	s_and_b64 s[94:95], s[4:5], vcc
	s_and_saveexec_b64 s[96:97], s[94:95]
	s_cbranch_execz .Lcvpf0_21
	v_mad_i64_i32 v[234:235], s[98:99], s16, v232, 0
	v_lshl_add_u64 v[234:235], v[234:235], 2, v[32:33]
	global_load_dword v221, v[234:235], off
	s_cmp_lg_u32 s92, 0
	s_cbranch_scc0 .Lcvpa0_21
	global_load_dword v149, v[238:239], off offset:168
.Lcvpa0_21:
	s_cmp_lg_u32 s93, 0
	s_cbranch_scc0 .Lcvpf0_21
	global_load_dword v181, v[240:241], off offset:168
.Lcvpf0_21:
	s_or_b64 exec, exec, s[96:97]
	v_add_u32_e32 v232, 44, v34
	v_cmp_gt_i32_e32 vcc, s17, v232
	s_nop 0
	s_and_b64 s[94:95], s[4:5], vcc
	s_and_saveexec_b64 s[96:97], s[94:95]
	s_cbranch_execz .Lcvpf0_22
	v_mad_i64_i32 v[234:235], s[98:99], s16, v232, 0
	v_lshl_add_u64 v[234:235], v[234:235], 2, v[32:33]
	global_load_dword v222, v[234:235], off
	s_cmp_lg_u32 s92, 0
	s_cbranch_scc0 .Lcvpa0_22
	global_load_dword v150, v[238:239], off offset:176
.Lcvpa0_22:
	s_cmp_lg_u32 s93, 0
	s_cbranch_scc0 .Lcvpf0_22
	global_load_dword v182, v[240:241], off offset:176
.Lcvpf0_22:
	s_or_b64 exec, exec, s[96:97]
	v_add_u32_e32 v232, 46, v34
	v_cmp_gt_i32_e32 vcc, s17, v232
	s_nop 0
	s_and_b64 s[94:95], s[4:5], vcc
	s_and_saveexec_b64 s[96:97], s[94:95]
	s_cbranch_execz .Lcvpf0_23
	v_mad_i64_i32 v[234:235], s[98:99], s16, v232, 0
	v_lshl_add_u64 v[234:235], v[234:235], 2, v[32:33]
	global_load_dword v223, v[234:235], off
	s_cmp_lg_u32 s92, 0
	s_cbranch_scc0 .Lcvpa0_23
	global_load_dword v151, v[238:239], off offset:184
.Lcvpa0_23:
	s_cmp_lg_u32 s93, 0
	s_cbranch_scc0 .Lcvpf0_23
	global_load_dword v183, v[240:241], off offset:184
.Lcvpf0_23:
	s_or_b64 exec, exec, s[96:97]
	v_add_u32_e32 v232, 48, v34
	v_cmp_gt_i32_e32 vcc, s17, v232
	s_nop 0
	s_and_b64 s[94:95], s[4:5], vcc
	s_and_saveexec_b64 s[96:97], s[94:95]
	s_cbranch_execz .Lcvpf0_24
	v_mad_i64_i32 v[234:235], s[98:99], s16, v232, 0
	v_lshl_add_u64 v[234:235], v[234:235], 2, v[32:33]
	global_load_dword v224, v[234:235], off
	s_cmp_lg_u32 s92, 0
	s_cbranch_scc0 .Lcvpa0_24
	global_load_dword v152, v[238:239], off offset:192
.Lcvpa0_24:
	s_cmp_lg_u32 s93, 0
	s_cbranch_scc0 .Lcvpf0_24
	global_load_dword v184, v[240:241], off offset:192
.Lcvpf0_24:
	s_or_b64 exec, exec, s[96:97]
	v_add_u32_e32 v232, 50, v34
	v_cmp_gt_i32_e32 vcc, s17, v232
	s_nop 0
	s_and_b64 s[94:95], s[4:5], vcc
	s_and_saveexec_b64 s[96:97], s[94:95]
	s_cbranch_execz .Lcvpf0_25
	v_mad_i64_i32 v[234:235], s[98:99], s16, v232, 0
	v_lshl_add_u64 v[234:235], v[234:235], 2, v[32:33]
	global_load_dword v225, v[234:235], off
	s_cmp_lg_u32 s92, 0
	s_cbranch_scc0 .Lcvpa0_25
	global_load_dword v153, v[238:239], off offset:200
.Lcvpa0_25:
	s_cmp_lg_u32 s93, 0
	s_cbranch_scc0 .Lcvpf0_25
	global_load_dword v185, v[240:241], off offset:200
.Lcvpf0_25:
	s_or_b64 exec, exec, s[96:97]
	v_add_u32_e32 v232, 52, v34
	v_cmp_gt_i32_e32 vcc, s17, v232
	s_nop 0
	s_and_b64 s[94:95], s[4:5], vcc
	s_and_saveexec_b64 s[96:97], s[94:95]
	s_cbranch_execz .Lcvpf0_26
	v_mad_i64_i32 v[234:235], s[98:99], s16, v232, 0
	v_lshl_add_u64 v[234:235], v[234:235], 2, v[32:33]
	global_load_dword v226, v[234:235], off
	s_cmp_lg_u32 s92, 0
	s_cbranch_scc0 .Lcvpa0_26
	global_load_dword v154, v[238:239], off offset:208
.Lcvpa0_26:
	s_cmp_lg_u32 s93, 0
	s_cbranch_scc0 .Lcvpf0_26
	global_load_dword v186, v[240:241], off offset:208
.Lcvpf0_26:
	s_or_b64 exec, exec, s[96:97]
	v_add_u32_e32 v232, 54, v34
	v_cmp_gt_i32_e32 vcc, s17, v232
	s_nop 0
	s_and_b64 s[94:95], s[4:5], vcc
	s_and_saveexec_b64 s[96:97], s[94:95]
	s_cbranch_execz .Lcvpf0_27
	v_mad_i64_i32 v[234:235], s[98:99], s16, v232, 0
	v_lshl_add_u64 v[234:235], v[234:235], 2, v[32:33]
	global_load_dword v227, v[234:235], off
	s_cmp_lg_u32 s92, 0
	s_cbranch_scc0 .Lcvpa0_27
	global_load_dword v155, v[238:239], off offset:216
.Lcvpa0_27:
	s_cmp_lg_u32 s93, 0
	s_cbranch_scc0 .Lcvpf0_27
	global_load_dword v187, v[240:241], off offset:216
.Lcvpf0_27:
	s_or_b64 exec, exec, s[96:97]
	v_add_u32_e32 v232, 56, v34
	v_cmp_gt_i32_e32 vcc, s17, v232
	s_nop 0
	s_and_b64 s[94:95], s[4:5], vcc
	s_and_saveexec_b64 s[96:97], s[94:95]
	s_cbranch_execz .Lcvpf0_28
	v_mad_i64_i32 v[234:235], s[98:99], s16, v232, 0
	v_lshl_add_u64 v[234:235], v[234:235], 2, v[32:33]
	global_load_dword v228, v[234:235], off
	s_cmp_lg_u32 s92, 0
	s_cbranch_scc0 .Lcvpa0_28
	global_load_dword v156, v[238:239], off offset:224
.Lcvpa0_28:
	s_cmp_lg_u32 s93, 0
	s_cbranch_scc0 .Lcvpf0_28
	global_load_dword v188, v[240:241], off offset:224
.Lcvpf0_28:
	s_or_b64 exec, exec, s[96:97]
	v_add_u32_e32 v232, 58, v34
	v_cmp_gt_i32_e32 vcc, s17, v232
	s_nop 0
	s_and_b64 s[94:95], s[4:5], vcc
	s_and_saveexec_b64 s[96:97], s[94:95]
	s_cbranch_execz .Lcvpf0_29
	v_mad_i64_i32 v[234:235], s[98:99], s16, v232, 0
	v_lshl_add_u64 v[234:235], v[234:235], 2, v[32:33]
	global_load_dword v229, v[234:235], off
	s_cmp_lg_u32 s92, 0
	s_cbranch_scc0 .Lcvpa0_29
	global_load_dword v157, v[238:239], off offset:232
.Lcvpa0_29:
	s_cmp_lg_u32 s93, 0
	s_cbranch_scc0 .Lcvpf0_29
	global_load_dword v189, v[240:241], off offset:232
.Lcvpf0_29:
	s_or_b64 exec, exec, s[96:97]
	v_add_u32_e32 v232, 60, v34
	v_cmp_gt_i32_e32 vcc, s17, v232
	s_nop 0
	s_and_b64 s[94:95], s[4:5], vcc
	s_and_saveexec_b64 s[96:97], s[94:95]
	s_cbranch_execz .Lcvpf0_30
	v_mad_i64_i32 v[234:235], s[98:99], s16, v232, 0
	v_lshl_add_u64 v[234:235], v[234:235], 2, v[32:33]
	global_load_dword v230, v[234:235], off
	s_cmp_lg_u32 s92, 0
	s_cbranch_scc0 .Lcvpa0_30
	global_load_dword v158, v[238:239], off offset:240
.Lcvpa0_30:
	s_cmp_lg_u32 s93, 0
	s_cbranch_scc0 .Lcvpf0_30
	global_load_dword v190, v[240:241], off offset:240
.Lcvpf0_30:
	s_or_b64 exec, exec, s[96:97]
	v_add_u32_e32 v232, 62, v34
	v_cmp_gt_i32_e32 vcc, s17, v232
	s_nop 0
	s_and_b64 s[94:95], s[4:5], vcc
	s_and_saveexec_b64 s[96:97], s[94:95]
	s_cbranch_execz .Lcvpf0_31
	v_mad_i64_i32 v[234:235], s[98:99], s16, v232, 0
	v_lshl_add_u64 v[234:235], v[234:235], 2, v[32:33]
	global_load_dword v231, v[234:235], off
	s_cmp_lg_u32 s92, 0
	s_cbranch_scc0 .Lcvpa0_31
	global_load_dword v159, v[238:239], off offset:248
.Lcvpa0_31:
	s_cmp_lg_u32 s93, 0
	s_cbranch_scc0 .Lcvpf0_31
	global_load_dword v191, v[240:241], off offset:248
.Lcvpf0_31:
	s_or_b64 exec, exec, s[96:97]
	s_and_saveexec_b64 s[12:13], s[18:19]
	s_cbranch_execz .LBB0_39
	s_waitcnt vmcnt(0)
	v_mov_b32_e32 v36, v200
	s_and_b64 vcc, exec, s[2:3]
	v_ashrrev_i32_e32 v35, 31, v34
	s_cbranch_vccnz .LBB0_31
	v_lshl_add_u64 v[38:39], v[34:35], 2, s[14:15]
	v_mov_b32_e32 v37, v128
	s_cmp_lt_i32 s50, 3
	s_mov_b64 s[18:19], -1
	s_cbranch_scc0 .LBB0_32

.LBB0_32:
	s_cmp_eq_u32 s50, 3
	s_waitcnt vmcnt(0)
	v_mov_b32_e32 v38, v37
	s_cbranch_scc0 .LBB0_34
	v_lshl_add_u64 v[38:39], v[34:35], 2, s[40:41]
	v_mov_b32_e32 v38, v160
	s_waitcnt vmcnt(0)
	v_mul_f32_e32 v38, v37, v38

.LBB0_35:
	s_cmp_lg_u32 s50, 2
	s_cbranch_scc1 .LBB0_37
	v_lshl_add_u64 v[38:39], v[34:35], 2, s[40:41]
	v_mov_b32_e32 v35, v160
	s_waitcnt vmcnt(0)
	v_sub_f32_e32 v35, 1.0, v35
	v_mul_f32_e32 v37, v37, v35

.LBB0_39:
	s_or_b64 exec, exec, s[12:13]
	v_add_u32_e32 v36, 2, v34
	v_cmp_gt_i32_e32 vcc, s17, v36
	ds_write_b32 v99, v35
	s_and_b64 s[18:19], s[4:5], vcc
	v_mov_b32_e32 v35, 0
	s_and_saveexec_b64 s[12:13], s[18:19]
	s_cbranch_execz .LBB0_51
	s_waitcnt vmcnt(0)
	v_mov_b32_e32 v35, v201
	s_and_b64 vcc, exec, s[2:3]
	s_cbranch_vccnz .LBB0_43
	s_ashr_i32 s39, s38, 31
	v_lshl_add_u64 v[36:37], s[38:39], 0, v[66:67]
	v_lshl_add_u64 v[36:37], v[36:37], 2, s[14:15]
	v_mov_b32_e32 v36, v129
	s_cmp_lt_i32 s50, 3
	s_mov_b64 s[18:19], -1
	s_cbranch_scc0 .LBB0_44

.LBB0_44:
	s_cmp_eq_u32 s50, 3
	s_waitcnt vmcnt(0)
	v_mov_b32_e32 v37, v36
	s_cbranch_scc0 .LBB0_46
	s_ashr_i32 s39, s38, 31
	v_lshl_add_u64 v[38:39], s[38:39], 0, v[66:67]
	v_lshl_add_u64 v[38:39], v[38:39], 2, s[40:41]
	v_mov_b32_e32 v37, v161
	s_waitcnt vmcnt(0)
	v_mul_f32_e32 v37, v36, v37

.LBB0_47:
	s_cmp_eq_u32 s50, 2
	s_cbranch_scc0 .LBB0_49
	s_ashr_i32 s39, s38, 31
	v_lshl_add_u64 v[38:39], s[38:39], 0, v[66:67]
	v_lshl_add_u64 v[38:39], v[38:39], 2, s[40:41]
	v_mov_b32_e32 v37, v161
	s_waitcnt vmcnt(0)
	v_sub_f32_e32 v37, 1.0, v37
	v_mul_f32_e32 v36, v36, v37

.LBB0_51:
	s_or_b64 exec, exec, s[12:13]
	v_add_u32_e32 v36, 4, v34
	v_cmp_gt_i32_e32 vcc, s17, v36
	ds_write_b32 v99, v35 offset:264
	s_and_b64 s[18:19], s[4:5], vcc
	v_mov_b32_e32 v35, 0
	s_and_saveexec_b64 s[12:13], s[18:19]
	s_cbranch_execz .LBB0_63
	s_waitcnt vmcnt(0)
	v_mov_b32_e32 v35, v202
	s_and_b64 vcc, exec, s[2:3]
	s_cbranch_vccnz .LBB0_55
	s_ashr_i32 s39, s38, 31
	v_lshl_add_u64 v[36:37], s[38:39], 0, v[66:67]
	v_lshl_add_u64 v[36:37], v[36:37], 2, s[14:15]
	v_mov_b32_e32 v36, v130
	s_cmp_lt_i32 s50, 3
	s_mov_b64 s[18:19], -1
	s_cbranch_scc0 .LBB0_56

.LBB0_56:
	s_cmp_eq_u32 s50, 3
	s_waitcnt vmcnt(0)
	v_mov_b32_e32 v37, v36
	s_cbranch_scc0 .LBB0_58
	s_ashr_i32 s39, s38, 31
	v_lshl_add_u64 v[38:39], s[38:39], 0, v[66:67]
	v_lshl_add_u64 v[38:39], v[38:39], 2, s[40:41]
	v_mov_b32_e32 v37, v162
	s_waitcnt vmcnt(0)
	v_mul_f32_e32 v37, v36, v37

.LBB0_59:
	s_cmp_eq_u32 s50, 2
	s_cbranch_scc0 .LBB0_61
	s_ashr_i32 s39, s38, 31
	v_lshl_add_u64 v[38:39], s[38:39], 0, v[66:67]
	v_lshl_add_u64 v[38:39], v[38:39], 2, s[40:41]
	v_mov_b32_e32 v37, v162
	s_waitcnt vmcnt(0)
	v_sub_f32_e32 v37, 1.0, v37
	v_mul_f32_e32 v36, v36, v37

.LBB0_63:
	s_or_b64 exec, exec, s[12:13]
	v_add_u32_e32 v36, 6, v34
	v_cmp_gt_i32_e32 vcc, s17, v36
	ds_write_b32 v99, v35 offset:528
	s_and_b64 s[18:19], s[4:5], vcc
	v_mov_b32_e32 v35, 0
	s_and_saveexec_b64 s[12:13], s[18:19]
	s_cbranch_execz .LBB0_75
	s_waitcnt vmcnt(0)
	v_mov_b32_e32 v35, v203
	s_and_b64 vcc, exec, s[2:3]
	s_cbranch_vccnz .LBB0_67
	s_ashr_i32 s39, s38, 31
	v_lshl_add_u64 v[36:37], s[38:39], 0, v[66:67]
	v_lshl_add_u64 v[36:37], v[36:37], 2, s[14:15]
	v_mov_b32_e32 v36, v131
	s_cmp_lt_i32 s50, 3
	s_mov_b64 s[18:19], -1
	s_cbranch_scc0 .LBB0_68

.LBB0_68:
	s_cmp_eq_u32 s50, 3
	s_waitcnt vmcnt(0)
	v_mov_b32_e32 v37, v36
	s_cbranch_scc0 .LBB0_70
	s_ashr_i32 s39, s38, 31
	v_lshl_add_u64 v[38:39], s[38:39], 0, v[66:67]
	v_lshl_add_u64 v[38:39], v[38:39], 2, s[40:41]
	v_mov_b32_e32 v37, v163
	s_waitcnt vmcnt(0)
	v_mul_f32_e32 v37, v36, v37

.LBB0_71:
	s_cmp_eq_u32 s50, 2
	s_cbranch_scc0 .LBB0_73
	s_ashr_i32 s39, s38, 31
	v_lshl_add_u64 v[38:39], s[38:39], 0, v[66:67]
	v_lshl_add_u64 v[38:39], v[38:39], 2, s[40:41]
	v_mov_b32_e32 v37, v163
	s_waitcnt vmcnt(0)
	v_sub_f32_e32 v37, 1.0, v37
	v_mul_f32_e32 v36, v36, v37

.LBB0_75:
	s_or_b64 exec, exec, s[12:13]
	v_add_u32_e32 v36, 8, v34
	v_cmp_gt_i32_e32 vcc, s17, v36
	ds_write_b32 v99, v35 offset:792
	s_and_b64 s[18:19], s[4:5], vcc
	v_mov_b32_e32 v35, 0
	s_and_saveexec_b64 s[12:13], s[18:19]
	s_cbranch_execz .LBB0_87
	s_waitcnt vmcnt(0)
	v_mov_b32_e32 v35, v204
	s_and_b64 vcc, exec, s[2:3]
	s_cbranch_vccnz .LBB0_79
	s_ashr_i32 s39, s38, 31
	v_lshl_add_u64 v[36:37], s[38:39], 0, v[66:67]
	v_lshl_add_u64 v[36:37], v[36:37], 2, s[14:15]
	v_mov_b32_e32 v36, v132
	s_cmp_lt_i32 s50, 3
	s_mov_b64 s[18:19], -1
	s_cbranch_scc0 .LBB0_80

.LBB0_80:
	s_cmp_eq_u32 s50, 3
	s_waitcnt vmcnt(0)
	v_mov_b32_e32 v37, v36
	s_cbranch_scc0 .LBB0_82
	s_ashr_i32 s39, s38, 31
	v_lshl_add_u64 v[38:39], s[38:39], 0, v[66:67]
	v_lshl_add_u64 v[38:39], v[38:39], 2, s[40:41]
	v_mov_b32_e32 v37, v164
	s_waitcnt vmcnt(0)
	v_mul_f32_e32 v37, v36, v37

.LBB0_83:
	s_cmp_eq_u32 s50, 2
	s_cbranch_scc0 .LBB0_85
	s_ashr_i32 s39, s38, 31
	v_lshl_add_u64 v[38:39], s[38:39], 0, v[66:67]
	v_lshl_add_u64 v[38:39], v[38:39], 2, s[40:41]
	v_mov_b32_e32 v37, v164
	s_waitcnt vmcnt(0)
	v_sub_f32_e32 v37, 1.0, v37
	v_mul_f32_e32 v36, v36, v37

.LBB0_87:
	s_or_b64 exec, exec, s[12:13]
	v_add_u32_e32 v36, 10, v34
	v_cmp_gt_i32_e32 vcc, s17, v36
	ds_write_b32 v99, v35 offset:1056
	s_and_b64 s[18:19], s[4:5], vcc
	v_mov_b32_e32 v35, 0
	s_and_saveexec_b64 s[12:13], s[18:19]
	s_cbranch_execz .LBB0_99
	s_waitcnt vmcnt(0)
	v_mov_b32_e32 v35, v205
	s_and_b64 vcc, exec, s[2:3]
	s_cbranch_vccnz .LBB0_91
	s_ashr_i32 s39, s38, 31
	v_lshl_add_u64 v[36:37], s[38:39], 0, v[66:67]
	v_lshl_add_u64 v[36:37], v[36:37], 2, s[14:15]
	v_mov_b32_e32 v36, v133
	s_cmp_lt_i32 s50, 3
	s_mov_b64 s[18:19], -1
	s_cbranch_scc0 .LBB0_92

.LBB0_92:
	s_cmp_eq_u32 s50, 3
	s_waitcnt vmcnt(0)
	v_mov_b32_e32 v37, v36
	s_cbranch_scc0 .LBB0_94
	s_ashr_i32 s39, s38, 31
	v_lshl_add_u64 v[38:39], s[38:39], 0, v[66:67]
	v_lshl_add_u64 v[38:39], v[38:39], 2, s[40:41]
	v_mov_b32_e32 v37, v165
	s_waitcnt vmcnt(0)
	v_mul_f32_e32 v37, v36, v37

.LBB0_95:
	s_cmp_eq_u32 s50, 2
	s_cbranch_scc0 .LBB0_97
	s_ashr_i32 s39, s38, 31
	v_lshl_add_u64 v[38:39], s[38:39], 0, v[66:67]
	v_lshl_add_u64 v[38:39], v[38:39], 2, s[40:41]
	v_mov_b32_e32 v37, v165
	s_waitcnt vmcnt(0)
	v_sub_f32_e32 v37, 1.0, v37
	v_mul_f32_e32 v36, v36, v37

.LBB0_99:
	s_or_b64 exec, exec, s[12:13]
	v_add_u32_e32 v36, 12, v34
	v_cmp_gt_i32_e32 vcc, s17, v36
	ds_write_b32 v99, v35 offset:1320
	s_and_b64 s[18:19], s[4:5], vcc
	v_mov_b32_e32 v35, 0
	s_and_saveexec_b64 s[12:13], s[18:19]
	s_cbranch_execz .LBB0_111
	s_waitcnt vmcnt(0)
	v_mov_b32_e32 v35, v206
	s_and_b64 vcc, exec, s[2:3]
	s_cbranch_vccnz .LBB0_103
	s_ashr_i32 s39, s38, 31
	v_lshl_add_u64 v[36:37], s[38:39], 0, v[66:67]
	v_lshl_add_u64 v[36:37], v[36:37], 2, s[14:15]
	v_mov_b32_e32 v36, v134
	s_cmp_lt_i32 s50, 3
	s_mov_b64 s[18:19], -1
	s_cbranch_scc0 .LBB0_104

.LBB0_104:
	s_cmp_eq_u32 s50, 3
	s_waitcnt vmcnt(0)
	v_mov_b32_e32 v37, v36
	s_cbranch_scc0 .LBB0_106
	s_ashr_i32 s39, s38, 31
	v_lshl_add_u64 v[38:39], s[38:39], 0, v[66:67]
	v_lshl_add_u64 v[38:39], v[38:39], 2, s[40:41]
	v_mov_b32_e32 v37, v166
	s_waitcnt vmcnt(0)
	v_mul_f32_e32 v37, v36, v37

.LBB0_107:
	s_cmp_eq_u32 s50, 2
	s_cbranch_scc0 .LBB0_109
	s_ashr_i32 s39, s38, 31
	v_lshl_add_u64 v[38:39], s[38:39], 0, v[66:67]
	v_lshl_add_u64 v[38:39], v[38:39], 2, s[40:41]
	v_mov_b32_e32 v37, v166
	s_waitcnt vmcnt(0)
	v_sub_f32_e32 v37, 1.0, v37
	v_mul_f32_e32 v36, v36, v37

.LBB0_111:
	s_or_b64 exec, exec, s[12:13]
	v_add_u32_e32 v36, 14, v34
	v_cmp_gt_i32_e32 vcc, s17, v36
	ds_write_b32 v99, v35 offset:1584
	s_and_b64 s[18:19], s[4:5], vcc
	v_mov_b32_e32 v35, 0
	s_and_saveexec_b64 s[12:13], s[18:19]
	s_cbranch_execz .LBB0_123
	s_waitcnt vmcnt(0)
	v_mov_b32_e32 v35, v207
	s_and_b64 vcc, exec, s[2:3]
	s_cbranch_vccnz .LBB0_115
	s_ashr_i32 s39, s38, 31
	v_lshl_add_u64 v[36:37], s[38:39], 0, v[66:67]
	v_lshl_add_u64 v[36:37], v[36:37], 2, s[14:15]
	v_mov_b32_e32 v36, v135
	s_cmp_lt_i32 s50, 3
	s_mov_b64 s[18:19], -1
	s_cbranch_scc0 .LBB0_116

.LBB0_116:
	s_cmp_eq_u32 s50, 3
	s_waitcnt vmcnt(0)
	v_mov_b32_e32 v37, v36
	s_cbranch_scc0 .LBB0_118
	s_ashr_i32 s39, s38, 31
	v_lshl_add_u64 v[38:39], s[38:39], 0, v[66:67]
	v_lshl_add_u64 v[38:39], v[38:39], 2, s[40:41]
	v_mov_b32_e32 v37, v167
	s_waitcnt vmcnt(0)
	v_mul_f32_e32 v37, v36, v37

.LBB0_119:
	s_cmp_eq_u32 s50, 2
	s_cbranch_scc0 .LBB0_121
	s_ashr_i32 s39, s38, 31
	v_lshl_add_u64 v[38:39], s[38:39], 0, v[66:67]
	v_lshl_add_u64 v[38:39], v[38:39], 2, s[40:41]
	v_mov_b32_e32 v37, v167
	s_waitcnt vmcnt(0)
	v_sub_f32_e32 v37, 1.0, v37
	v_mul_f32_e32 v36, v36, v37

.LBB0_123:
	s_or_b64 exec, exec, s[12:13]
	v_add_u32_e32 v36, 16, v34
	v_cmp_gt_i32_e32 vcc, s17, v36
	ds_write_b32 v99, v35 offset:1848
	s_and_b64 s[18:19], s[4:5], vcc
	v_mov_b32_e32 v35, 0
	s_and_saveexec_b64 s[12:13], s[18:19]
	s_cbranch_execz .LBB0_135
	s_waitcnt vmcnt(0)
	v_mov_b32_e32 v35, v208
	s_and_b64 vcc, exec, s[2:3]
	s_cbranch_vccnz .LBB0_127
	s_ashr_i32 s39, s38, 31
	v_lshl_add_u64 v[36:37], s[38:39], 0, v[66:67]
	v_lshl_add_u64 v[36:37], v[36:37], 2, s[14:15]
	v_mov_b32_e32 v36, v136
	s_cmp_lt_i32 s50, 3
	s_mov_b64 s[18:19], -1
	s_cbranch_scc0 .LBB0_128

.LBB0_128:
	s_cmp_eq_u32 s50, 3
	s_waitcnt vmcnt(0)
	v_mov_b32_e32 v37, v36
	s_cbranch_scc0 .LBB0_130
	s_ashr_i32 s39, s38, 31
	v_lshl_add_u64 v[38:39], s[38:39], 0, v[66:67]
	v_lshl_add_u64 v[38:39], v[38:39], 2, s[40:41]
	v_mov_b32_e32 v37, v168
	s_waitcnt vmcnt(0)
	v_mul_f32_e32 v37, v36, v37

.LBB0_131:
	s_cmp_eq_u32 s50, 2
	s_cbranch_scc0 .LBB0_133
	s_ashr_i32 s39, s38, 31
	v_lshl_add_u64 v[38:39], s[38:39], 0, v[66:67]
	v_lshl_add_u64 v[38:39], v[38:39], 2, s[40:41]
	v_mov_b32_e32 v37, v168
	s_waitcnt vmcnt(0)
	v_sub_f32_e32 v37, 1.0, v37
	v_mul_f32_e32 v36, v36, v37

.LBB0_135:
	s_or_b64 exec, exec, s[12:13]
	v_add_u32_e32 v36, 18, v34
	v_cmp_gt_i32_e32 vcc, s17, v36
	ds_write_b32 v99, v35 offset:2112
	s_and_b64 s[18:19], s[4:5], vcc
	v_mov_b32_e32 v35, 0
	s_and_saveexec_b64 s[12:13], s[18:19]
	s_cbranch_execz .LBB0_147
	s_waitcnt vmcnt(0)
	v_mov_b32_e32 v35, v209
	s_and_b64 vcc, exec, s[2:3]
	s_cbranch_vccnz .LBB0_139
	s_ashr_i32 s39, s38, 31
	v_lshl_add_u64 v[36:37], s[38:39], 0, v[66:67]
	v_lshl_add_u64 v[36:37], v[36:37], 2, s[14:15]
	v_mov_b32_e32 v36, v137
	s_cmp_lt_i32 s50, 3
	s_mov_b64 s[18:19], -1
	s_cbranch_scc0 .LBB0_140

.LBB0_140:
	s_cmp_eq_u32 s50, 3
	s_waitcnt vmcnt(0)
	v_mov_b32_e32 v37, v36
	s_cbranch_scc0 .LBB0_142
	s_ashr_i32 s39, s38, 31
	v_lshl_add_u64 v[38:39], s[38:39], 0, v[66:67]
	v_lshl_add_u64 v[38:39], v[38:39], 2, s[40:41]
	v_mov_b32_e32 v37, v169
	s_waitcnt vmcnt(0)
	v_mul_f32_e32 v37, v36, v37

.LBB0_143:
	s_cmp_eq_u32 s50, 2
	s_cbranch_scc0 .LBB0_145
	s_ashr_i32 s39, s38, 31
	v_lshl_add_u64 v[38:39], s[38:39], 0, v[66:67]
	v_lshl_add_u64 v[38:39], v[38:39], 2, s[40:41]
	v_mov_b32_e32 v37, v169
	s_waitcnt vmcnt(0)
	v_sub_f32_e32 v37, 1.0, v37
	v_mul_f32_e32 v36, v36, v37

.LBB0_147:
	s_or_b64 exec, exec, s[12:13]
	v_add_u32_e32 v36, 20, v34
	v_cmp_gt_i32_e32 vcc, s17, v36
	ds_write_b32 v99, v35 offset:2376
	s_and_b64 s[18:19], s[4:5], vcc
	v_mov_b32_e32 v35, 0
	s_and_saveexec_b64 s[12:13], s[18:19]
	s_cbranch_execz .LBB0_159
	s_waitcnt vmcnt(0)
	v_mov_b32_e32 v35, v210
	s_and_b64 vcc, exec, s[2:3]
	s_cbranch_vccnz .LBB0_151
	s_ashr_i32 s39, s38, 31
	v_lshl_add_u64 v[36:37], s[38:39], 0, v[66:67]
	v_lshl_add_u64 v[36:37], v[36:37], 2, s[14:15]
	v_mov_b32_e32 v36, v138
	s_cmp_lt_i32 s50, 3
	s_mov_b64 s[18:19], -1
	s_cbranch_scc0 .LBB0_152

.LBB0_152:
	s_cmp_eq_u32 s50, 3
	s_waitcnt vmcnt(0)
	v_mov_b32_e32 v37, v36
	s_cbranch_scc0 .LBB0_154
	s_ashr_i32 s39, s38, 31
	v_lshl_add_u64 v[38:39], s[38:39], 0, v[66:67]
	v_lshl_add_u64 v[38:39], v[38:39], 2, s[40:41]
	v_mov_b32_e32 v37, v170
	s_waitcnt vmcnt(0)
	v_mul_f32_e32 v37, v36, v37

.LBB0_155:
	s_cmp_eq_u32 s50, 2
	s_cbranch_scc0 .LBB0_157
	s_ashr_i32 s39, s38, 31
	v_lshl_add_u64 v[38:39], s[38:39], 0, v[66:67]
	v_lshl_add_u64 v[38:39], v[38:39], 2, s[40:41]
	v_mov_b32_e32 v37, v170
	s_waitcnt vmcnt(0)
	v_sub_f32_e32 v37, 1.0, v37
	v_mul_f32_e32 v36, v36, v37

.LBB0_159:
	s_or_b64 exec, exec, s[12:13]
	v_add_u32_e32 v36, 22, v34
	v_cmp_gt_i32_e32 vcc, s17, v36
	ds_write_b32 v99, v35 offset:2640
	s_and_b64 s[18:19], s[4:5], vcc
	v_mov_b32_e32 v35, 0
	s_and_saveexec_b64 s[12:13], s[18:19]
	s_cbranch_execz .LBB0_171
	s_waitcnt vmcnt(0)
	v_mov_b32_e32 v35, v211
	s_and_b64 vcc, exec, s[2:3]
	s_cbranch_vccnz .LBB0_163
	s_ashr_i32 s39, s38, 31
	v_lshl_add_u64 v[36:37], s[38:39], 0, v[66:67]
	v_lshl_add_u64 v[36:37], v[36:37], 2, s[14:15]
	v_mov_b32_e32 v36, v139
	s_cmp_lt_i32 s50, 3
	s_mov_b64 s[18:19], -1
	s_cbranch_scc0 .LBB0_164

.LBB0_164:
	s_cmp_eq_u32 s50, 3
	s_waitcnt vmcnt(0)
	v_mov_b32_e32 v37, v36
	s_cbranch_scc0 .LBB0_166
	s_ashr_i32 s39, s38, 31
	v_lshl_add_u64 v[38:39], s[38:39], 0, v[66:67]
	v_lshl_add_u64 v[38:39], v[38:39], 2, s[40:41]
	v_mov_b32_e32 v37, v171
	s_waitcnt vmcnt(0)
	v_mul_f32_e32 v37, v36, v37

.LBB0_167:
	s_cmp_eq_u32 s50, 2
	s_cbranch_scc0 .LBB0_169
	s_ashr_i32 s39, s38, 31
	v_lshl_add_u64 v[38:39], s[38:39], 0, v[66:67]
	v_lshl_add_u64 v[38:39], v[38:39], 2, s[40:41]
	v_mov_b32_e32 v37, v171
	s_waitcnt vmcnt(0)
	v_sub_f32_e32 v37, 1.0, v37
	v_mul_f32_e32 v36, v36, v37

.LBB0_171:
	s_or_b64 exec, exec, s[12:13]
	v_add_u32_e32 v36, 24, v34
	v_cmp_gt_i32_e32 vcc, s17, v36
	ds_write_b32 v99, v35 offset:2904
	s_and_b64 s[18:19], s[4:5], vcc
	v_mov_b32_e32 v35, 0
	s_and_saveexec_b64 s[12:13], s[18:19]
	s_cbranch_execz .LBB0_183
	s_waitcnt vmcnt(0)
	v_mov_b32_e32 v35, v212
	s_and_b64 vcc, exec, s[2:3]
	s_cbranch_vccnz .LBB0_175
	s_ashr_i32 s39, s38, 31
	v_lshl_add_u64 v[36:37], s[38:39], 0, v[66:67]
	v_lshl_add_u64 v[36:37], v[36:37], 2, s[14:15]
	v_mov_b32_e32 v36, v140
	s_cmp_lt_i32 s50, 3
	s_mov_b64 s[18:19], -1
	s_cbranch_scc0 .LBB0_176

.LBB0_176:
	s_cmp_eq_u32 s50, 3
	s_waitcnt vmcnt(0)
	v_mov_b32_e32 v37, v36
	s_cbranch_scc0 .LBB0_178
	s_ashr_i32 s39, s38, 31
	v_lshl_add_u64 v[38:39], s[38:39], 0, v[66:67]
	v_lshl_add_u64 v[38:39], v[38:39], 2, s[40:41]
	v_mov_b32_e32 v37, v172
	s_waitcnt vmcnt(0)
	v_mul_f32_e32 v37, v36, v37

.LBB0_179:
	s_cmp_eq_u32 s50, 2
	s_cbranch_scc0 .LBB0_181
	s_ashr_i32 s39, s38, 31
	v_lshl_add_u64 v[38:39], s[38:39], 0, v[66:67]
	v_lshl_add_u64 v[38:39], v[38:39], 2, s[40:41]
	v_mov_b32_e32 v37, v172
	s_waitcnt vmcnt(0)
	v_sub_f32_e32 v37, 1.0, v37
	v_mul_f32_e32 v36, v36, v37

.LBB0_183:
	s_or_b64 exec, exec, s[12:13]
	v_add_u32_e32 v36, 26, v34
	v_cmp_gt_i32_e32 vcc, s17, v36
	ds_write_b32 v99, v35 offset:3168
	s_and_b64 s[18:19], s[4:5], vcc
	v_mov_b32_e32 v35, 0
	s_and_saveexec_b64 s[12:13], s[18:19]
	s_cbranch_execz .LBB0_195
	s_waitcnt vmcnt(0)
	v_mov_b32_e32 v35, v213
	s_and_b64 vcc, exec, s[2:3]
	s_cbranch_vccnz .LBB0_187
	s_ashr_i32 s39, s38, 31
	v_lshl_add_u64 v[36:37], s[38:39], 0, v[66:67]
	v_lshl_add_u64 v[36:37], v[36:37], 2, s[14:15]
	v_mov_b32_e32 v36, v141
	s_cmp_lt_i32 s50, 3
	s_mov_b64 s[18:19], -1
	s_cbranch_scc0 .LBB0_188

.LBB0_188:
	s_cmp_eq_u32 s50, 3
	s_waitcnt vmcnt(0)
	v_mov_b32_e32 v37, v36
	s_cbranch_scc0 .LBB0_190
	s_ashr_i32 s39, s38, 31
	v_lshl_add_u64 v[38:39], s[38:39], 0, v[66:67]
	v_lshl_add_u64 v[38:39], v[38:39], 2, s[40:41]
	v_mov_b32_e32 v37, v173
	s_waitcnt vmcnt(0)
	v_mul_f32_e32 v37, v36, v37

.LBB0_191:
	s_cmp_eq_u32 s50, 2
	s_cbranch_scc0 .LBB0_193
	s_ashr_i32 s39, s38, 31
	v_lshl_add_u64 v[38:39], s[38:39], 0, v[66:67]
	v_lshl_add_u64 v[38:39], v[38:39], 2, s[40:41]
	v_mov_b32_e32 v37, v173
	s_waitcnt vmcnt(0)
	v_sub_f32_e32 v37, 1.0, v37
	v_mul_f32_e32 v36, v36, v37

.LBB0_195:
	s_or_b64 exec, exec, s[12:13]
	v_add_u32_e32 v36, 28, v34
	v_cmp_gt_i32_e32 vcc, s17, v36
	ds_write_b32 v99, v35 offset:3432
	s_and_b64 s[18:19], s[4:5], vcc
	v_mov_b32_e32 v35, 0
	s_and_saveexec_b64 s[12:13], s[18:19]
	s_cbranch_execz .LBB0_207
	s_waitcnt vmcnt(0)
	v_mov_b32_e32 v35, v214
	s_and_b64 vcc, exec, s[2:3]
	s_cbranch_vccnz .LBB0_199
	s_ashr_i32 s39, s38, 31
	v_lshl_add_u64 v[36:37], s[38:39], 0, v[66:67]
	v_lshl_add_u64 v[36:37], v[36:37], 2, s[14:15]
	v_mov_b32_e32 v36, v142
	s_cmp_lt_i32 s50, 3
	s_mov_b64 s[18:19], -1
	s_cbranch_scc0 .LBB0_200

.LBB0_200:
	s_cmp_eq_u32 s50, 3
	s_waitcnt vmcnt(0)
	v_mov_b32_e32 v37, v36
	s_cbranch_scc0 .LBB0_202
	s_ashr_i32 s39, s38, 31
	v_lshl_add_u64 v[38:39], s[38:39], 0, v[66:67]
	v_lshl_add_u64 v[38:39], v[38:39], 2, s[40:41]
	v_mov_b32_e32 v37, v174
	s_waitcnt vmcnt(0)
	v_mul_f32_e32 v37, v36, v37

.LBB0_203:
	s_cmp_eq_u32 s50, 2
	s_cbranch_scc0 .LBB0_205
	s_ashr_i32 s39, s38, 31
	v_lshl_add_u64 v[38:39], s[38:39], 0, v[66:67]
	v_lshl_add_u64 v[38:39], v[38:39], 2, s[40:41]
	v_mov_b32_e32 v37, v174
	s_waitcnt vmcnt(0)
	v_sub_f32_e32 v37, 1.0, v37
	v_mul_f32_e32 v36, v36, v37

.LBB0_207:
	s_or_b64 exec, exec, s[12:13]
	v_add_u32_e32 v36, 30, v34
	v_cmp_gt_i32_e32 vcc, s17, v36
	ds_write_b32 v99, v35 offset:3696
	s_and_b64 s[18:19], s[4:5], vcc
	v_mov_b32_e32 v35, 0
	s_and_saveexec_b64 s[12:13], s[18:19]
	s_cbranch_execz .LBB0_219
	s_waitcnt vmcnt(0)
	v_mov_b32_e32 v35, v215
	s_and_b64 vcc, exec, s[2:3]
	s_cbranch_vccnz .LBB0_211
	s_ashr_i32 s39, s38, 31
	v_lshl_add_u64 v[36:37], s[38:39], 0, v[66:67]
	v_lshl_add_u64 v[36:37], v[36:37], 2, s[14:15]
	v_mov_b32_e32 v36, v143
	s_cmp_lt_i32 s50, 3
	s_mov_b64 s[18:19], -1
	s_cbranch_scc0 .LBB0_212

.LBB0_212:
	s_cmp_eq_u32 s50, 3
	s_waitcnt vmcnt(0)
	v_mov_b32_e32 v37, v36
	s_cbranch_scc0 .LBB0_214
	s_ashr_i32 s39, s38, 31
	v_lshl_add_u64 v[38:39], s[38:39], 0, v[66:67]
	v_lshl_add_u64 v[38:39], v[38:39], 2, s[40:41]
	v_mov_b32_e32 v37, v175
	s_waitcnt vmcnt(0)
	v_mul_f32_e32 v37, v36, v37

.LBB0_215:
	s_cmp_eq_u32 s50, 2
	s_cbranch_scc0 .LBB0_217
	s_ashr_i32 s39, s38, 31
	v_lshl_add_u64 v[38:39], s[38:39], 0, v[66:67]
	v_lshl_add_u64 v[38:39], v[38:39], 2, s[40:41]
	v_mov_b32_e32 v37, v175
	s_waitcnt vmcnt(0)
	v_sub_f32_e32 v37, 1.0, v37
	v_mul_f32_e32 v36, v36, v37

.LBB0_219:
	s_or_b64 exec, exec, s[12:13]
	v_add_u32_e32 v36, 32, v34
	v_cmp_gt_i32_e32 vcc, s17, v36
	ds_write_b32 v99, v35 offset:3960
	s_and_b64 s[18:19], s[4:5], vcc
	v_mov_b32_e32 v35, 0
	s_and_saveexec_b64 s[12:13], s[18:19]
	s_cbranch_execz .LBB0_231
	s_waitcnt vmcnt(0)
	v_mov_b32_e32 v35, v216
	s_and_b64 vcc, exec, s[2:3]
	s_cbranch_vccnz .LBB0_223
	s_ashr_i32 s39, s38, 31
	v_lshl_add_u64 v[36:37], s[38:39], 0, v[66:67]
	v_lshl_add_u64 v[36:37], v[36:37], 2, s[14:15]
	v_mov_b32_e32 v36, v144
	s_cmp_lt_i32 s50, 3
	s_mov_b64 s[18:19], -1
	s_cbranch_scc0 .LBB0_224

.LBB0_224:
	s_cmp_eq_u32 s50, 3
	s_waitcnt vmcnt(0)
	v_mov_b32_e32 v37, v36
	s_cbranch_scc0 .LBB0_226
	s_ashr_i32 s39, s38, 31
	v_lshl_add_u64 v[38:39], s[38:39], 0, v[66:67]
	v_lshl_add_u64 v[38:39], v[38:39], 2, s[40:41]
	v_mov_b32_e32 v37, v176
	s_waitcnt vmcnt(0)
	v_mul_f32_e32 v37, v36, v37

.LBB0_227:
	s_cmp_eq_u32 s50, 2
	s_cbranch_scc0 .LBB0_229
	s_ashr_i32 s39, s38, 31
	v_lshl_add_u64 v[38:39], s[38:39], 0, v[66:67]
	v_lshl_add_u64 v[38:39], v[38:39], 2, s[40:41]
	v_mov_b32_e32 v37, v176
	s_waitcnt vmcnt(0)
	v_sub_f32_e32 v37, 1.0, v37
	v_mul_f32_e32 v36, v36, v37

.LBB0_231:
	s_or_b64 exec, exec, s[12:13]
	v_add_u32_e32 v36, 34, v34
	v_cmp_gt_i32_e32 vcc, s17, v36
	ds_write_b32 v99, v35 offset:4224
	s_and_b64 s[18:19], s[4:5], vcc
	v_mov_b32_e32 v35, 0
	s_and_saveexec_b64 s[12:13], s[18:19]
	s_cbranch_execz .LBB0_243
	s_waitcnt vmcnt(0)
	v_mov_b32_e32 v35, v217
	s_and_b64 vcc, exec, s[2:3]
	s_cbranch_vccnz .LBB0_235
	s_ashr_i32 s39, s38, 31
	v_lshl_add_u64 v[36:37], s[38:39], 0, v[66:67]
	v_lshl_add_u64 v[36:37], v[36:37], 2, s[14:15]
	v_mov_b32_e32 v36, v145
	s_cmp_lt_i32 s50, 3
	s_mov_b64 s[18:19], -1
	s_cbranch_scc0 .LBB0_236

.LBB0_236:
	s_cmp_eq_u32 s50, 3
	s_waitcnt vmcnt(0)
	v_mov_b32_e32 v37, v36
	s_cbranch_scc0 .LBB0_238
	s_ashr_i32 s39, s38, 31
	v_lshl_add_u64 v[38:39], s[38:39], 0, v[66:67]
	v_lshl_add_u64 v[38:39], v[38:39], 2, s[40:41]
	v_mov_b32_e32 v37, v177
	s_waitcnt vmcnt(0)
	v_mul_f32_e32 v37, v36, v37

.LBB0_239:
	s_cmp_eq_u32 s50, 2
	s_cbranch_scc0 .LBB0_241
	s_ashr_i32 s39, s38, 31
	v_lshl_add_u64 v[38:39], s[38:39], 0, v[66:67]
	v_lshl_add_u64 v[38:39], v[38:39], 2, s[40:41]
	v_mov_b32_e32 v37, v177
	s_waitcnt vmcnt(0)
	v_sub_f32_e32 v37, 1.0, v37
	v_mul_f32_e32 v36, v36, v37

.LBB0_243:
	s_or_b64 exec, exec, s[12:13]
	v_add_u32_e32 v36, 36, v34
	v_cmp_gt_i32_e32 vcc, s17, v36
	ds_write_b32 v99, v35 offset:4488
	s_and_b64 s[18:19], s[4:5], vcc
	v_mov_b32_e32 v35, 0
	s_and_saveexec_b64 s[12:13], s[18:19]
	s_cbranch_execz .LBB0_255
	s_waitcnt vmcnt(0)
	v_mov_b32_e32 v35, v218
	s_and_b64 vcc, exec, s[2:3]
	s_cbranch_vccnz .LBB0_247
	s_ashr_i32 s39, s38, 31
	v_lshl_add_u64 v[36:37], s[38:39], 0, v[66:67]
	v_lshl_add_u64 v[36:37], v[36:37], 2, s[14:15]
	v_mov_b32_e32 v36, v146
	s_cmp_lt_i32 s50, 3
	s_mov_b64 s[18:19], -1
	s_cbranch_scc0 .LBB0_248

.LBB0_248:
	s_cmp_eq_u32 s50, 3
	s_waitcnt vmcnt(0)
	v_mov_b32_e32 v37, v36
	s_cbranch_scc0 .LBB0_250
	s_ashr_i32 s39, s38, 31
	v_lshl_add_u64 v[38:39], s[38:39], 0, v[66:67]
	v_lshl_add_u64 v[38:39], v[38:39], 2, s[40:41]
	v_mov_b32_e32 v37, v178
	s_waitcnt vmcnt(0)
	v_mul_f32_e32 v37, v36, v37

.LBB0_251:
	s_cmp_eq_u32 s50, 2
	s_cbranch_scc0 .LBB0_253
	s_ashr_i32 s39, s38, 31
	v_lshl_add_u64 v[38:39], s[38:39], 0, v[66:67]
	v_lshl_add_u64 v[38:39], v[38:39], 2, s[40:41]
	v_mov_b32_e32 v37, v178
	s_waitcnt vmcnt(0)
	v_sub_f32_e32 v37, 1.0, v37
	v_mul_f32_e32 v36, v36, v37

.LBB0_255:
	s_or_b64 exec, exec, s[12:13]
	v_add_u32_e32 v36, 38, v34
	v_cmp_gt_i32_e32 vcc, s17, v36
	ds_write_b32 v99, v35 offset:4752
	s_and_b64 s[18:19], s[4:5], vcc
	v_mov_b32_e32 v35, 0
	s_and_saveexec_b64 s[12:13], s[18:19]
	s_cbranch_execz .LBB0_267
	s_waitcnt vmcnt(0)
	v_mov_b32_e32 v35, v219
	s_and_b64 vcc, exec, s[2:3]
	s_cbranch_vccnz .LBB0_259
	s_ashr_i32 s39, s38, 31
	v_lshl_add_u64 v[36:37], s[38:39], 0, v[66:67]
	v_lshl_add_u64 v[36:37], v[36:37], 2, s[14:15]
	v_mov_b32_e32 v36, v147
	s_cmp_lt_i32 s50, 3
	s_mov_b64 s[18:19], -1
	s_cbranch_scc0 .LBB0_260

.LBB0_260:
	s_cmp_eq_u32 s50, 3
	s_waitcnt vmcnt(0)
	v_mov_b32_e32 v37, v36
	s_cbranch_scc0 .LBB0_262
	s_ashr_i32 s39, s38, 31
	v_lshl_add_u64 v[38:39], s[38:39], 0, v[66:67]
	v_lshl_add_u64 v[38:39], v[38:39], 2, s[40:41]
	v_mov_b32_e32 v37, v179
	s_waitcnt vmcnt(0)
	v_mul_f32_e32 v37, v36, v37

.LBB0_263:
	s_cmp_eq_u32 s50, 2
	s_cbranch_scc0 .LBB0_265
	s_ashr_i32 s39, s38, 31
	v_lshl_add_u64 v[38:39], s[38:39], 0, v[66:67]
	v_lshl_add_u64 v[38:39], v[38:39], 2, s[40:41]
	v_mov_b32_e32 v37, v179
	s_waitcnt vmcnt(0)
	v_sub_f32_e32 v37, 1.0, v37
	v_mul_f32_e32 v36, v36, v37

.LBB0_267:
	s_or_b64 exec, exec, s[12:13]
	v_add_u32_e32 v36, 40, v34
	v_cmp_gt_i32_e32 vcc, s17, v36
	ds_write_b32 v99, v35 offset:5016
	s_and_b64 s[18:19], s[4:5], vcc
	v_mov_b32_e32 v35, 0
	s_and_saveexec_b64 s[12:13], s[18:19]
	s_cbranch_execz .LBB0_279
	s_waitcnt vmcnt(0)
	v_mov_b32_e32 v35, v220
	s_and_b64 vcc, exec, s[2:3]
	s_cbranch_vccnz .LBB0_271
	s_ashr_i32 s39, s38, 31
	v_lshl_add_u64 v[36:37], s[38:39], 0, v[66:67]
	v_lshl_add_u64 v[36:37], v[36:37], 2, s[14:15]
	v_mov_b32_e32 v36, v148
	s_cmp_lt_i32 s50, 3
	s_mov_b64 s[18:19], -1
	s_cbranch_scc0 .LBB0_272

.LBB0_272:
	s_cmp_eq_u32 s50, 3
	s_waitcnt vmcnt(0)
	v_mov_b32_e32 v37, v36
	s_cbranch_scc0 .LBB0_274
	s_ashr_i32 s39, s38, 31
	v_lshl_add_u64 v[38:39], s[38:39], 0, v[66:67]
	v_lshl_add_u64 v[38:39], v[38:39], 2, s[40:41]
	v_mov_b32_e32 v37, v180
	s_waitcnt vmcnt(0)
	v_mul_f32_e32 v37, v36, v37

.LBB0_275:
	s_cmp_eq_u32 s50, 2
	s_cbranch_scc0 .LBB0_277
	s_ashr_i32 s39, s38, 31
	v_lshl_add_u64 v[38:39], s[38:39], 0, v[66:67]
	v_lshl_add_u64 v[38:39], v[38:39], 2, s[40:41]
	v_mov_b32_e32 v37, v180
	s_waitcnt vmcnt(0)
	v_sub_f32_e32 v37, 1.0, v37
	v_mul_f32_e32 v36, v36, v37

.LBB0_279:
	s_or_b64 exec, exec, s[12:13]
	v_add_u32_e32 v36, 42, v34
	v_cmp_gt_i32_e32 vcc, s17, v36
	ds_write_b32 v99, v35 offset:5280
	s_and_b64 s[18:19], s[4:5], vcc
	v_mov_b32_e32 v35, 0
	s_and_saveexec_b64 s[12:13], s[18:19]
	s_cbranch_execz .LBB0_291
	s_waitcnt vmcnt(0)
	v_mov_b32_e32 v35, v221
	s_and_b64 vcc, exec, s[2:3]
	s_cbranch_vccnz .LBB0_283
	s_ashr_i32 s39, s38, 31
	v_lshl_add_u64 v[36:37], s[38:39], 0, v[66:67]
	v_lshl_add_u64 v[36:37], v[36:37], 2, s[14:15]
	v_mov_b32_e32 v36, v149
	s_cmp_lt_i32 s50, 3
	s_mov_b64 s[18:19], -1
	s_cbranch_scc0 .LBB0_284

.LBB0_284:
	s_cmp_eq_u32 s50, 3
	s_waitcnt vmcnt(0)
	v_mov_b32_e32 v37, v36
	s_cbranch_scc0 .LBB0_286
	s_ashr_i32 s39, s38, 31
	v_lshl_add_u64 v[38:39], s[38:39], 0, v[66:67]
	v_lshl_add_u64 v[38:39], v[38:39], 2, s[40:41]
	v_mov_b32_e32 v37, v181
	s_waitcnt vmcnt(0)
	v_mul_f32_e32 v37, v36, v37

.LBB0_287:
	s_cmp_eq_u32 s50, 2
	s_cbranch_scc0 .LBB0_289
	s_ashr_i32 s39, s38, 31
	v_lshl_add_u64 v[38:39], s[38:39], 0, v[66:67]
	v_lshl_add_u64 v[38:39], v[38:39], 2, s[40:41]
	v_mov_b32_e32 v37, v181
	s_waitcnt vmcnt(0)
	v_sub_f32_e32 v37, 1.0, v37
	v_mul_f32_e32 v36, v36, v37

.LBB0_291:
	s_or_b64 exec, exec, s[12:13]
	v_add_u32_e32 v36, 44, v34
	v_cmp_gt_i32_e32 vcc, s17, v36
	ds_write_b32 v99, v35 offset:5544
	s_and_b64 s[18:19], s[4:5], vcc
	v_mov_b32_e32 v35, 0
	s_and_saveexec_b64 s[12:13], s[18:19]
	s_cbranch_execz .LBB0_303
	s_waitcnt vmcnt(0)
	v_mov_b32_e32 v35, v222
	s_and_b64 vcc, exec, s[2:3]
	s_cbranch_vccnz .LBB0_295
	s_ashr_i32 s39, s38, 31
	v_lshl_add_u64 v[36:37], s[38:39], 0, v[66:67]
	v_lshl_add_u64 v[36:37], v[36:37], 2, s[14:15]
	v_mov_b32_e32 v36, v150
	s_cmp_lt_i32 s50, 3
	s_mov_b64 s[18:19], -1
	s_cbranch_scc0 .LBB0_296

.LBB0_296:
	s_cmp_eq_u32 s50, 3
	s_waitcnt vmcnt(0)
	v_mov_b32_e32 v37, v36
	s_cbranch_scc0 .LBB0_298
	s_ashr_i32 s39, s38, 31
	v_lshl_add_u64 v[38:39], s[38:39], 0, v[66:67]
	v_lshl_add_u64 v[38:39], v[38:39], 2, s[40:41]
	v_mov_b32_e32 v37, v182
	s_waitcnt vmcnt(0)
	v_mul_f32_e32 v37, v36, v37

.LBB0_299:
	s_cmp_eq_u32 s50, 2
	s_cbranch_scc0 .LBB0_301
	s_ashr_i32 s39, s38, 31
	v_lshl_add_u64 v[38:39], s[38:39], 0, v[66:67]
	v_lshl_add_u64 v[38:39], v[38:39], 2, s[40:41]
	v_mov_b32_e32 v37, v182
	s_waitcnt vmcnt(0)
	v_sub_f32_e32 v37, 1.0, v37
	v_mul_f32_e32 v36, v36, v37

.LBB0_303:
	s_or_b64 exec, exec, s[12:13]
	v_add_u32_e32 v36, 46, v34
	v_cmp_gt_i32_e32 vcc, s17, v36
	ds_write_b32 v99, v35 offset:5808
	s_and_b64 s[18:19], s[4:5], vcc
	v_mov_b32_e32 v35, 0
	s_and_saveexec_b64 s[12:13], s[18:19]
	s_cbranch_execz .LBB0_315
	s_waitcnt vmcnt(0)
	v_mov_b32_e32 v35, v223
	s_and_b64 vcc, exec, s[2:3]
	s_cbranch_vccnz .LBB0_307
	s_ashr_i32 s39, s38, 31
	v_lshl_add_u64 v[36:37], s[38:39], 0, v[66:67]
	v_lshl_add_u64 v[36:37], v[36:37], 2, s[14:15]
	v_mov_b32_e32 v36, v151
	s_cmp_lt_i32 s50, 3
	s_mov_b64 s[18:19], -1
	s_cbranch_scc0 .LBB0_308

.LBB0_308:
	s_cmp_eq_u32 s50, 3
	s_waitcnt vmcnt(0)
	v_mov_b32_e32 v37, v36
	s_cbranch_scc0 .LBB0_310
	s_ashr_i32 s39, s38, 31
	v_lshl_add_u64 v[38:39], s[38:39], 0, v[66:67]
	v_lshl_add_u64 v[38:39], v[38:39], 2, s[40:41]
	v_mov_b32_e32 v37, v183
	s_waitcnt vmcnt(0)
	v_mul_f32_e32 v37, v36, v37

.LBB0_311:
	s_cmp_eq_u32 s50, 2
	s_cbranch_scc0 .LBB0_313
	s_ashr_i32 s39, s38, 31
	v_lshl_add_u64 v[38:39], s[38:39], 0, v[66:67]
	v_lshl_add_u64 v[38:39], v[38:39], 2, s[40:41]
	v_mov_b32_e32 v37, v183
	s_waitcnt vmcnt(0)
	v_sub_f32_e32 v37, 1.0, v37
	v_mul_f32_e32 v36, v36, v37

.LBB0_315:
	s_or_b64 exec, exec, s[12:13]
	v_add_u32_e32 v36, 48, v34
	v_cmp_gt_i32_e32 vcc, s17, v36
	ds_write_b32 v99, v35 offset:6072
	s_and_b64 s[18:19], s[4:5], vcc
	v_mov_b32_e32 v35, 0
	s_and_saveexec_b64 s[12:13], s[18:19]
	s_cbranch_execz .LBB0_327
	s_waitcnt vmcnt(0)
	v_mov_b32_e32 v35, v224
	s_and_b64 vcc, exec, s[2:3]
	s_cbranch_vccnz .LBB0_319
	s_ashr_i32 s39, s38, 31
	v_lshl_add_u64 v[36:37], s[38:39], 0, v[66:67]
	v_lshl_add_u64 v[36:37], v[36:37], 2, s[14:15]
	v_mov_b32_e32 v36, v152
	s_cmp_lt_i32 s50, 3
	s_mov_b64 s[18:19], -1
	s_cbranch_scc0 .LBB0_320

.LBB0_320:
	s_cmp_eq_u32 s50, 3
	s_waitcnt vmcnt(0)
	v_mov_b32_e32 v37, v36
	s_cbranch_scc0 .LBB0_322
	s_ashr_i32 s39, s38, 31
	v_lshl_add_u64 v[38:39], s[38:39], 0, v[66:67]
	v_lshl_add_u64 v[38:39], v[38:39], 2, s[40:41]
	v_mov_b32_e32 v37, v184
	s_waitcnt vmcnt(0)
	v_mul_f32_e32 v37, v36, v37

.LBB0_323:
	s_cmp_eq_u32 s50, 2
	s_cbranch_scc0 .LBB0_325
	s_ashr_i32 s39, s38, 31
	v_lshl_add_u64 v[38:39], s[38:39], 0, v[66:67]
	v_lshl_add_u64 v[38:39], v[38:39], 2, s[40:41]
	v_mov_b32_e32 v37, v184
	s_waitcnt vmcnt(0)
	v_sub_f32_e32 v37, 1.0, v37
	v_mul_f32_e32 v36, v36, v37

.LBB0_327:
	s_or_b64 exec, exec, s[12:13]
	v_add_u32_e32 v36, 50, v34
	v_cmp_gt_i32_e32 vcc, s17, v36
	ds_write_b32 v99, v35 offset:6336
	s_and_b64 s[18:19], s[4:5], vcc
	v_mov_b32_e32 v35, 0
	s_and_saveexec_b64 s[12:13], s[18:19]
	s_cbranch_execz .LBB0_339
	s_waitcnt vmcnt(0)
	v_mov_b32_e32 v35, v225
	s_and_b64 vcc, exec, s[2:3]
	s_cbranch_vccnz .LBB0_331
	s_ashr_i32 s39, s38, 31
	v_lshl_add_u64 v[36:37], s[38:39], 0, v[66:67]
	v_lshl_add_u64 v[36:37], v[36:37], 2, s[14:15]
	v_mov_b32_e32 v36, v153
	s_cmp_lt_i32 s50, 3
	s_mov_b64 s[18:19], -1
	s_cbranch_scc0 .LBB0_332

.LBB0_332:
	s_cmp_eq_u32 s50, 3
	s_waitcnt vmcnt(0)
	v_mov_b32_e32 v37, v36
	s_cbranch_scc0 .LBB0_334
	s_ashr_i32 s39, s38, 31
	v_lshl_add_u64 v[38:39], s[38:39], 0, v[66:67]
	v_lshl_add_u64 v[38:39], v[38:39], 2, s[40:41]
	v_mov_b32_e32 v37, v185
	s_waitcnt vmcnt(0)
	v_mul_f32_e32 v37, v36, v37

.LBB0_335:
	s_cmp_eq_u32 s50, 2
	s_cbranch_scc0 .LBB0_337
	s_ashr_i32 s39, s38, 31
	v_lshl_add_u64 v[38:39], s[38:39], 0, v[66:67]
	v_lshl_add_u64 v[38:39], v[38:39], 2, s[40:41]
	v_mov_b32_e32 v37, v185
	s_waitcnt vmcnt(0)
	v_sub_f32_e32 v37, 1.0, v37
	v_mul_f32_e32 v36, v36, v37

.LBB0_339:
	s_or_b64 exec, exec, s[12:13]
	v_add_u32_e32 v36, 52, v34
	v_cmp_gt_i32_e32 vcc, s17, v36
	ds_write_b32 v99, v35 offset:6600
	s_and_b64 s[18:19], s[4:5], vcc
	v_mov_b32_e32 v35, 0
	s_and_saveexec_b64 s[12:13], s[18:19]
	s_cbranch_execz .LBB0_351
	s_waitcnt vmcnt(0)
	v_mov_b32_e32 v35, v226
	s_and_b64 vcc, exec, s[2:3]
	s_cbranch_vccnz .LBB0_343
	s_ashr_i32 s39, s38, 31
	v_lshl_add_u64 v[36:37], s[38:39], 0, v[66:67]
	v_lshl_add_u64 v[36:37], v[36:37], 2, s[14:15]
	v_mov_b32_e32 v36, v154
	s_cmp_lt_i32 s50, 3
	s_mov_b64 s[18:19], -1
	s_cbranch_scc0 .LBB0_344

.LBB0_344:
	s_cmp_eq_u32 s50, 3
	s_waitcnt vmcnt(0)
	v_mov_b32_e32 v37, v36
	s_cbranch_scc0 .LBB0_346
	s_ashr_i32 s39, s38, 31
	v_lshl_add_u64 v[38:39], s[38:39], 0, v[66:67]
	v_lshl_add_u64 v[38:39], v[38:39], 2, s[40:41]
	v_mov_b32_e32 v37, v186
	s_waitcnt vmcnt(0)
	v_mul_f32_e32 v37, v36, v37

.LBB0_347:
	s_cmp_eq_u32 s50, 2
	s_cbranch_scc0 .LBB0_349
	s_ashr_i32 s39, s38, 31
	v_lshl_add_u64 v[38:39], s[38:39], 0, v[66:67]
	v_lshl_add_u64 v[38:39], v[38:39], 2, s[40:41]
	v_mov_b32_e32 v37, v186
	s_waitcnt vmcnt(0)
	v_sub_f32_e32 v37, 1.0, v37
	v_mul_f32_e32 v36, v36, v37

.LBB0_351:
	s_or_b64 exec, exec, s[12:13]
	v_add_u32_e32 v36, 54, v34
	v_cmp_gt_i32_e32 vcc, s17, v36
	ds_write_b32 v99, v35 offset:6864
	s_and_b64 s[18:19], s[4:5], vcc
	v_mov_b32_e32 v35, 0
	s_and_saveexec_b64 s[12:13], s[18:19]
	s_cbranch_execz .LBB0_363
	s_waitcnt vmcnt(0)
	v_mov_b32_e32 v35, v227
	s_and_b64 vcc, exec, s[2:3]
	s_cbranch_vccnz .LBB0_355
	s_ashr_i32 s39, s38, 31
	v_lshl_add_u64 v[36:37], s[38:39], 0, v[66:67]
	v_lshl_add_u64 v[36:37], v[36:37], 2, s[14:15]
	v_mov_b32_e32 v36, v155
	s_cmp_lt_i32 s50, 3
	s_mov_b64 s[18:19], -1
	s_cbranch_scc0 .LBB0_356

.LBB0_356:
	s_cmp_eq_u32 s50, 3
	s_waitcnt vmcnt(0)
	v_mov_b32_e32 v37, v36
	s_cbranch_scc0 .LBB0_358
	s_ashr_i32 s39, s38, 31
	v_lshl_add_u64 v[38:39], s[38:39], 0, v[66:67]
	v_lshl_add_u64 v[38:39], v[38:39], 2, s[40:41]
	v_mov_b32_e32 v37, v187
	s_waitcnt vmcnt(0)
	v_mul_f32_e32 v37, v36, v37

.LBB0_359:
	s_cmp_eq_u32 s50, 2
	s_cbranch_scc0 .LBB0_361
	s_ashr_i32 s39, s38, 31
	v_lshl_add_u64 v[38:39], s[38:39], 0, v[66:67]
	v_lshl_add_u64 v[38:39], v[38:39], 2, s[40:41]
	v_mov_b32_e32 v37, v187
	s_waitcnt vmcnt(0)
	v_sub_f32_e32 v37, 1.0, v37
	v_mul_f32_e32 v36, v36, v37

.LBB0_363:
	s_or_b64 exec, exec, s[12:13]
	v_add_u32_e32 v36, 56, v34
	v_cmp_gt_i32_e32 vcc, s17, v36
	ds_write_b32 v99, v35 offset:7128
	s_and_b64 s[18:19], s[4:5], vcc
	v_mov_b32_e32 v35, 0
	s_and_saveexec_b64 s[12:13], s[18:19]
	s_cbranch_execz .LBB0_375
	s_waitcnt vmcnt(0)
	v_mov_b32_e32 v35, v228
	s_and_b64 vcc, exec, s[2:3]
	s_cbranch_vccnz .LBB0_367
	s_ashr_i32 s39, s38, 31
	v_lshl_add_u64 v[36:37], s[38:39], 0, v[66:67]
	v_lshl_add_u64 v[36:37], v[36:37], 2, s[14:15]
	v_mov_b32_e32 v36, v156
	s_cmp_lt_i32 s50, 3
	s_mov_b64 s[18:19], -1
	s_cbranch_scc0 .LBB0_368

.LBB0_368:
	s_cmp_eq_u32 s50, 3
	s_waitcnt vmcnt(0)
	v_mov_b32_e32 v37, v36
	s_cbranch_scc0 .LBB0_370
	s_ashr_i32 s39, s38, 31
	v_lshl_add_u64 v[38:39], s[38:39], 0, v[66:67]
	v_lshl_add_u64 v[38:39], v[38:39], 2, s[40:41]
	v_mov_b32_e32 v37, v188
	s_waitcnt vmcnt(0)
	v_mul_f32_e32 v37, v36, v37

.LBB0_371:
	s_cmp_eq_u32 s50, 2
	s_cbranch_scc0 .LBB0_373
	s_ashr_i32 s39, s38, 31
	v_lshl_add_u64 v[38:39], s[38:39], 0, v[66:67]
	v_lshl_add_u64 v[38:39], v[38:39], 2, s[40:41]
	v_mov_b32_e32 v37, v188
	s_waitcnt vmcnt(0)
	v_sub_f32_e32 v37, 1.0, v37
	v_mul_f32_e32 v36, v36, v37

.LBB0_375:
	s_or_b64 exec, exec, s[12:13]
	v_add_u32_e32 v36, 58, v34
	v_cmp_gt_i32_e32 vcc, s17, v36
	ds_write_b32 v99, v35 offset:7392
	s_and_b64 s[18:19], s[4:5], vcc
	v_mov_b32_e32 v35, 0
	s_and_saveexec_b64 s[12:13], s[18:19]
	s_cbranch_execz .LBB0_387
	s_waitcnt vmcnt(0)
	v_mov_b32_e32 v35, v229
	s_and_b64 vcc, exec, s[2:3]
	s_cbranch_vccnz .LBB0_379
	s_ashr_i32 s39, s38, 31
	v_lshl_add_u64 v[36:37], s[38:39], 0, v[66:67]
	v_lshl_add_u64 v[36:37], v[36:37], 2, s[14:15]
	v_mov_b32_e32 v36, v157
	s_cmp_lt_i32 s50, 3
	s_mov_b64 s[18:19], -1
	s_cbranch_scc0 .LBB0_380

.LBB0_380:
	s_cmp_eq_u32 s50, 3
	s_waitcnt vmcnt(0)
	v_mov_b32_e32 v37, v36
	s_cbranch_scc0 .LBB0_382
	s_ashr_i32 s39, s38, 31
	v_lshl_add_u64 v[38:39], s[38:39], 0, v[66:67]
	v_lshl_add_u64 v[38:39], v[38:39], 2, s[40:41]
	v_mov_b32_e32 v37, v189
	s_waitcnt vmcnt(0)
	v_mul_f32_e32 v37, v36, v37

.LBB0_383:
	s_cmp_eq_u32 s50, 2
	s_cbranch_scc0 .LBB0_385
	s_ashr_i32 s39, s38, 31
	v_lshl_add_u64 v[38:39], s[38:39], 0, v[66:67]
	v_lshl_add_u64 v[38:39], v[38:39], 2, s[40:41]
	v_mov_b32_e32 v37, v189
	s_waitcnt vmcnt(0)
	v_sub_f32_e32 v37, 1.0, v37
	v_mul_f32_e32 v36, v36, v37

.LBB0_387:
	s_or_b64 exec, exec, s[12:13]
	v_add_u32_e32 v36, 60, v34
	v_cmp_gt_i32_e32 vcc, s17, v36
	ds_write_b32 v99, v35 offset:7656
	s_and_b64 s[18:19], s[4:5], vcc
	v_mov_b32_e32 v35, 0
	s_and_saveexec_b64 s[12:13], s[18:19]
	s_cbranch_execz .LBB0_399
	s_waitcnt vmcnt(0)
	v_mov_b32_e32 v35, v230
	s_and_b64 vcc, exec, s[2:3]
	s_cbranch_vccnz .LBB0_391
	s_ashr_i32 s39, s38, 31
	v_lshl_add_u64 v[36:37], s[38:39], 0, v[66:67]
	v_lshl_add_u64 v[36:37], v[36:37], 2, s[14:15]
	v_mov_b32_e32 v36, v158
	s_cmp_lt_i32 s50, 3
	s_mov_b64 s[18:19], -1
	s_cbranch_scc0 .LBB0_392

.LBB0_392:
	s_cmp_eq_u32 s50, 3
	s_waitcnt vmcnt(0)
	v_mov_b32_e32 v37, v36
	s_cbranch_scc0 .LBB0_394
	s_ashr_i32 s39, s38, 31
	v_lshl_add_u64 v[38:39], s[38:39], 0, v[66:67]
	v_lshl_add_u64 v[38:39], v[38:39], 2, s[40:41]
	v_mov_b32_e32 v37, v190
	s_waitcnt vmcnt(0)
	v_mul_f32_e32 v37, v36, v37

.LBB0_395:
	s_cmp_eq_u32 s50, 2
	s_cbranch_scc0 .LBB0_397
	s_ashr_i32 s39, s38, 31
	v_lshl_add_u64 v[38:39], s[38:39], 0, v[66:67]
	v_lshl_add_u64 v[38:39], v[38:39], 2, s[40:41]
	v_mov_b32_e32 v37, v190
	s_waitcnt vmcnt(0)
	v_sub_f32_e32 v37, 1.0, v37
	v_mul_f32_e32 v36, v36, v37

.LBB0_399:
	s_or_b64 exec, exec, s[12:13]
	ds_write_b32 v99, v35 offset:7920
	v_add_u32_e32 v35, 62, v34
	v_cmp_gt_i32_e32 vcc, s17, v35
	s_and_b64 s[12:13], s[4:5], vcc
	v_mov_b32_e32 v34, 0
	s_and_saveexec_b64 s[4:5], s[12:13]
	s_cbranch_execz .LBB0_411
	s_waitcnt vmcnt(0)
	v_mov_b32_e32 v32, v231
	s_and_b64 vcc, exec, s[2:3]
	s_cbranch_vccnz .LBB0_403
	s_ashr_i32 s39, s38, 31
	v_lshl_add_u64 v[34:35], s[38:39], 0, v[66:67]
	v_lshl_add_u64 v[34:35], v[34:35], 2, s[14:15]
	v_mov_b32_e32 v33, v159
	s_cmp_lt_i32 s50, 3
	s_mov_b64 s[2:3], -1
	s_cbranch_scc0 .LBB0_404

.LBB0_404:
	s_cmp_eq_u32 s50, 3
	s_waitcnt vmcnt(0)
	v_mov_b32_e32 v34, v33
	s_cbranch_scc0 .LBB0_406
	s_ashr_i32 s39, s38, 31
	v_lshl_add_u64 v[34:35], s[38:39], 0, v[66:67]
	v_lshl_add_u64 v[34:35], v[34:35], 2, s[40:41]
	v_mov_b32_e32 v34, v191
	s_waitcnt vmcnt(0)
	v_mul_f32_e32 v34, v33, v34

.LBB0_407:
	s_cmp_eq_u32 s50, 2
	s_cbranch_scc0 .LBB0_409
	s_ashr_i32 s39, s38, 31
	v_lshl_add_u64 v[34:35], s[38:39], 0, v[66:67]
	v_lshl_add_u64 v[34:35], v[34:35], 2, s[40:41]
	v_mov_b32_e32 v34, v191
	s_waitcnt vmcnt(0)
	v_sub_f32_e32 v34, 1.0, v34
	v_mul_f32_e32 v33, v33, v34

.LBB0_434:
	s_mul_i32 s2, s17, 0x50
	s_mul_hi_u32 s3, s16, 0x50
	s_add_i32 s3, s3, s2
	s_mul_i32 s2, s16, 0x50
	s_add_u32 s30, s0, s2
	s_addc_u32 s31, s1, s3
	s_load_dword s2, s[30:31], 0x150
	s_load_dword s40, s[30:31], 0x160
	s_load_dword s4, s[30:31], 0x168
	s_load_dwordx4 s[16:19], s[30:31], 0x140
	s_load_dwordx4 s[12:15], s[30:31], 0x120
	s_load_dwordx2 s[36:37], s[30:31], 0x130
	s_waitcnt lgkmcnt(0)
	s_ashr_i32 s3, s2, 31
	s_lshr_b32 s3, s3, 27
	s_add_i32 s2, s2, s3
	s_ashr_i32 s2, s2, 5
	s_abs_i32 s3, s2
	v_cvt_f32_u32_e32 v2, s3
	s_sub_i32 s34, 0, s3
	s_sub_i32 s4, s43, s4
	s_abs_i32 s5, s4
	v_rcp_iflag_f32_e32 v2, v2
	s_xor_b32 s19, s4, s2
	s_ashr_i32 s19, s19, 31
	v_mov_b32_e32 v3, s13
	v_mul_f32_e32 v2, 0x4f7ffffe, v2
	v_cvt_u32_f32_e32 v2, v2
	s_nop 0
	v_readfirstlane_b32 s35, v2
	s_mul_i32 s34, s34, s35
	s_mul_hi_u32 s34, s35, s34
	s_add_i32 s35, s35, s34
	s_mul_hi_u32 s34, s5, s35
	s_mul_i32 s35, s34, s3
	s_sub_i32 s5, s5, s35
	s_add_i32 s38, s34, 1
	s_sub_i32 s35, s5, s3
	s_cmp_ge_u32 s5, s3
	s_cselect_b32 s34, s38, s34
	s_cselect_b32 s5, s35, s5
	s_add_i32 s35, s34, 1
	s_cmp_ge_u32 s5, s3
	s_cselect_b32 s3, s35, s34
	s_xor_b32 s3, s3, s19
	s_sub_i32 s3, s3, s19
	s_mul_i32 s2, s3, s2
	s_sub_i32 s39, s4, s2
	s_lshl_b32 s38, s39, 5
	s_lshl_b32 s34, s3, 6
	v_or_b32_e32 v4, s38, v89
	v_mov_b32_e32 v2, s12
	v_ashrrev_i32_e32 v5, 31, v4
	s_cmp_lg_u64 s[14:15], 0
	v_cmp_gt_i32_e64 s[4:5], s18, v4
	v_lshl_add_u64 v[2:3], v[4:5], 2, v[2:3]
	s_cselect_b64 s[2:3], -1, 0
	v_add_u32_e32 v4, s34, v66
	v_cmp_gt_i32_e32 vcc, s17, v4
	v_cndmask_b32_e64 v8, 0, 1, s[2:3]
	s_and_b64 s[18:19], s[4:5], vcc
	v_mov_b32_e32 v5, 0
	v_cmp_ne_u32_e64 s[2:3], 1, v8
	s_cmp_lg_u64 s[14:15], 0
	s_cselect_b32 s92, 1, 0
	s_cmp_gt_i32 s40, 1
	s_cselect_b32 s93, 1, 0
	v_mov_b32_e32 v236, v4
	v_ashrrev_i32_e32 v237, 31, v4
	v_lshl_add_u64 v[238:239], v[236:237], 2, s[14:15]
	v_lshl_add_u64 v[240:241], v[236:237], 2, s[36:37]
	v_add_u32_e32 v232, 0, v4
	v_cmp_gt_i32_e32 vcc, s17, v232
	s_nop 0
	s_and_b64 s[94:95], s[4:5], vcc
	s_and_saveexec_b64 s[96:97], s[94:95]
	s_cbranch_execz .Lcvpf1_0
	v_mad_i64_i32 v[234:235], s[98:99], s16, v232, 0
	v_lshl_add_u64 v[234:235], v[234:235], 2, v[2:3]
	global_load_dword v200, v[234:235], off
	s_cmp_lg_u32 s92, 0
	s_cbranch_scc0 .Lcvpa1_0
	global_load_dword v128, v[238:239], off

.Lcvpf1_0:
	s_or_b64 exec, exec, s[96:97]
	v_add_u32_e32 v232, 2, v4
	v_cmp_gt_i32_e32 vcc, s17, v232
	s_nop 0
	s_and_b64 s[94:95], s[4:5], vcc
	s_and_saveexec_b64 s[96:97], s[94:95]
	s_cbranch_execz .Lcvpf1_1
	v_mad_i64_i32 v[234:235], s[98:99], s16, v232, 0
	v_lshl_add_u64 v[234:235], v[234:235], 2, v[2:3]
	global_load_dword v201, v[234:235], off
	s_cmp_lg_u32 s92, 0
	s_cbranch_scc0 .Lcvpa1_1
	global_load_dword v129, v[238:239], off offset:8

.Lcvpf1_1:
	s_or_b64 exec, exec, s[96:97]
	v_add_u32_e32 v232, 4, v4
	v_cmp_gt_i32_e32 vcc, s17, v232
	s_nop 0
	s_and_b64 s[94:95], s[4:5], vcc
	s_and_saveexec_b64 s[96:97], s[94:95]
	s_cbranch_execz .Lcvpf1_2
	v_mad_i64_i32 v[234:235], s[98:99], s16, v232, 0
	v_lshl_add_u64 v[234:235], v[234:235], 2, v[2:3]
	global_load_dword v202, v[234:235], off
	s_cmp_lg_u32 s92, 0
	s_cbranch_scc0 .Lcvpa1_2
	global_load_dword v130, v[238:239], off offset:16

.Lcvpf1_2:
	s_or_b64 exec, exec, s[96:97]
	v_add_u32_e32 v232, 6, v4
	v_cmp_gt_i32_e32 vcc, s17, v232
	s_nop 0
	s_and_b64 s[94:95], s[4:5], vcc
	s_and_saveexec_b64 s[96:97], s[94:95]
	s_cbranch_execz .Lcvpf1_3
	v_mad_i64_i32 v[234:235], s[98:99], s16, v232, 0
	v_lshl_add_u64 v[234:235], v[234:235], 2, v[2:3]
	global_load_dword v203, v[234:235], off
	s_cmp_lg_u32 s92, 0
	s_cbranch_scc0 .Lcvpa1_3
	global_load_dword v131, v[238:239], off offset:24

.Lcvpf1_3:
	s_or_b64 exec, exec, s[96:97]
	v_add_u32_e32 v232, 8, v4
	v_cmp_gt_i32_e32 vcc, s17, v232
	s_nop 0
	s_and_b64 s[94:95], s[4:5], vcc
	s_and_saveexec_b64 s[96:97], s[94:95]
	s_cbranch_execz .Lcvpf1_4
	v_mad_i64_i32 v[234:235], s[98:99], s16, v232, 0
	v_lshl_add_u64 v[234:235], v[234:235], 2, v[2:3]
	global_load_dword v204, v[234:235], off
	s_cmp_lg_u32 s92, 0
	s_cbranch_scc0 .Lcvpa1_4
	global_load_dword v132, v[238:239], off offset:32

.Lcvpf1_4:
	s_or_b64 exec, exec, s[96:97]
	v_add_u32_e32 v232, 10, v4
	v_cmp_gt_i32_e32 vcc, s17, v232
	s_nop 0
	s_and_b64 s[94:95], s[4:5], vcc
	s_and_saveexec_b64 s[96:97], s[94:95]
	s_cbranch_execz .Lcvpf1_5
	v_mad_i64_i32 v[234:235], s[98:99], s16, v232, 0
	v_lshl_add_u64 v[234:235], v[234:235], 2, v[2:3]
	global_load_dword v205, v[234:235], off
	s_cmp_lg_u32 s92, 0
	s_cbranch_scc0 .Lcvpa1_5
	global_load_dword v133, v[238:239], off offset:40

.Lcvpf1_5:
	s_or_b64 exec, exec, s[96:97]
	v_add_u32_e32 v232, 12, v4
	v_cmp_gt_i32_e32 vcc, s17, v232
	s_nop 0
	s_and_b64 s[94:95], s[4:5], vcc
	s_and_saveexec_b64 s[96:97], s[94:95]
	s_cbranch_execz .Lcvpf1_6
	v_mad_i64_i32 v[234:235], s[98:99], s16, v232, 0
	v_lshl_add_u64 v[234:235], v[234:235], 2, v[2:3]
	global_load_dword v206, v[234:235], off
	s_cmp_lg_u32 s92, 0
	s_cbranch_scc0 .Lcvpa1_6
	global_load_dword v134, v[238:239], off offset:48

.Lcvpf1_6:
	s_or_b64 exec, exec, s[96:97]
	v_add_u32_e32 v232, 14, v4
	v_cmp_gt_i32_e32 vcc, s17, v232
	s_nop 0
	s_and_b64 s[94:95], s[4:5], vcc
	s_and_saveexec_b64 s[96:97], s[94:95]
	s_cbranch_execz .Lcvpf1_7
	v_mad_i64_i32 v[234:235], s[98:99], s16, v232, 0
	v_lshl_add_u64 v[234:235], v[234:235], 2, v[2:3]
	global_load_dword v207, v[234:235], off
	s_cmp_lg_u32 s92, 0
	s_cbranch_scc0 .Lcvpa1_7
	global_load_dword v135, v[238:239], off offset:56

.Lcvpf1_7:
	s_or_b64 exec, exec, s[96:97]
	v_add_u32_e32 v232, 16, v4
	v_cmp_gt_i32_e32 vcc, s17, v232
	s_nop 0
	s_and_b64 s[94:95], s[4:5], vcc
	s_and_saveexec_b64 s[96:97], s[94:95]
	s_cbranch_execz .Lcvpf1_8
	v_mad_i64_i32 v[234:235], s[98:99], s16, v232, 0
	v_lshl_add_u64 v[234:235], v[234:235], 2, v[2:3]
	global_load_dword v208, v[234:235], off
	s_cmp_lg_u32 s92, 0
	s_cbranch_scc0 .Lcvpa1_8
	global_load_dword v136, v[238:239], off offset:64

.Lcvpf1_8:
	s_or_b64 exec, exec, s[96:97]
	v_add_u32_e32 v232, 18, v4
	v_cmp_gt_i32_e32 vcc, s17, v232
	s_nop 0
	s_and_b64 s[94:95], s[4:5], vcc
	s_and_saveexec_b64 s[96:97], s[94:95]
	s_cbranch_execz .Lcvpf1_9
	v_mad_i64_i32 v[234:235], s[98:99], s16, v232, 0
	v_lshl_add_u64 v[234:235], v[234:235], 2, v[2:3]
	global_load_dword v209, v[234:235], off
	s_cmp_lg_u32 s92, 0
	s_cbranch_scc0 .Lcvpa1_9
	global_load_dword v137, v[238:239], off offset:72

.Lcvpf1_9:
	s_or_b64 exec, exec, s[96:97]
	v_add_u32_e32 v232, 20, v4
	v_cmp_gt_i32_e32 vcc, s17, v232
	s_nop 0
	s_and_b64 s[94:95], s[4:5], vcc
	s_and_saveexec_b64 s[96:97], s[94:95]
	s_cbranch_execz .Lcvpf1_10
	v_mad_i64_i32 v[234:235], s[98:99], s16, v232, 0
	v_lshl_add_u64 v[234:235], v[234:235], 2, v[2:3]
	global_load_dword v210, v[234:235], off
	s_cmp_lg_u32 s92, 0
	s_cbranch_scc0 .Lcvpa1_10
	global_load_dword v138, v[238:239], off offset:80

.Lcvpf1_10:
	s_or_b64 exec, exec, s[96:97]
	v_add_u32_e32 v232, 22, v4
	v_cmp_gt_i32_e32 vcc, s17, v232
	s_nop 0
	s_and_b64 s[94:95], s[4:5], vcc
	s_and_saveexec_b64 s[96:97], s[94:95]
	s_cbranch_execz .Lcvpf1_11
	v_mad_i64_i32 v[234:235], s[98:99], s16, v232, 0
	v_lshl_add_u64 v[234:235], v[234:235], 2, v[2:3]
	global_load_dword v211, v[234:235], off
	s_cmp_lg_u32 s92, 0
	s_cbranch_scc0 .Lcvpa1_11
	global_load_dword v139, v[238:239], off offset:88

.Lcvpf1_11:
	s_or_b64 exec, exec, s[96:97]
	v_add_u32_e32 v232, 24, v4
	v_cmp_gt_i32_e32 vcc, s17, v232
	s_nop 0
	s_and_b64 s[94:95], s[4:5], vcc
	s_and_saveexec_b64 s[96:97], s[94:95]
	s_cbranch_execz .Lcvpf1_12
	v_mad_i64_i32 v[234:235], s[98:99], s16, v232, 0
	v_lshl_add_u64 v[234:235], v[234:235], 2, v[2:3]
	global_load_dword v212, v[234:235], off
	s_cmp_lg_u32 s92, 0
	s_cbranch_scc0 .Lcvpa1_12
	global_load_dword v140, v[238:239], off offset:96

.Lcvpf1_12:
	s_or_b64 exec, exec, s[96:97]
	v_add_u32_e32 v232, 26, v4
	v_cmp_gt_i32_e32 vcc, s17, v232
	s_nop 0
	s_and_b64 s[94:95], s[4:5], vcc
	s_and_saveexec_b64 s[96:97], s[94:95]
	s_cbranch_execz .Lcvpf1_13
	v_mad_i64_i32 v[234:235], s[98:99], s16, v232, 0
	v_lshl_add_u64 v[234:235], v[234:235], 2, v[2:3]
	global_load_dword v213, v[234:235], off
	s_cmp_lg_u32 s92, 0
	s_cbranch_scc0 .Lcvpa1_13
	global_load_dword v141, v[238:239], off offset:104

.Lcvpf1_13:
	s_or_b64 exec, exec, s[96:97]
	v_add_u32_e32 v232, 28, v4
	v_cmp_gt_i32_e32 vcc, s17, v232
	s_nop 0
	s_and_b64 s[94:95], s[4:5], vcc
	s_and_saveexec_b64 s[96:97], s[94:95]
	s_cbranch_execz .Lcvpf1_14
	v_mad_i64_i32 v[234:235], s[98:99], s16, v232, 0
	v_lshl_add_u64 v[234:235], v[234:235], 2, v[2:3]
	global_load_dword v214, v[234:235], off
	s_cmp_lg_u32 s92, 0
	s_cbranch_scc0 .Lcvpa1_14
	global_load_dword v142, v[238:239], off offset:112

.Lcvpf1_14:
	s_or_b64 exec, exec, s[96:97]
	v_add_u32_e32 v232, 30, v4
	v_cmp_gt_i32_e32 vcc, s17, v232
	s_nop 0
	s_and_b64 s[94:95], s[4:5], vcc
	s_and_saveexec_b64 s[96:97], s[94:95]
	s_cbranch_execz .Lcvpf1_15
	v_mad_i64_i32 v[234:235], s[98:99], s16, v232, 0
	v_lshl_add_u64 v[234:235], v[234:235], 2, v[2:3]
	global_load_dword v215, v[234:235], off
	s_cmp_lg_u32 s92, 0
	s_cbranch_scc0 .Lcvpa1_15
	global_load_dword v143, v[238:239], off offset:120

.Lcvpf1_15:
	s_or_b64 exec, exec, s[96:97]
	v_add_u32_e32 v232, 32, v4
	v_cmp_gt_i32_e32 vcc, s17, v232
	s_nop 0
	s_and_b64 s[94:95], s[4:5], vcc
	s_and_saveexec_b64 s[96:97], s[94:95]
	s_cbranch_execz .Lcvpf1_16
	v_mad_i64_i32 v[234:235], s[98:99], s16, v232, 0
	v_lshl_add_u64 v[234:235], v[234:235], 2, v[2:3]
	global_load_dword v216, v[234:235], off
	s_cmp_lg_u32 s92, 0
	s_cbranch_scc0 .Lcvpa1_16
	global_load_dword v144, v[238:239], off offset:128

.Lcvpf1_16:
	s_or_b64 exec, exec, s[96:97]
	v_add_u32_e32 v232, 34, v4
	v_cmp_gt_i32_e32 vcc, s17, v232
	s_nop 0
	s_and_b64 s[94:95], s[4:5], vcc
	s_and_saveexec_b64 s[96:97], s[94:95]
	s_cbranch_execz .Lcvpf1_17
	v_mad_i64_i32 v[234:235], s[98:99], s16, v232, 0
	v_lshl_add_u64 v[234:235], v[234:235], 2, v[2:3]
	global_load_dword v217, v[234:235], off
	s_cmp_lg_u32 s92, 0
	s_cbranch_scc0 .Lcvpa1_17
	global_load_dword v145, v[238:239], off offset:136

.Lcvpf1_17:
	s_or_b64 exec, exec, s[96:97]
	v_add_u32_e32 v232, 36, v4
	v_cmp_gt_i32_e32 vcc, s17, v232
	s_nop 0
	s_and_b64 s[94:95], s[4:5], vcc
	s_and_saveexec_b64 s[96:97], s[94:95]
	s_cbranch_execz .Lcvpf1_18
	v_mad_i64_i32 v[234:235], s[98:99], s16, v232, 0
	v_lshl_add_u64 v[234:235], v[234:235], 2, v[2:3]
	global_load_dword v218, v[234:235], off
	s_cmp_lg_u32 s92, 0
	s_cbranch_scc0 .Lcvpa1_18
	global_load_dword v146, v[238:239], off offset:144

.Lcvpf1_18:
	s_or_b64 exec, exec, s[96:97]
	v_add_u32_e32 v232, 38, v4
	v_cmp_gt_i32_e32 vcc, s17, v232
	s_nop 0
	s_and_b64 s[94:95], s[4:5], vcc
	s_and_saveexec_b64 s[96:97], s[94:95]
	s_cbranch_execz .Lcvpf1_19
	v_mad_i64_i32 v[234:235], s[98:99], s16, v232, 0
	v_lshl_add_u64 v[234:235], v[234:235], 2, v[2:3]
	global_load_dword v219, v[234:235], off
	s_cmp_lg_u32 s92, 0
	s_cbranch_scc0 .Lcvpa1_19
	global_load_dword v147, v[238:239], off offset:152

.Lcvpf1_19:
	s_or_b64 exec, exec, s[96:97]
	v_add_u32_e32 v232, 40, v4
	v_cmp_gt_i32_e32 vcc, s17, v232
	s_nop 0
	s_and_b64 s[94:95], s[4:5], vcc
	s_and_saveexec_b64 s[96:97], s[94:95]
	s_cbranch_execz .Lcvpf1_20
	v_mad_i64_i32 v[234:235], s[98:99], s16, v232, 0
	v_lshl_add_u64 v[234:235], v[234:235], 2, v[2:3]
	global_load_dword v220, v[234:235], off
	s_cmp_lg_u32 s92, 0
	s_cbranch_scc0 .Lcvpa1_20
	global_load_dword v148, v[238:239], off offset:160

.Lcvpf1_20:
	s_or_b64 exec, exec, s[96:97]
	v_add_u32_e32 v232, 42, v4
	v_cmp_gt_i32_e32 vcc, s17, v232
	s_nop 0
	s_and_b64 s[94:95], s[4:5], vcc
	s_and_saveexec_b64 s[96:97], s[94:95]
	s_cbranch_execz .Lcvpf1_21
	v_mad_i64_i32 v[234:235], s[98:99], s16, v232, 0
	v_lshl_add_u64 v[234:235], v[234:235], 2, v[2:3]
	global_load_dword v221, v[234:235], off
	s_cmp_lg_u32 s92, 0
	s_cbranch_scc0 .Lcvpa1_21
	global_load_dword v149, v[238:239], off offset:168

.Lcvpf1_21:
	s_or_b64 exec, exec, s[96:97]
	v_add_u32_e32 v232, 44, v4
	v_cmp_gt_i32_e32 vcc, s17, v232
	s_nop 0
	s_and_b64 s[94:95], s[4:5], vcc
	s_and_saveexec_b64 s[96:97], s[94:95]
	s_cbranch_execz .Lcvpf1_22
	v_mad_i64_i32 v[234:235], s[98:99], s16, v232, 0
	v_lshl_add_u64 v[234:235], v[234:235], 2, v[2:3]
	global_load_dword v222, v[234:235], off
	s_cmp_lg_u32 s92, 0
	s_cbranch_scc0 .Lcvpa1_22
	global_load_dword v150, v[238:239], off offset:176

.Lcvpf1_22:
	s_or_b64 exec, exec, s[96:97]
	v_add_u32_e32 v232, 46, v4
	v_cmp_gt_i32_e32 vcc, s17, v232
	s_nop 0
	s_and_b64 s[94:95], s[4:5], vcc
	s_and_saveexec_b64 s[96:97], s[94:95]
	s_cbranch_execz .Lcvpf1_23
	v_mad_i64_i32 v[234:235], s[98:99], s16, v232, 0
	v_lshl_add_u64 v[234:235], v[234:235], 2, v[2:3]
	global_load_dword v223, v[234:235], off
	s_cmp_lg_u32 s92, 0
	s_cbranch_scc0 .Lcvpa1_23
	global_load_dword v151, v[238:239], off offset:184

.Lcvpf1_23:
	s_or_b64 exec, exec, s[96:97]
	v_add_u32_e32 v232, 48, v4
	v_cmp_gt_i32_e32 vcc, s17, v232
	s_nop 0
	s_and_b64 s[94:95], s[4:5], vcc
	s_and_saveexec_b64 s[96:97], s[94:95]
	s_cbranch_execz .Lcvpf1_24
	v_mad_i64_i32 v[234:235], s[98:99], s16, v232, 0
	v_lshl_add_u64 v[234:235], v[234:235], 2, v[2:3]
	global_load_dword v224, v[234:235], off
	s_cmp_lg_u32 s92, 0
	s_cbranch_scc0 .Lcvpa1_24
	global_load_dword v152, v[238:239], off offset:192

.Lcvpf1_24:
	s_or_b64 exec, exec, s[96:97]
	v_add_u32_e32 v232, 50, v4
	v_cmp_gt_i32_e32 vcc, s17, v232
	s_nop 0
	s_and_b64 s[94:95], s[4:5], vcc
	s_and_saveexec_b64 s[96:97], s[94:95]
	s_cbranch_execz .Lcvpf1_25
	v_mad_i64_i32 v[234:235], s[98:99], s16, v232, 0
	v_lshl_add_u64 v[234:235], v[234:235], 2, v[2:3]
	global_load_dword v225, v[234:235], off
	s_cmp_lg_u32 s92, 0
	s_cbranch_scc0 .Lcvpa1_25
	global_load_dword v153, v[238:239], off offset:200

.Lcvpf1_25:
	s_or_b64 exec, exec, s[96:97]
	v_add_u32_e32 v232, 52, v4
	v_cmp_gt_i32_e32 vcc, s17, v232
	s_nop 0
	s_and_b64 s[94:95], s[4:5], vcc
	s_and_saveexec_b64 s[96:97], s[94:95]
	s_cbranch_execz .Lcvpf1_26
	v_mad_i64_i32 v[234:235], s[98:99], s16, v232, 0
	v_lshl_add_u64 v[234:235], v[234:235], 2, v[2:3]
	global_load_dword v226, v[234:235], off
	s_cmp_lg_u32 s92, 0
	s_cbranch_scc0 .Lcvpa1_26
	global_load_dword v154, v[238:239], off offset:208

.Lcvpf1_26:
	s_or_b64 exec, exec, s[96:97]
	v_add_u32_e32 v232, 54, v4
	v_cmp_gt_i32_e32 vcc, s17, v232
	s_nop 0
	s_and_b64 s[94:95], s[4:5], vcc
	s_and_saveexec_b64 s[96:97], s[94:95]
	s_cbranch_execz .Lcvpf1_27
	v_mad_i64_i32 v[234:235], s[98:99], s16, v232, 0
	v_lshl_add_u64 v[234:235], v[234:235], 2, v[2:3]
	global_load_dword v227, v[234:235], off
	s_cmp_lg_u32 s92, 0
	s_cbranch_scc0 .Lcvpa1_27
	global_load_dword v155, v[238:239], off offset:216

.Lcvpf1_27:
	s_or_b64 exec, exec, s[96:97]
	v_add_u32_e32 v232, 56, v4
	v_cmp_gt_i32_e32 vcc, s17, v232
	s_nop 0
	s_and_b64 s[94:95], s[4:5], vcc
	s_and_saveexec_b64 s[96:97], s[94:95]
	s_cbranch_execz .Lcvpf1_28
	v_mad_i64_i32 v[234:235], s[98:99], s16, v232, 0
	v_lshl_add_u64 v[234:235], v[234:235], 2, v[2:3]
	global_load_dword v228, v[234:235], off
	s_cmp_lg_u32 s92, 0
	s_cbranch_scc0 .Lcvpa1_28
	global_load_dword v156, v[238:239], off offset:224

.Lcvpf1_28:
	s_or_b64 exec, exec, s[96:97]
	v_add_u32_e32 v232, 58, v4
	v_cmp_gt_i32_e32 vcc, s17, v232
	s_nop 0
	s_and_b64 s[94:95], s[4:5], vcc
	s_and_saveexec_b64 s[96:97], s[94:95]
	s_cbranch_execz .Lcvpf1_29
	v_mad_i64_i32 v[234:235], s[98:99], s16, v232, 0
	v_lshl_add_u64 v[234:235], v[234:235], 2, v[2:3]
	global_load_dword v229, v[234:235], off
	s_cmp_lg_u32 s92, 0
	s_cbranch_scc0 .Lcvpa1_29
	global_load_dword v157, v[238:239], off offset:232

.Lcvpf1_29:
	s_or_b64 exec, exec, s[96:97]
	v_add_u32_e32 v232, 60, v4
	v_cmp_gt_i32_e32 vcc, s17, v232
	s_nop 0
	s_and_b64 s[94:95], s[4:5], vcc
	s_and_saveexec_b64 s[96:97], s[94:95]
	s_cbranch_execz .Lcvpf1_30
	v_mad_i64_i32 v[234:235], s[98:99], s16, v232, 0
	v_lshl_add_u64 v[234:235], v[234:235], 2, v[2:3]
	global_load_dword v230, v[234:235], off
	s_cmp_lg_u32 s92, 0
	s_cbranch_scc0 .Lcvpa1_30
	global_load_dword v158, v[238:239], off offset:240

.Lcvpf1_30:
	s_or_b64 exec, exec, s[96:97]
	v_add_u32_e32 v232, 62, v4
	v_cmp_gt_i32_e32 vcc, s17, v232
	s_nop 0
	s_and_b64 s[94:95], s[4:5], vcc
	s_and_saveexec_b64 s[96:97], s[94:95]
	s_cbranch_execz .Lcvpf1_31
	v_mad_i64_i32 v[234:235], s[98:99], s16, v232, 0
	v_lshl_add_u64 v[234:235], v[234:235], 2, v[2:3]
	global_load_dword v231, v[234:235], off
	s_cmp_lg_u32 s92, 0
	s_cbranch_scc0 .Lcvpa1_31
	global_load_dword v159, v[238:239], off offset:248

.Lcvpf1_31:
	s_or_b64 exec, exec, s[96:97]
	s_and_saveexec_b64 s[12:13], s[18:19]
	s_cbranch_execz .LBB0_446
	s_waitcnt vmcnt(0)
	v_mov_b32_e32 v8, v200
	s_and_b64 vcc, exec, s[2:3]
	v_ashrrev_i32_e32 v5, 31, v4
	s_cbranch_vccnz .LBB0_438
	v_lshl_add_u64 v[10:11], v[4:5], 2, s[14:15]
	v_mov_b32_e32 v9, v128
	s_cmp_lt_i32 s40, 3
	s_mov_b64 s[18:19], -1
	s_cbranch_scc0 .LBB0_439

.LBB0_439:
	s_cmp_eq_u32 s40, 3
	s_waitcnt vmcnt(0)
	v_mov_b32_e32 v10, v9
	s_cbranch_scc0 .LBB0_441
	v_lshl_add_u64 v[10:11], v[4:5], 2, s[36:37]
	v_mov_b32_e32 v10, v160
	s_waitcnt vmcnt(0)
	v_mul_f32_e32 v10, v9, v10

.LBB0_442:
	s_cmp_lg_u32 s40, 2
	s_cbranch_scc1 .LBB0_444
	v_lshl_add_u64 v[10:11], v[4:5], 2, s[36:37]
	v_mov_b32_e32 v5, v160
	s_waitcnt vmcnt(0)
	v_sub_f32_e32 v5, 1.0, v5
	v_mul_f32_e32 v9, v9, v5

.LBB0_446:
	s_or_b64 exec, exec, s[12:13]
	v_add_u32_e32 v8, 2, v4
	v_cmp_gt_i32_e32 vcc, s17, v8
	ds_write_b32 v7, v5
	s_and_b64 s[18:19], s[4:5], vcc
	v_mov_b32_e32 v5, 0
	s_and_saveexec_b64 s[12:13], s[18:19]
	s_cbranch_execz .LBB0_458
	s_waitcnt vmcnt(0)
	v_mov_b32_e32 v5, v201
	s_and_b64 vcc, exec, s[2:3]
	s_cbranch_vccnz .LBB0_450
	s_ashr_i32 s35, s34, 31
	v_lshl_add_u64 v[8:9], s[34:35], 0, v[66:67]
	v_lshl_add_u64 v[8:9], v[8:9], 2, s[14:15]
	v_mov_b32_e32 v8, v129
	s_cmp_lt_i32 s40, 3
	s_mov_b64 s[18:19], -1
	s_cbranch_scc0 .LBB0_451

.LBB0_451:
	s_cmp_eq_u32 s40, 3
	s_waitcnt vmcnt(0)
	v_mov_b32_e32 v9, v8
	s_cbranch_scc0 .LBB0_453
	s_ashr_i32 s35, s34, 31
	v_lshl_add_u64 v[10:11], s[34:35], 0, v[66:67]
	v_lshl_add_u64 v[10:11], v[10:11], 2, s[36:37]
	v_mov_b32_e32 v9, v161
	s_waitcnt vmcnt(0)
	v_mul_f32_e32 v9, v8, v9

.LBB0_454:
	s_cmp_eq_u32 s40, 2
	s_cbranch_scc0 .LBB0_456
	s_ashr_i32 s35, s34, 31
	v_lshl_add_u64 v[10:11], s[34:35], 0, v[66:67]
	v_lshl_add_u64 v[10:11], v[10:11], 2, s[36:37]
	v_mov_b32_e32 v9, v161
	s_waitcnt vmcnt(0)
	v_sub_f32_e32 v9, 1.0, v9
	v_mul_f32_e32 v8, v8, v9

.LBB0_458:
	s_or_b64 exec, exec, s[12:13]
	v_add_u32_e32 v8, 4, v4
	v_cmp_gt_i32_e32 vcc, s17, v8
	ds_write_b32 v7, v5 offset:264
	s_and_b64 s[18:19], s[4:5], vcc
	v_mov_b32_e32 v5, 0
	s_and_saveexec_b64 s[12:13], s[18:19]
	s_cbranch_execz .LBB0_470
	s_waitcnt vmcnt(0)
	v_mov_b32_e32 v5, v202
	s_and_b64 vcc, exec, s[2:3]
	s_cbranch_vccnz .LBB0_462
	s_ashr_i32 s35, s34, 31
	v_lshl_add_u64 v[8:9], s[34:35], 0, v[66:67]
	v_lshl_add_u64 v[8:9], v[8:9], 2, s[14:15]
	v_mov_b32_e32 v8, v130
	s_cmp_lt_i32 s40, 3
	s_mov_b64 s[18:19], -1
	s_cbranch_scc0 .LBB0_463

.LBB0_463:
	s_cmp_eq_u32 s40, 3
	s_waitcnt vmcnt(0)
	v_mov_b32_e32 v9, v8
	s_cbranch_scc0 .LBB0_465
	s_ashr_i32 s35, s34, 31
	v_lshl_add_u64 v[10:11], s[34:35], 0, v[66:67]
	v_lshl_add_u64 v[10:11], v[10:11], 2, s[36:37]
	v_mov_b32_e32 v9, v162
	s_waitcnt vmcnt(0)
	v_mul_f32_e32 v9, v8, v9

.LBB0_466:
	s_cmp_eq_u32 s40, 2
	s_cbranch_scc0 .LBB0_468
	s_ashr_i32 s35, s34, 31
	v_lshl_add_u64 v[10:11], s[34:35], 0, v[66:67]
	v_lshl_add_u64 v[10:11], v[10:11], 2, s[36:37]
	v_mov_b32_e32 v9, v162
	s_waitcnt vmcnt(0)
	v_sub_f32_e32 v9, 1.0, v9
	v_mul_f32_e32 v8, v8, v9

.LBB0_470:
	s_or_b64 exec, exec, s[12:13]
	v_add_u32_e32 v8, 6, v4
	v_cmp_gt_i32_e32 vcc, s17, v8
	ds_write_b32 v7, v5 offset:528
	s_and_b64 s[18:19], s[4:5], vcc
	v_mov_b32_e32 v5, 0
	s_and_saveexec_b64 s[12:13], s[18:19]
	s_cbranch_execz .LBB0_482
	s_waitcnt vmcnt(0)
	v_mov_b32_e32 v5, v203
	s_and_b64 vcc, exec, s[2:3]
	s_cbranch_vccnz .LBB0_474
	s_ashr_i32 s35, s34, 31
	v_lshl_add_u64 v[8:9], s[34:35], 0, v[66:67]
	v_lshl_add_u64 v[8:9], v[8:9], 2, s[14:15]
	v_mov_b32_e32 v8, v131
	s_cmp_lt_i32 s40, 3
	s_mov_b64 s[18:19], -1
	s_cbranch_scc0 .LBB0_475

.LBB0_475:
	s_cmp_eq_u32 s40, 3
	s_waitcnt vmcnt(0)
	v_mov_b32_e32 v9, v8
	s_cbranch_scc0 .LBB0_477
	s_ashr_i32 s35, s34, 31
	v_lshl_add_u64 v[10:11], s[34:35], 0, v[66:67]
	v_lshl_add_u64 v[10:11], v[10:11], 2, s[36:37]
	v_mov_b32_e32 v9, v163
	s_waitcnt vmcnt(0)
	v_mul_f32_e32 v9, v8, v9

.LBB0_478:
	s_cmp_eq_u32 s40, 2
	s_cbranch_scc0 .LBB0_480
	s_ashr_i32 s35, s34, 31
	v_lshl_add_u64 v[10:11], s[34:35], 0, v[66:67]
	v_lshl_add_u64 v[10:11], v[10:11], 2, s[36:37]
	v_mov_b32_e32 v9, v163
	s_waitcnt vmcnt(0)
	v_sub_f32_e32 v9, 1.0, v9
	v_mul_f32_e32 v8, v8, v9

.LBB0_482:
	s_or_b64 exec, exec, s[12:13]
	v_add_u32_e32 v8, 8, v4
	v_cmp_gt_i32_e32 vcc, s17, v8
	ds_write_b32 v7, v5 offset:792
	s_and_b64 s[18:19], s[4:5], vcc
	v_mov_b32_e32 v5, 0
	s_and_saveexec_b64 s[12:13], s[18:19]
	s_cbranch_execz .LBB0_494
	s_waitcnt vmcnt(0)
	v_mov_b32_e32 v5, v204
	s_and_b64 vcc, exec, s[2:3]
	s_cbranch_vccnz .LBB0_486
	s_ashr_i32 s35, s34, 31
	v_lshl_add_u64 v[8:9], s[34:35], 0, v[66:67]
	v_lshl_add_u64 v[8:9], v[8:9], 2, s[14:15]
	v_mov_b32_e32 v8, v132
	s_cmp_lt_i32 s40, 3
	s_mov_b64 s[18:19], -1
	s_cbranch_scc0 .LBB0_487

.LBB0_487:
	s_cmp_eq_u32 s40, 3
	s_waitcnt vmcnt(0)
	v_mov_b32_e32 v9, v8
	s_cbranch_scc0 .LBB0_489
	s_ashr_i32 s35, s34, 31
	v_lshl_add_u64 v[10:11], s[34:35], 0, v[66:67]
	v_lshl_add_u64 v[10:11], v[10:11], 2, s[36:37]
	v_mov_b32_e32 v9, v164
	s_waitcnt vmcnt(0)
	v_mul_f32_e32 v9, v8, v9

.LBB0_490:
	s_cmp_eq_u32 s40, 2
	s_cbranch_scc0 .LBB0_492
	s_ashr_i32 s35, s34, 31
	v_lshl_add_u64 v[10:11], s[34:35], 0, v[66:67]
	v_lshl_add_u64 v[10:11], v[10:11], 2, s[36:37]
	v_mov_b32_e32 v9, v164
	s_waitcnt vmcnt(0)
	v_sub_f32_e32 v9, 1.0, v9
	v_mul_f32_e32 v8, v8, v9

.LBB0_494:
	s_or_b64 exec, exec, s[12:13]
	v_add_u32_e32 v8, 10, v4
	v_cmp_gt_i32_e32 vcc, s17, v8
	ds_write_b32 v7, v5 offset:1056
	s_and_b64 s[18:19], s[4:5], vcc
	v_mov_b32_e32 v5, 0
	s_and_saveexec_b64 s[12:13], s[18:19]
	s_cbranch_execz .LBB0_506
	s_waitcnt vmcnt(0)
	v_mov_b32_e32 v5, v205
	s_and_b64 vcc, exec, s[2:3]
	s_cbranch_vccnz .LBB0_498
	s_ashr_i32 s35, s34, 31
	v_lshl_add_u64 v[8:9], s[34:35], 0, v[66:67]
	v_lshl_add_u64 v[8:9], v[8:9], 2, s[14:15]
	v_mov_b32_e32 v8, v133
	s_cmp_lt_i32 s40, 3
	s_mov_b64 s[18:19], -1
	s_cbranch_scc0 .LBB0_499

.LBB0_499:
	s_cmp_eq_u32 s40, 3
	s_waitcnt vmcnt(0)
	v_mov_b32_e32 v9, v8
	s_cbranch_scc0 .LBB0_501
	s_ashr_i32 s35, s34, 31
	v_lshl_add_u64 v[10:11], s[34:35], 0, v[66:67]
	v_lshl_add_u64 v[10:11], v[10:11], 2, s[36:37]
	v_mov_b32_e32 v9, v165
	s_waitcnt vmcnt(0)
	v_mul_f32_e32 v9, v8, v9

.LBB0_502:
	s_cmp_eq_u32 s40, 2
	s_cbranch_scc0 .LBB0_504
	s_ashr_i32 s35, s34, 31
	v_lshl_add_u64 v[10:11], s[34:35], 0, v[66:67]
	v_lshl_add_u64 v[10:11], v[10:11], 2, s[36:37]
	v_mov_b32_e32 v9, v165
	s_waitcnt vmcnt(0)
	v_sub_f32_e32 v9, 1.0, v9
	v_mul_f32_e32 v8, v8, v9

.LBB0_506:
	s_or_b64 exec, exec, s[12:13]
	v_add_u32_e32 v8, 12, v4
	v_cmp_gt_i32_e32 vcc, s17, v8
	ds_write_b32 v7, v5 offset:1320
	s_and_b64 s[18:19], s[4:5], vcc
	v_mov_b32_e32 v5, 0
	s_and_saveexec_b64 s[12:13], s[18:19]
	s_cbranch_execz .LBB0_518
	s_waitcnt vmcnt(0)
	v_mov_b32_e32 v5, v206
	s_and_b64 vcc, exec, s[2:3]
	s_cbranch_vccnz .LBB0_510
	s_ashr_i32 s35, s34, 31
	v_lshl_add_u64 v[8:9], s[34:35], 0, v[66:67]
	v_lshl_add_u64 v[8:9], v[8:9], 2, s[14:15]
	v_mov_b32_e32 v8, v134
	s_cmp_lt_i32 s40, 3
	s_mov_b64 s[18:19], -1
	s_cbranch_scc0 .LBB0_511

.LBB0_511:
	s_cmp_eq_u32 s40, 3
	s_waitcnt vmcnt(0)
	v_mov_b32_e32 v9, v8
	s_cbranch_scc0 .LBB0_513
	s_ashr_i32 s35, s34, 31
	v_lshl_add_u64 v[10:11], s[34:35], 0, v[66:67]
	v_lshl_add_u64 v[10:11], v[10:11], 2, s[36:37]
	v_mov_b32_e32 v9, v166
	s_waitcnt vmcnt(0)
	v_mul_f32_e32 v9, v8, v9

.LBB0_514:
	s_cmp_eq_u32 s40, 2
	s_cbranch_scc0 .LBB0_516
	s_ashr_i32 s35, s34, 31
	v_lshl_add_u64 v[10:11], s[34:35], 0, v[66:67]
	v_lshl_add_u64 v[10:11], v[10:11], 2, s[36:37]
	v_mov_b32_e32 v9, v166
	s_waitcnt vmcnt(0)
	v_sub_f32_e32 v9, 1.0, v9
	v_mul_f32_e32 v8, v8, v9

.LBB0_518:
	s_or_b64 exec, exec, s[12:13]
	v_add_u32_e32 v8, 14, v4
	v_cmp_gt_i32_e32 vcc, s17, v8
	ds_write_b32 v7, v5 offset:1584
	s_and_b64 s[18:19], s[4:5], vcc
	v_mov_b32_e32 v5, 0
	s_and_saveexec_b64 s[12:13], s[18:19]
	s_cbranch_execz .LBB0_530
	s_waitcnt vmcnt(0)
	v_mov_b32_e32 v5, v207
	s_and_b64 vcc, exec, s[2:3]
	s_cbranch_vccnz .LBB0_522
	s_ashr_i32 s35, s34, 31
	v_lshl_add_u64 v[8:9], s[34:35], 0, v[66:67]
	v_lshl_add_u64 v[8:9], v[8:9], 2, s[14:15]
	v_mov_b32_e32 v8, v135
	s_cmp_lt_i32 s40, 3
	s_mov_b64 s[18:19], -1
	s_cbranch_scc0 .LBB0_523

.LBB0_523:
	s_cmp_eq_u32 s40, 3
	s_waitcnt vmcnt(0)
	v_mov_b32_e32 v9, v8
	s_cbranch_scc0 .LBB0_525
	s_ashr_i32 s35, s34, 31
	v_lshl_add_u64 v[10:11], s[34:35], 0, v[66:67]
	v_lshl_add_u64 v[10:11], v[10:11], 2, s[36:37]
	v_mov_b32_e32 v9, v167
	s_waitcnt vmcnt(0)
	v_mul_f32_e32 v9, v8, v9

.LBB0_526:
	s_cmp_eq_u32 s40, 2
	s_cbranch_scc0 .LBB0_528
	s_ashr_i32 s35, s34, 31
	v_lshl_add_u64 v[10:11], s[34:35], 0, v[66:67]
	v_lshl_add_u64 v[10:11], v[10:11], 2, s[36:37]
	v_mov_b32_e32 v9, v167
	s_waitcnt vmcnt(0)
	v_sub_f32_e32 v9, 1.0, v9
	v_mul_f32_e32 v8, v8, v9

.LBB0_530:
	s_or_b64 exec, exec, s[12:13]
	v_add_u32_e32 v8, 16, v4
	v_cmp_gt_i32_e32 vcc, s17, v8
	ds_write_b32 v7, v5 offset:1848
	s_and_b64 s[18:19], s[4:5], vcc
	v_mov_b32_e32 v5, 0
	s_and_saveexec_b64 s[12:13], s[18:19]
	s_cbranch_execz .LBB0_542
	s_waitcnt vmcnt(0)
	v_mov_b32_e32 v5, v208
	s_and_b64 vcc, exec, s[2:3]
	s_cbranch_vccnz .LBB0_534
	s_ashr_i32 s35, s34, 31
	v_lshl_add_u64 v[8:9], s[34:35], 0, v[66:67]
	v_lshl_add_u64 v[8:9], v[8:9], 2, s[14:15]
	v_mov_b32_e32 v8, v136
	s_cmp_lt_i32 s40, 3
	s_mov_b64 s[18:19], -1
	s_cbranch_scc0 .LBB0_535

.LBB0_535:
	s_cmp_eq_u32 s40, 3
	s_waitcnt vmcnt(0)
	v_mov_b32_e32 v9, v8
	s_cbranch_scc0 .LBB0_537
	s_ashr_i32 s35, s34, 31
	v_lshl_add_u64 v[10:11], s[34:35], 0, v[66:67]
	v_lshl_add_u64 v[10:11], v[10:11], 2, s[36:37]
	v_mov_b32_e32 v9, v168
	s_waitcnt vmcnt(0)
	v_mul_f32_e32 v9, v8, v9

.LBB0_538:
	s_cmp_eq_u32 s40, 2
	s_cbranch_scc0 .LBB0_540
	s_ashr_i32 s35, s34, 31
	v_lshl_add_u64 v[10:11], s[34:35], 0, v[66:67]
	v_lshl_add_u64 v[10:11], v[10:11], 2, s[36:37]
	v_mov_b32_e32 v9, v168
	s_waitcnt vmcnt(0)
	v_sub_f32_e32 v9, 1.0, v9
	v_mul_f32_e32 v8, v8, v9

.LBB0_542:
	s_or_b64 exec, exec, s[12:13]
	v_add_u32_e32 v8, 18, v4
	v_cmp_gt_i32_e32 vcc, s17, v8
	ds_write_b32 v7, v5 offset:2112
	s_and_b64 s[18:19], s[4:5], vcc
	v_mov_b32_e32 v5, 0
	s_and_saveexec_b64 s[12:13], s[18:19]
	s_cbranch_execz .LBB0_554
	s_waitcnt vmcnt(0)
	v_mov_b32_e32 v5, v209
	s_and_b64 vcc, exec, s[2:3]
	s_cbranch_vccnz .LBB0_546
	s_ashr_i32 s35, s34, 31
	v_lshl_add_u64 v[8:9], s[34:35], 0, v[66:67]
	v_lshl_add_u64 v[8:9], v[8:9], 2, s[14:15]
	v_mov_b32_e32 v8, v137
	s_cmp_lt_i32 s40, 3
	s_mov_b64 s[18:19], -1
	s_cbranch_scc0 .LBB0_547

.LBB0_547:
	s_cmp_eq_u32 s40, 3
	s_waitcnt vmcnt(0)
	v_mov_b32_e32 v9, v8
	s_cbranch_scc0 .LBB0_549
	s_ashr_i32 s35, s34, 31
	v_lshl_add_u64 v[10:11], s[34:35], 0, v[66:67]
	v_lshl_add_u64 v[10:11], v[10:11], 2, s[36:37]
	v_mov_b32_e32 v9, v169
	s_waitcnt vmcnt(0)
	v_mul_f32_e32 v9, v8, v9

.LBB0_550:
	s_cmp_eq_u32 s40, 2
	s_cbranch_scc0 .LBB0_552
	s_ashr_i32 s35, s34, 31
	v_lshl_add_u64 v[10:11], s[34:35], 0, v[66:67]
	v_lshl_add_u64 v[10:11], v[10:11], 2, s[36:37]
	v_mov_b32_e32 v9, v169
	s_waitcnt vmcnt(0)
	v_sub_f32_e32 v9, 1.0, v9
	v_mul_f32_e32 v8, v8, v9

.LBB0_554:
	s_or_b64 exec, exec, s[12:13]
	v_add_u32_e32 v8, 20, v4
	v_cmp_gt_i32_e32 vcc, s17, v8
	ds_write_b32 v7, v5 offset:2376
	s_and_b64 s[18:19], s[4:5], vcc
	v_mov_b32_e32 v5, 0
	s_and_saveexec_b64 s[12:13], s[18:19]
	s_cbranch_execz .LBB0_566
	s_waitcnt vmcnt(0)
	v_mov_b32_e32 v5, v210
	s_and_b64 vcc, exec, s[2:3]
	s_cbranch_vccnz .LBB0_558
	s_ashr_i32 s35, s34, 31
	v_lshl_add_u64 v[8:9], s[34:35], 0, v[66:67]
	v_lshl_add_u64 v[8:9], v[8:9], 2, s[14:15]
	v_mov_b32_e32 v8, v138
	s_cmp_lt_i32 s40, 3
	s_mov_b64 s[18:19], -1
	s_cbranch_scc0 .LBB0_559

.LBB0_559:
	s_cmp_eq_u32 s40, 3
	s_waitcnt vmcnt(0)
	v_mov_b32_e32 v9, v8
	s_cbranch_scc0 .LBB0_561
	s_ashr_i32 s35, s34, 31
	v_lshl_add_u64 v[10:11], s[34:35], 0, v[66:67]
	v_lshl_add_u64 v[10:11], v[10:11], 2, s[36:37]
	v_mov_b32_e32 v9, v170
	s_waitcnt vmcnt(0)
	v_mul_f32_e32 v9, v8, v9

.LBB0_562:
	s_cmp_eq_u32 s40, 2
	s_cbranch_scc0 .LBB0_564
	s_ashr_i32 s35, s34, 31
	v_lshl_add_u64 v[10:11], s[34:35], 0, v[66:67]
	v_lshl_add_u64 v[10:11], v[10:11], 2, s[36:37]
	v_mov_b32_e32 v9, v170
	s_waitcnt vmcnt(0)
	v_sub_f32_e32 v9, 1.0, v9
	v_mul_f32_e32 v8, v8, v9

.LBB0_566:
	s_or_b64 exec, exec, s[12:13]
	v_add_u32_e32 v8, 22, v4
	v_cmp_gt_i32_e32 vcc, s17, v8
	ds_write_b32 v7, v5 offset:2640
	s_and_b64 s[18:19], s[4:5], vcc
	v_mov_b32_e32 v5, 0
	s_and_saveexec_b64 s[12:13], s[18:19]
	s_cbranch_execz .LBB0_578
	s_waitcnt vmcnt(0)
	v_mov_b32_e32 v5, v211
	s_and_b64 vcc, exec, s[2:3]
	s_cbranch_vccnz .LBB0_570
	s_ashr_i32 s35, s34, 31
	v_lshl_add_u64 v[8:9], s[34:35], 0, v[66:67]
	v_lshl_add_u64 v[8:9], v[8:9], 2, s[14:15]
	v_mov_b32_e32 v8, v139
	s_cmp_lt_i32 s40, 3
	s_mov_b64 s[18:19], -1
	s_cbranch_scc0 .LBB0_571

.LBB0_571:
	s_cmp_eq_u32 s40, 3
	s_waitcnt vmcnt(0)
	v_mov_b32_e32 v9, v8
	s_cbranch_scc0 .LBB0_573
	s_ashr_i32 s35, s34, 31
	v_lshl_add_u64 v[10:11], s[34:35], 0, v[66:67]
	v_lshl_add_u64 v[10:11], v[10:11], 2, s[36:37]
	v_mov_b32_e32 v9, v171
	s_waitcnt vmcnt(0)
	v_mul_f32_e32 v9, v8, v9

.LBB0_574:
	s_cmp_eq_u32 s40, 2
	s_cbranch_scc0 .LBB0_576
	s_ashr_i32 s35, s34, 31
	v_lshl_add_u64 v[10:11], s[34:35], 0, v[66:67]
	v_lshl_add_u64 v[10:11], v[10:11], 2, s[36:37]
	v_mov_b32_e32 v9, v171
	s_waitcnt vmcnt(0)
	v_sub_f32_e32 v9, 1.0, v9
	v_mul_f32_e32 v8, v8, v9

.LBB0_578:
	s_or_b64 exec, exec, s[12:13]
	v_add_u32_e32 v8, 24, v4
	v_cmp_gt_i32_e32 vcc, s17, v8
	ds_write_b32 v7, v5 offset:2904
	s_and_b64 s[18:19], s[4:5], vcc
	v_mov_b32_e32 v5, 0
	s_and_saveexec_b64 s[12:13], s[18:19]
	s_cbranch_execz .LBB0_590
	s_waitcnt vmcnt(0)
	v_mov_b32_e32 v5, v212
	s_and_b64 vcc, exec, s[2:3]
	s_cbranch_vccnz .LBB0_582
	s_ashr_i32 s35, s34, 31
	v_lshl_add_u64 v[8:9], s[34:35], 0, v[66:67]
	v_lshl_add_u64 v[8:9], v[8:9], 2, s[14:15]
	v_mov_b32_e32 v8, v140
	s_cmp_lt_i32 s40, 3
	s_mov_b64 s[18:19], -1
	s_cbranch_scc0 .LBB0_583

.LBB0_583:
	s_cmp_eq_u32 s40, 3
	s_waitcnt vmcnt(0)
	v_mov_b32_e32 v9, v8
	s_cbranch_scc0 .LBB0_585
	s_ashr_i32 s35, s34, 31
	v_lshl_add_u64 v[10:11], s[34:35], 0, v[66:67]
	v_lshl_add_u64 v[10:11], v[10:11], 2, s[36:37]
	v_mov_b32_e32 v9, v172
	s_waitcnt vmcnt(0)
	v_mul_f32_e32 v9, v8, v9

.LBB0_586:
	s_cmp_eq_u32 s40, 2
	s_cbranch_scc0 .LBB0_588
	s_ashr_i32 s35, s34, 31
	v_lshl_add_u64 v[10:11], s[34:35], 0, v[66:67]
	v_lshl_add_u64 v[10:11], v[10:11], 2, s[36:37]
	v_mov_b32_e32 v9, v172
	s_waitcnt vmcnt(0)
	v_sub_f32_e32 v9, 1.0, v9
	v_mul_f32_e32 v8, v8, v9

.LBB0_590:
	s_or_b64 exec, exec, s[12:13]
	v_add_u32_e32 v8, 26, v4
	v_cmp_gt_i32_e32 vcc, s17, v8
	ds_write_b32 v7, v5 offset:3168
	s_and_b64 s[18:19], s[4:5], vcc
	v_mov_b32_e32 v5, 0
	s_and_saveexec_b64 s[12:13], s[18:19]
	s_cbranch_execz .LBB0_602
	s_waitcnt vmcnt(0)
	v_mov_b32_e32 v5, v213
	s_and_b64 vcc, exec, s[2:3]
	s_cbranch_vccnz .LBB0_594
	s_ashr_i32 s35, s34, 31
	v_lshl_add_u64 v[8:9], s[34:35], 0, v[66:67]
	v_lshl_add_u64 v[8:9], v[8:9], 2, s[14:15]
	v_mov_b32_e32 v8, v141
	s_cmp_lt_i32 s40, 3
	s_mov_b64 s[18:19], -1
	s_cbranch_scc0 .LBB0_595

.LBB0_595:
	s_cmp_eq_u32 s40, 3
	s_waitcnt vmcnt(0)
	v_mov_b32_e32 v9, v8
	s_cbranch_scc0 .LBB0_597
	s_ashr_i32 s35, s34, 31
	v_lshl_add_u64 v[10:11], s[34:35], 0, v[66:67]
	v_lshl_add_u64 v[10:11], v[10:11], 2, s[36:37]
	v_mov_b32_e32 v9, v173
	s_waitcnt vmcnt(0)
	v_mul_f32_e32 v9, v8, v9

.LBB0_598:
	s_cmp_eq_u32 s40, 2
	s_cbranch_scc0 .LBB0_600
	s_ashr_i32 s35, s34, 31
	v_lshl_add_u64 v[10:11], s[34:35], 0, v[66:67]
	v_lshl_add_u64 v[10:11], v[10:11], 2, s[36:37]
	v_mov_b32_e32 v9, v173
	s_waitcnt vmcnt(0)
	v_sub_f32_e32 v9, 1.0, v9
	v_mul_f32_e32 v8, v8, v9

.LBB0_602:
	s_or_b64 exec, exec, s[12:13]
	v_add_u32_e32 v8, 28, v4
	v_cmp_gt_i32_e32 vcc, s17, v8
	ds_write_b32 v7, v5 offset:3432
	s_and_b64 s[18:19], s[4:5], vcc
	v_mov_b32_e32 v5, 0
	s_and_saveexec_b64 s[12:13], s[18:19]
	s_cbranch_execz .LBB0_614
	s_waitcnt vmcnt(0)
	v_mov_b32_e32 v5, v214
	s_and_b64 vcc, exec, s[2:3]
	s_cbranch_vccnz .LBB0_606
	s_ashr_i32 s35, s34, 31
	v_lshl_add_u64 v[8:9], s[34:35], 0, v[66:67]
	v_lshl_add_u64 v[8:9], v[8:9], 2, s[14:15]
	v_mov_b32_e32 v8, v142
	s_cmp_lt_i32 s40, 3
	s_mov_b64 s[18:19], -1
	s_cbranch_scc0 .LBB0_607

.LBB0_607:
	s_cmp_eq_u32 s40, 3
	s_waitcnt vmcnt(0)
	v_mov_b32_e32 v9, v8
	s_cbranch_scc0 .LBB0_609
	s_ashr_i32 s35, s34, 31
	v_lshl_add_u64 v[10:11], s[34:35], 0, v[66:67]
	v_lshl_add_u64 v[10:11], v[10:11], 2, s[36:37]
	v_mov_b32_e32 v9, v174
	s_waitcnt vmcnt(0)
	v_mul_f32_e32 v9, v8, v9

.LBB0_610:
	s_cmp_eq_u32 s40, 2
	s_cbranch_scc0 .LBB0_612
	s_ashr_i32 s35, s34, 31
	v_lshl_add_u64 v[10:11], s[34:35], 0, v[66:67]
	v_lshl_add_u64 v[10:11], v[10:11], 2, s[36:37]
	v_mov_b32_e32 v9, v174
	s_waitcnt vmcnt(0)
	v_sub_f32_e32 v9, 1.0, v9
	v_mul_f32_e32 v8, v8, v9

.LBB0_614:
	s_or_b64 exec, exec, s[12:13]
	v_add_u32_e32 v8, 30, v4
	v_cmp_gt_i32_e32 vcc, s17, v8
	ds_write_b32 v7, v5 offset:3696
	s_and_b64 s[18:19], s[4:5], vcc
	v_mov_b32_e32 v5, 0
	s_and_saveexec_b64 s[12:13], s[18:19]
	s_cbranch_execz .LBB0_626
	s_waitcnt vmcnt(0)
	v_mov_b32_e32 v5, v215
	s_and_b64 vcc, exec, s[2:3]
	s_cbranch_vccnz .LBB0_618
	s_ashr_i32 s35, s34, 31
	v_lshl_add_u64 v[8:9], s[34:35], 0, v[66:67]
	v_lshl_add_u64 v[8:9], v[8:9], 2, s[14:15]
	v_mov_b32_e32 v8, v143
	s_cmp_lt_i32 s40, 3
	s_mov_b64 s[18:19], -1
	s_cbranch_scc0 .LBB0_619

.LBB0_619:
	s_cmp_eq_u32 s40, 3
	s_waitcnt vmcnt(0)
	v_mov_b32_e32 v9, v8
	s_cbranch_scc0 .LBB0_621
	s_ashr_i32 s35, s34, 31
	v_lshl_add_u64 v[10:11], s[34:35], 0, v[66:67]
	v_lshl_add_u64 v[10:11], v[10:11], 2, s[36:37]
	v_mov_b32_e32 v9, v175
	s_waitcnt vmcnt(0)
	v_mul_f32_e32 v9, v8, v9

.LBB0_622:
	s_cmp_eq_u32 s40, 2
	s_cbranch_scc0 .LBB0_624
	s_ashr_i32 s35, s34, 31
	v_lshl_add_u64 v[10:11], s[34:35], 0, v[66:67]
	v_lshl_add_u64 v[10:11], v[10:11], 2, s[36:37]
	v_mov_b32_e32 v9, v175
	s_waitcnt vmcnt(0)
	v_sub_f32_e32 v9, 1.0, v9
	v_mul_f32_e32 v8, v8, v9

.LBB0_626:
	s_or_b64 exec, exec, s[12:13]
	v_add_u32_e32 v8, 32, v4
	v_cmp_gt_i32_e32 vcc, s17, v8
	ds_write_b32 v7, v5 offset:3960
	s_and_b64 s[18:19], s[4:5], vcc
	v_mov_b32_e32 v5, 0
	s_and_saveexec_b64 s[12:13], s[18:19]
	s_cbranch_execz .LBB0_638
	s_waitcnt vmcnt(0)
	v_mov_b32_e32 v5, v216
	s_and_b64 vcc, exec, s[2:3]
	s_cbranch_vccnz .LBB0_630
	s_ashr_i32 s35, s34, 31
	v_lshl_add_u64 v[8:9], s[34:35], 0, v[66:67]
	v_lshl_add_u64 v[8:9], v[8:9], 2, s[14:15]
	v_mov_b32_e32 v8, v144
	s_cmp_lt_i32 s40, 3
	s_mov_b64 s[18:19], -1
	s_cbranch_scc0 .LBB0_631

.LBB0_631:
	s_cmp_eq_u32 s40, 3
	s_waitcnt vmcnt(0)
	v_mov_b32_e32 v9, v8
	s_cbranch_scc0 .LBB0_633
	s_ashr_i32 s35, s34, 31
	v_lshl_add_u64 v[10:11], s[34:35], 0, v[66:67]
	v_lshl_add_u64 v[10:11], v[10:11], 2, s[36:37]
	v_mov_b32_e32 v9, v176
	s_waitcnt vmcnt(0)
	v_mul_f32_e32 v9, v8, v9

.LBB0_634:
	s_cmp_eq_u32 s40, 2
	s_cbranch_scc0 .LBB0_636
	s_ashr_i32 s35, s34, 31
	v_lshl_add_u64 v[10:11], s[34:35], 0, v[66:67]
	v_lshl_add_u64 v[10:11], v[10:11], 2, s[36:37]
	v_mov_b32_e32 v9, v176
	s_waitcnt vmcnt(0)
	v_sub_f32_e32 v9, 1.0, v9
	v_mul_f32_e32 v8, v8, v9

.LBB0_638:
	s_or_b64 exec, exec, s[12:13]
	v_add_u32_e32 v8, 34, v4
	v_cmp_gt_i32_e32 vcc, s17, v8
	ds_write_b32 v7, v5 offset:4224
	s_and_b64 s[18:19], s[4:5], vcc
	v_mov_b32_e32 v5, 0
	s_and_saveexec_b64 s[12:13], s[18:19]
	s_cbranch_execz .LBB0_650
	s_waitcnt vmcnt(0)
	v_mov_b32_e32 v5, v217
	s_and_b64 vcc, exec, s[2:3]
	s_cbranch_vccnz .LBB0_642
	s_ashr_i32 s35, s34, 31
	v_lshl_add_u64 v[8:9], s[34:35], 0, v[66:67]
	v_lshl_add_u64 v[8:9], v[8:9], 2, s[14:15]
	v_mov_b32_e32 v8, v145
	s_cmp_lt_i32 s40, 3
	s_mov_b64 s[18:19], -1
	s_cbranch_scc0 .LBB0_643

.LBB0_643:
	s_cmp_eq_u32 s40, 3
	s_waitcnt vmcnt(0)
	v_mov_b32_e32 v9, v8
	s_cbranch_scc0 .LBB0_645
	s_ashr_i32 s35, s34, 31
	v_lshl_add_u64 v[10:11], s[34:35], 0, v[66:67]
	v_lshl_add_u64 v[10:11], v[10:11], 2, s[36:37]
	v_mov_b32_e32 v9, v177
	s_waitcnt vmcnt(0)
	v_mul_f32_e32 v9, v8, v9

.LBB0_646:
	s_cmp_eq_u32 s40, 2
	s_cbranch_scc0 .LBB0_648
	s_ashr_i32 s35, s34, 31
	v_lshl_add_u64 v[10:11], s[34:35], 0, v[66:67]
	v_lshl_add_u64 v[10:11], v[10:11], 2, s[36:37]
	v_mov_b32_e32 v9, v177
	s_waitcnt vmcnt(0)
	v_sub_f32_e32 v9, 1.0, v9
	v_mul_f32_e32 v8, v8, v9

.LBB0_650:
	s_or_b64 exec, exec, s[12:13]
	v_add_u32_e32 v8, 36, v4
	v_cmp_gt_i32_e32 vcc, s17, v8
	ds_write_b32 v7, v5 offset:4488
	s_and_b64 s[18:19], s[4:5], vcc
	v_mov_b32_e32 v5, 0
	s_and_saveexec_b64 s[12:13], s[18:19]
	s_cbranch_execz .LBB0_662
	s_waitcnt vmcnt(0)
	v_mov_b32_e32 v5, v218
	s_and_b64 vcc, exec, s[2:3]
	s_cbranch_vccnz .LBB0_654
	s_ashr_i32 s35, s34, 31
	v_lshl_add_u64 v[8:9], s[34:35], 0, v[66:67]
	v_lshl_add_u64 v[8:9], v[8:9], 2, s[14:15]
	v_mov_b32_e32 v8, v146
	s_cmp_lt_i32 s40, 3
	s_mov_b64 s[18:19], -1
	s_cbranch_scc0 .LBB0_655

.LBB0_655:
	s_cmp_eq_u32 s40, 3
	s_waitcnt vmcnt(0)
	v_mov_b32_e32 v9, v8
	s_cbranch_scc0 .LBB0_657
	s_ashr_i32 s35, s34, 31
	v_lshl_add_u64 v[10:11], s[34:35], 0, v[66:67]
	v_lshl_add_u64 v[10:11], v[10:11], 2, s[36:37]
	v_mov_b32_e32 v9, v178
	s_waitcnt vmcnt(0)
	v_mul_f32_e32 v9, v8, v9

.LBB0_658:
	s_cmp_eq_u32 s40, 2
	s_cbranch_scc0 .LBB0_660
	s_ashr_i32 s35, s34, 31
	v_lshl_add_u64 v[10:11], s[34:35], 0, v[66:67]
	v_lshl_add_u64 v[10:11], v[10:11], 2, s[36:37]
	v_mov_b32_e32 v9, v178
	s_waitcnt vmcnt(0)
	v_sub_f32_e32 v9, 1.0, v9
	v_mul_f32_e32 v8, v8, v9

.LBB0_662:
	s_or_b64 exec, exec, s[12:13]
	v_add_u32_e32 v8, 38, v4
	v_cmp_gt_i32_e32 vcc, s17, v8
	ds_write_b32 v7, v5 offset:4752
	s_and_b64 s[18:19], s[4:5], vcc
	v_mov_b32_e32 v5, 0
	s_and_saveexec_b64 s[12:13], s[18:19]
	s_cbranch_execz .LBB0_674
	s_waitcnt vmcnt(0)
	v_mov_b32_e32 v5, v219
	s_and_b64 vcc, exec, s[2:3]
	s_cbranch_vccnz .LBB0_666
	s_ashr_i32 s35, s34, 31
	v_lshl_add_u64 v[8:9], s[34:35], 0, v[66:67]
	v_lshl_add_u64 v[8:9], v[8:9], 2, s[14:15]
	v_mov_b32_e32 v8, v147
	s_cmp_lt_i32 s40, 3
	s_mov_b64 s[18:19], -1
	s_cbranch_scc0 .LBB0_667

.LBB0_667:
	s_cmp_eq_u32 s40, 3
	s_waitcnt vmcnt(0)
	v_mov_b32_e32 v9, v8
	s_cbranch_scc0 .LBB0_669
	s_ashr_i32 s35, s34, 31
	v_lshl_add_u64 v[10:11], s[34:35], 0, v[66:67]
	v_lshl_add_u64 v[10:11], v[10:11], 2, s[36:37]
	v_mov_b32_e32 v9, v179
	s_waitcnt vmcnt(0)
	v_mul_f32_e32 v9, v8, v9

.LBB0_670:
	s_cmp_eq_u32 s40, 2
	s_cbranch_scc0 .LBB0_672
	s_ashr_i32 s35, s34, 31
	v_lshl_add_u64 v[10:11], s[34:35], 0, v[66:67]
	v_lshl_add_u64 v[10:11], v[10:11], 2, s[36:37]
	v_mov_b32_e32 v9, v179
	s_waitcnt vmcnt(0)
	v_sub_f32_e32 v9, 1.0, v9
	v_mul_f32_e32 v8, v8, v9

.LBB0_674:
	s_or_b64 exec, exec, s[12:13]
	v_add_u32_e32 v8, 40, v4
	v_cmp_gt_i32_e32 vcc, s17, v8
	ds_write_b32 v7, v5 offset:5016
	s_and_b64 s[18:19], s[4:5], vcc
	v_mov_b32_e32 v5, 0
	s_and_saveexec_b64 s[12:13], s[18:19]
	s_cbranch_execz .LBB0_686
	s_waitcnt vmcnt(0)
	v_mov_b32_e32 v5, v220
	s_and_b64 vcc, exec, s[2:3]
	s_cbranch_vccnz .LBB0_678
	s_ashr_i32 s35, s34, 31
	v_lshl_add_u64 v[8:9], s[34:35], 0, v[66:67]
	v_lshl_add_u64 v[8:9], v[8:9], 2, s[14:15]
	v_mov_b32_e32 v8, v148
	s_cmp_lt_i32 s40, 3
	s_mov_b64 s[18:19], -1
	s_cbranch_scc0 .LBB0_679

.LBB0_679:
	s_cmp_eq_u32 s40, 3
	s_waitcnt vmcnt(0)
	v_mov_b32_e32 v9, v8
	s_cbranch_scc0 .LBB0_681
	s_ashr_i32 s35, s34, 31
	v_lshl_add_u64 v[10:11], s[34:35], 0, v[66:67]
	v_lshl_add_u64 v[10:11], v[10:11], 2, s[36:37]
	v_mov_b32_e32 v9, v180
	s_waitcnt vmcnt(0)
	v_mul_f32_e32 v9, v8, v9

.LBB0_682:
	s_cmp_eq_u32 s40, 2
	s_cbranch_scc0 .LBB0_684
	s_ashr_i32 s35, s34, 31
	v_lshl_add_u64 v[10:11], s[34:35], 0, v[66:67]
	v_lshl_add_u64 v[10:11], v[10:11], 2, s[36:37]
	v_mov_b32_e32 v9, v180
	s_waitcnt vmcnt(0)
	v_sub_f32_e32 v9, 1.0, v9
	v_mul_f32_e32 v8, v8, v9

.LBB0_686:
	s_or_b64 exec, exec, s[12:13]
	v_add_u32_e32 v8, 42, v4
	v_cmp_gt_i32_e32 vcc, s17, v8
	ds_write_b32 v7, v5 offset:5280
	s_and_b64 s[18:19], s[4:5], vcc
	v_mov_b32_e32 v5, 0
	s_and_saveexec_b64 s[12:13], s[18:19]
	s_cbranch_execz .LBB0_698
	s_waitcnt vmcnt(0)
	v_mov_b32_e32 v5, v221
	s_and_b64 vcc, exec, s[2:3]
	s_cbranch_vccnz .LBB0_690
	s_ashr_i32 s35, s34, 31
	v_lshl_add_u64 v[8:9], s[34:35], 0, v[66:67]
	v_lshl_add_u64 v[8:9], v[8:9], 2, s[14:15]
	v_mov_b32_e32 v8, v149
	s_cmp_lt_i32 s40, 3
	s_mov_b64 s[18:19], -1
	s_cbranch_scc0 .LBB0_691

.LBB0_691:
	s_cmp_eq_u32 s40, 3
	s_waitcnt vmcnt(0)
	v_mov_b32_e32 v9, v8
	s_cbranch_scc0 .LBB0_693
	s_ashr_i32 s35, s34, 31
	v_lshl_add_u64 v[10:11], s[34:35], 0, v[66:67]
	v_lshl_add_u64 v[10:11], v[10:11], 2, s[36:37]
	v_mov_b32_e32 v9, v181
	s_waitcnt vmcnt(0)
	v_mul_f32_e32 v9, v8, v9

.LBB0_694:
	s_cmp_eq_u32 s40, 2
	s_cbranch_scc0 .LBB0_696
	s_ashr_i32 s35, s34, 31
	v_lshl_add_u64 v[10:11], s[34:35], 0, v[66:67]
	v_lshl_add_u64 v[10:11], v[10:11], 2, s[36:37]
	v_mov_b32_e32 v9, v181
	s_waitcnt vmcnt(0)
	v_sub_f32_e32 v9, 1.0, v9
	v_mul_f32_e32 v8, v8, v9

.LBB0_698:
	s_or_b64 exec, exec, s[12:13]
	v_add_u32_e32 v8, 44, v4
	v_cmp_gt_i32_e32 vcc, s17, v8
	ds_write_b32 v7, v5 offset:5544
	s_and_b64 s[18:19], s[4:5], vcc
	v_mov_b32_e32 v5, 0
	s_and_saveexec_b64 s[12:13], s[18:19]
	s_cbranch_execz .LBB0_710
	s_waitcnt vmcnt(0)
	v_mov_b32_e32 v5, v222
	s_and_b64 vcc, exec, s[2:3]
	s_cbranch_vccnz .LBB0_702
	s_ashr_i32 s35, s34, 31
	v_lshl_add_u64 v[8:9], s[34:35], 0, v[66:67]
	v_lshl_add_u64 v[8:9], v[8:9], 2, s[14:15]
	v_mov_b32_e32 v8, v150
	s_cmp_lt_i32 s40, 3
	s_mov_b64 s[18:19], -1
	s_cbranch_scc0 .LBB0_703

.LBB0_703:
	s_cmp_eq_u32 s40, 3
	s_waitcnt vmcnt(0)
	v_mov_b32_e32 v9, v8
	s_cbranch_scc0 .LBB0_705
	s_ashr_i32 s35, s34, 31
	v_lshl_add_u64 v[10:11], s[34:35], 0, v[66:67]
	v_lshl_add_u64 v[10:11], v[10:11], 2, s[36:37]
	v_mov_b32_e32 v9, v182
	s_waitcnt vmcnt(0)
	v_mul_f32_e32 v9, v8, v9

.LBB0_706:
	s_cmp_eq_u32 s40, 2
	s_cbranch_scc0 .LBB0_708
	s_ashr_i32 s35, s34, 31
	v_lshl_add_u64 v[10:11], s[34:35], 0, v[66:67]
	v_lshl_add_u64 v[10:11], v[10:11], 2, s[36:37]
	v_mov_b32_e32 v9, v182
	s_waitcnt vmcnt(0)
	v_sub_f32_e32 v9, 1.0, v9
	v_mul_f32_e32 v8, v8, v9

.LBB0_710:
	s_or_b64 exec, exec, s[12:13]
	v_add_u32_e32 v8, 46, v4
	v_cmp_gt_i32_e32 vcc, s17, v8
	ds_write_b32 v7, v5 offset:5808
	s_and_b64 s[18:19], s[4:5], vcc
	v_mov_b32_e32 v5, 0
	s_and_saveexec_b64 s[12:13], s[18:19]
	s_cbranch_execz .LBB0_722
	s_waitcnt vmcnt(0)
	v_mov_b32_e32 v5, v223
	s_and_b64 vcc, exec, s[2:3]
	s_cbranch_vccnz .LBB0_714
	s_ashr_i32 s35, s34, 31
	v_lshl_add_u64 v[8:9], s[34:35], 0, v[66:67]
	v_lshl_add_u64 v[8:9], v[8:9], 2, s[14:15]
	v_mov_b32_e32 v8, v151
	s_cmp_lt_i32 s40, 3
	s_mov_b64 s[18:19], -1
	s_cbranch_scc0 .LBB0_715

.LBB0_715:
	s_cmp_eq_u32 s40, 3
	s_waitcnt vmcnt(0)
	v_mov_b32_e32 v9, v8
	s_cbranch_scc0 .LBB0_717
	s_ashr_i32 s35, s34, 31
	v_lshl_add_u64 v[10:11], s[34:35], 0, v[66:67]
	v_lshl_add_u64 v[10:11], v[10:11], 2, s[36:37]
	v_mov_b32_e32 v9, v183
	s_waitcnt vmcnt(0)
	v_mul_f32_e32 v9, v8, v9

.LBB0_718:
	s_cmp_eq_u32 s40, 2
	s_cbranch_scc0 .LBB0_720
	s_ashr_i32 s35, s34, 31
	v_lshl_add_u64 v[10:11], s[34:35], 0, v[66:67]
	v_lshl_add_u64 v[10:11], v[10:11], 2, s[36:37]
	v_mov_b32_e32 v9, v183
	s_waitcnt vmcnt(0)
	v_sub_f32_e32 v9, 1.0, v9
	v_mul_f32_e32 v8, v8, v9

.LBB0_722:
	s_or_b64 exec, exec, s[12:13]
	v_add_u32_e32 v8, 48, v4
	v_cmp_gt_i32_e32 vcc, s17, v8
	ds_write_b32 v7, v5 offset:6072
	s_and_b64 s[18:19], s[4:5], vcc
	v_mov_b32_e32 v5, 0
	s_and_saveexec_b64 s[12:13], s[18:19]
	s_cbranch_execz .LBB0_734
	s_waitcnt vmcnt(0)
	v_mov_b32_e32 v5, v224
	s_and_b64 vcc, exec, s[2:3]
	s_cbranch_vccnz .LBB0_726
	s_ashr_i32 s35, s34, 31
	v_lshl_add_u64 v[8:9], s[34:35], 0, v[66:67]
	v_lshl_add_u64 v[8:9], v[8:9], 2, s[14:15]
	v_mov_b32_e32 v8, v152
	s_cmp_lt_i32 s40, 3
	s_mov_b64 s[18:19], -1
	s_cbranch_scc0 .LBB0_727

.LBB0_727:
	s_cmp_eq_u32 s40, 3
	s_waitcnt vmcnt(0)
	v_mov_b32_e32 v9, v8
	s_cbranch_scc0 .LBB0_729
	s_ashr_i32 s35, s34, 31
	v_lshl_add_u64 v[10:11], s[34:35], 0, v[66:67]
	v_lshl_add_u64 v[10:11], v[10:11], 2, s[36:37]
	v_mov_b32_e32 v9, v184
	s_waitcnt vmcnt(0)
	v_mul_f32_e32 v9, v8, v9

.LBB0_730:
	s_cmp_eq_u32 s40, 2
	s_cbranch_scc0 .LBB0_732
	s_ashr_i32 s35, s34, 31
	v_lshl_add_u64 v[10:11], s[34:35], 0, v[66:67]
	v_lshl_add_u64 v[10:11], v[10:11], 2, s[36:37]
	v_mov_b32_e32 v9, v184
	s_waitcnt vmcnt(0)
	v_sub_f32_e32 v9, 1.0, v9
	v_mul_f32_e32 v8, v8, v9

.LBB0_734:
	s_or_b64 exec, exec, s[12:13]
	v_add_u32_e32 v8, 50, v4
	v_cmp_gt_i32_e32 vcc, s17, v8
	ds_write_b32 v7, v5 offset:6336
	s_and_b64 s[18:19], s[4:5], vcc
	v_mov_b32_e32 v5, 0
	s_and_saveexec_b64 s[12:13], s[18:19]
	s_cbranch_execz .LBB0_746
	s_waitcnt vmcnt(0)
	v_mov_b32_e32 v5, v225
	s_and_b64 vcc, exec, s[2:3]
	s_cbranch_vccnz .LBB0_738
	s_ashr_i32 s35, s34, 31
	v_lshl_add_u64 v[8:9], s[34:35], 0, v[66:67]
	v_lshl_add_u64 v[8:9], v[8:9], 2, s[14:15]
	v_mov_b32_e32 v8, v153
	s_cmp_lt_i32 s40, 3
	s_mov_b64 s[18:19], -1
	s_cbranch_scc0 .LBB0_739

.LBB0_739:
	s_cmp_eq_u32 s40, 3
	s_waitcnt vmcnt(0)
	v_mov_b32_e32 v9, v8
	s_cbranch_scc0 .LBB0_741
	s_ashr_i32 s35, s34, 31
	v_lshl_add_u64 v[10:11], s[34:35], 0, v[66:67]
	v_lshl_add_u64 v[10:11], v[10:11], 2, s[36:37]
	v_mov_b32_e32 v9, v185
	s_waitcnt vmcnt(0)
	v_mul_f32_e32 v9, v8, v9

.LBB0_742:
	s_cmp_eq_u32 s40, 2
	s_cbranch_scc0 .LBB0_744
	s_ashr_i32 s35, s34, 31
	v_lshl_add_u64 v[10:11], s[34:35], 0, v[66:67]
	v_lshl_add_u64 v[10:11], v[10:11], 2, s[36:37]
	v_mov_b32_e32 v9, v185
	s_waitcnt vmcnt(0)
	v_sub_f32_e32 v9, 1.0, v9
	v_mul_f32_e32 v8, v8, v9

.LBB0_746:
	s_or_b64 exec, exec, s[12:13]
	v_add_u32_e32 v8, 52, v4
	v_cmp_gt_i32_e32 vcc, s17, v8
	ds_write_b32 v7, v5 offset:6600
	s_and_b64 s[18:19], s[4:5], vcc
	v_mov_b32_e32 v5, 0
	s_and_saveexec_b64 s[12:13], s[18:19]
	s_cbranch_execz .LBB0_758
	s_waitcnt vmcnt(0)
	v_mov_b32_e32 v5, v226
	s_and_b64 vcc, exec, s[2:3]
	s_cbranch_vccnz .LBB0_750
	s_ashr_i32 s35, s34, 31
	v_lshl_add_u64 v[8:9], s[34:35], 0, v[66:67]
	v_lshl_add_u64 v[8:9], v[8:9], 2, s[14:15]
	v_mov_b32_e32 v8, v154
	s_cmp_lt_i32 s40, 3
	s_mov_b64 s[18:19], -1
	s_cbranch_scc0 .LBB0_751

.LBB0_751:
	s_cmp_eq_u32 s40, 3
	s_waitcnt vmcnt(0)
	v_mov_b32_e32 v9, v8
	s_cbranch_scc0 .LBB0_753
	s_ashr_i32 s35, s34, 31
	v_lshl_add_u64 v[10:11], s[34:35], 0, v[66:67]
	v_lshl_add_u64 v[10:11], v[10:11], 2, s[36:37]
	v_mov_b32_e32 v9, v186
	s_waitcnt vmcnt(0)
	v_mul_f32_e32 v9, v8, v9

.LBB0_754:
	s_cmp_eq_u32 s40, 2
	s_cbranch_scc0 .LBB0_756
	s_ashr_i32 s35, s34, 31
	v_lshl_add_u64 v[10:11], s[34:35], 0, v[66:67]
	v_lshl_add_u64 v[10:11], v[10:11], 2, s[36:37]
	v_mov_b32_e32 v9, v186
	s_waitcnt vmcnt(0)
	v_sub_f32_e32 v9, 1.0, v9
	v_mul_f32_e32 v8, v8, v9

.LBB0_758:
	s_or_b64 exec, exec, s[12:13]
	v_add_u32_e32 v8, 54, v4
	v_cmp_gt_i32_e32 vcc, s17, v8
	ds_write_b32 v7, v5 offset:6864
	s_and_b64 s[18:19], s[4:5], vcc
	v_mov_b32_e32 v5, 0
	s_and_saveexec_b64 s[12:13], s[18:19]
	s_cbranch_execz .LBB0_770
	s_waitcnt vmcnt(0)
	v_mov_b32_e32 v5, v227
	s_and_b64 vcc, exec, s[2:3]
	s_cbranch_vccnz .LBB0_762
	s_ashr_i32 s35, s34, 31
	v_lshl_add_u64 v[8:9], s[34:35], 0, v[66:67]
	v_lshl_add_u64 v[8:9], v[8:9], 2, s[14:15]
	v_mov_b32_e32 v8, v155
	s_cmp_lt_i32 s40, 3
	s_mov_b64 s[18:19], -1
	s_cbranch_scc0 .LBB0_763

.LBB0_763:
	s_cmp_eq_u32 s40, 3
	s_waitcnt vmcnt(0)
	v_mov_b32_e32 v9, v8
	s_cbranch_scc0 .LBB0_765
	s_ashr_i32 s35, s34, 31
	v_lshl_add_u64 v[10:11], s[34:35], 0, v[66:67]
	v_lshl_add_u64 v[10:11], v[10:11], 2, s[36:37]
	v_mov_b32_e32 v9, v187
	s_waitcnt vmcnt(0)
	v_mul_f32_e32 v9, v8, v9

.LBB0_766:
	s_cmp_eq_u32 s40, 2
	s_cbranch_scc0 .LBB0_768
	s_ashr_i32 s35, s34, 31
	v_lshl_add_u64 v[10:11], s[34:35], 0, v[66:67]
	v_lshl_add_u64 v[10:11], v[10:11], 2, s[36:37]
	v_mov_b32_e32 v9, v187
	s_waitcnt vmcnt(0)
	v_sub_f32_e32 v9, 1.0, v9
	v_mul_f32_e32 v8, v8, v9

.LBB0_770:
	s_or_b64 exec, exec, s[12:13]
	v_add_u32_e32 v8, 56, v4
	v_cmp_gt_i32_e32 vcc, s17, v8
	ds_write_b32 v7, v5 offset:7128
	s_and_b64 s[18:19], s[4:5], vcc
	v_mov_b32_e32 v5, 0
	s_and_saveexec_b64 s[12:13], s[18:19]
	s_cbranch_execz .LBB0_782
	s_waitcnt vmcnt(0)
	v_mov_b32_e32 v5, v228
	s_and_b64 vcc, exec, s[2:3]
	s_cbranch_vccnz .LBB0_774
	s_ashr_i32 s35, s34, 31
	v_lshl_add_u64 v[8:9], s[34:35], 0, v[66:67]
	v_lshl_add_u64 v[8:9], v[8:9], 2, s[14:15]
	v_mov_b32_e32 v8, v156
	s_cmp_lt_i32 s40, 3
	s_mov_b64 s[18:19], -1
	s_cbranch_scc0 .LBB0_775

.LBB0_775:
	s_cmp_eq_u32 s40, 3
	s_waitcnt vmcnt(0)
	v_mov_b32_e32 v9, v8
	s_cbranch_scc0 .LBB0_777
	s_ashr_i32 s35, s34, 31
	v_lshl_add_u64 v[10:11], s[34:35], 0, v[66:67]
	v_lshl_add_u64 v[10:11], v[10:11], 2, s[36:37]
	v_mov_b32_e32 v9, v188
	s_waitcnt vmcnt(0)
	v_mul_f32_e32 v9, v8, v9

.LBB0_778:
	s_cmp_eq_u32 s40, 2
	s_cbranch_scc0 .LBB0_780
	s_ashr_i32 s35, s34, 31
	v_lshl_add_u64 v[10:11], s[34:35], 0, v[66:67]
	v_lshl_add_u64 v[10:11], v[10:11], 2, s[36:37]
	v_mov_b32_e32 v9, v188
	s_waitcnt vmcnt(0)
	v_sub_f32_e32 v9, 1.0, v9
	v_mul_f32_e32 v8, v8, v9

.LBB0_782:
	s_or_b64 exec, exec, s[12:13]
	v_add_u32_e32 v8, 58, v4
	v_cmp_gt_i32_e32 vcc, s17, v8
	ds_write_b32 v7, v5 offset:7392
	s_and_b64 s[18:19], s[4:5], vcc
	v_mov_b32_e32 v5, 0
	s_and_saveexec_b64 s[12:13], s[18:19]
	s_cbranch_execz .LBB0_794
	s_waitcnt vmcnt(0)
	v_mov_b32_e32 v5, v229
	s_and_b64 vcc, exec, s[2:3]
	s_cbranch_vccnz .LBB0_786
	s_ashr_i32 s35, s34, 31
	v_lshl_add_u64 v[8:9], s[34:35], 0, v[66:67]
	v_lshl_add_u64 v[8:9], v[8:9], 2, s[14:15]
	v_mov_b32_e32 v8, v157
	s_cmp_lt_i32 s40, 3
	s_mov_b64 s[18:19], -1
	s_cbranch_scc0 .LBB0_787

.LBB0_787:
	s_cmp_eq_u32 s40, 3
	s_waitcnt vmcnt(0)
	v_mov_b32_e32 v9, v8
	s_cbranch_scc0 .LBB0_789
	s_ashr_i32 s35, s34, 31
	v_lshl_add_u64 v[10:11], s[34:35], 0, v[66:67]
	v_lshl_add_u64 v[10:11], v[10:11], 2, s[36:37]
	v_mov_b32_e32 v9, v189
	s_waitcnt vmcnt(0)
	v_mul_f32_e32 v9, v8, v9

.LBB0_790:
	s_cmp_eq_u32 s40, 2
	s_cbranch_scc0 .LBB0_792
	s_ashr_i32 s35, s34, 31
	v_lshl_add_u64 v[10:11], s[34:35], 0, v[66:67]
	v_lshl_add_u64 v[10:11], v[10:11], 2, s[36:37]
	v_mov_b32_e32 v9, v189
	s_waitcnt vmcnt(0)
	v_sub_f32_e32 v9, 1.0, v9
	v_mul_f32_e32 v8, v8, v9

.LBB0_794:
	s_or_b64 exec, exec, s[12:13]
	v_add_u32_e32 v8, 60, v4
	v_cmp_gt_i32_e32 vcc, s17, v8
	ds_write_b32 v7, v5 offset:7656
	s_and_b64 s[18:19], s[4:5], vcc
	v_mov_b32_e32 v5, 0
	s_and_saveexec_b64 s[12:13], s[18:19]
	s_cbranch_execz .LBB0_806
	s_waitcnt vmcnt(0)
	v_mov_b32_e32 v5, v230
	s_and_b64 vcc, exec, s[2:3]
	s_cbranch_vccnz .LBB0_798
	s_ashr_i32 s35, s34, 31
	v_lshl_add_u64 v[8:9], s[34:35], 0, v[66:67]
	v_lshl_add_u64 v[8:9], v[8:9], 2, s[14:15]
	v_mov_b32_e32 v8, v158
	s_cmp_lt_i32 s40, 3
	s_mov_b64 s[18:19], -1
	s_cbranch_scc0 .LBB0_799

.LBB0_799:
	s_cmp_eq_u32 s40, 3
	s_waitcnt vmcnt(0)
	v_mov_b32_e32 v9, v8
	s_cbranch_scc0 .LBB0_801
	s_ashr_i32 s35, s34, 31
	v_lshl_add_u64 v[10:11], s[34:35], 0, v[66:67]
	v_lshl_add_u64 v[10:11], v[10:11], 2, s[36:37]
	v_mov_b32_e32 v9, v190
	s_waitcnt vmcnt(0)
	v_mul_f32_e32 v9, v8, v9

.LBB0_802:
	s_cmp_eq_u32 s40, 2
	s_cbranch_scc0 .LBB0_804
	s_ashr_i32 s35, s34, 31
	v_lshl_add_u64 v[10:11], s[34:35], 0, v[66:67]
	v_lshl_add_u64 v[10:11], v[10:11], 2, s[36:37]
	v_mov_b32_e32 v9, v190
	s_waitcnt vmcnt(0)
	v_sub_f32_e32 v9, 1.0, v9
	v_mul_f32_e32 v8, v8, v9

.LBB0_806:
	s_or_b64 exec, exec, s[12:13]
	ds_write_b32 v7, v5 offset:7920
	v_add_u32_e32 v5, 62, v4
	v_cmp_gt_i32_e32 vcc, s17, v5
	s_and_b64 s[12:13], s[4:5], vcc
	v_mov_b32_e32 v4, 0
	s_and_saveexec_b64 s[4:5], s[12:13]
	s_cbranch_execz .LBB0_818
	s_waitcnt vmcnt(0)
	v_mov_b32_e32 v2, v231
	s_and_b64 vcc, exec, s[2:3]
	s_cbranch_vccnz .LBB0_810
	s_ashr_i32 s35, s34, 31
	v_lshl_add_u64 v[4:5], s[34:35], 0, v[66:67]
	v_lshl_add_u64 v[4:5], v[4:5], 2, s[14:15]
	v_mov_b32_e32 v3, v159
	s_cmp_lt_i32 s40, 3
	s_mov_b64 s[2:3], -1
	s_cbranch_scc0 .LBB0_811

.LBB0_811:
	s_cmp_eq_u32 s40, 3
	s_waitcnt vmcnt(0)
	v_mov_b32_e32 v4, v3
	s_cbranch_scc0 .LBB0_813
	s_ashr_i32 s35, s34, 31
	v_lshl_add_u64 v[4:5], s[34:35], 0, v[66:67]
	v_lshl_add_u64 v[4:5], v[4:5], 2, s[36:37]
	v_mov_b32_e32 v4, v191
	s_waitcnt vmcnt(0)
	v_mul_f32_e32 v4, v3, v4

.LBB0_814:
	s_cmp_eq_u32 s40, 2
	s_cbranch_scc0 .LBB0_816
	s_ashr_i32 s35, s34, 31
	v_lshl_add_u64 v[4:5], s[34:35], 0, v[66:67]
	v_lshl_add_u64 v[4:5], v[4:5], 2, s[36:37]
	v_mov_b32_e32 v4, v191
	s_waitcnt vmcnt(0)
	v_sub_f32_e32 v4, 1.0, v4
	v_mul_f32_e32 v3, v3, v4

.LBB0_1235:
	s_ashr_i32 s5, s6, 2
	s_lshl_b32 s6, s6, 8
	s_and_b32 s6, s6, 0x300
	s_cmp_gt_i32 s5, 0
	s_cselect_b64 s[58:59], -1, 0
	v_add_u32_e32 v144, s6, v150
	s_and_b64 s[6:7], s[58:59], exec
	s_cselect_b32 s7, s78, 0
	s_cselect_b32 s6, s79, 0
	s_add_u32 s56, s14, s7
	s_addc_u32 s57, s15, s6
	v_ashrrev_i32_e32 v145, 31, v144
	s_cmp_lt_i32 s5, 2
	s_cselect_b64 s[6:7], -1, 0
	s_cmp_gt_i32 s5, 1
	v_lshl_add_u64 v[140:141], v[144:145], 2, s[56:57]
	global_load_dwordx4 v[232:235], v[140:141], off
	global_load_dwordx4 v[236:239], v[140:141], off offset:16
	global_load_dwordx4 v[240:243], v[140:141], off offset:512
	global_load_dwordx4 v[244:247], v[140:141], off offset:528
	s_cbranch_scc1 .LBB0_1237
	s_waitcnt vmcnt(2)
	v_pk_add_f32 v[126:127], v[126:127], v[234:235]
	v_pk_add_f32 v[124:125], v[124:125], v[232:233]
	v_pk_add_f32 v[122:123], v[122:123], v[238:239]
	v_pk_add_f32 v[120:121], v[120:121], v[236:237]

.LBB0_1239:
	s_and_b64 s[58:59], s[58:59], exec
	s_cselect_b32 s49, s76, 0
	v_lshl_add_u32 v142, s4, 8, v148
	s_cselect_b32 s4, s77, 0
	s_add_u32 s49, s71, s49
	s_addc_u32 s51, s72, s4
	s_cmp_gt_i32 s5, 1
	s_cselect_b32 s4, 0x4000000, 0
	s_add_u32 s4, s49, s4
	s_addc_u32 s5, s51, 0
	v_ashrrev_i32_e32 v143, 31, v142
	v_lshl_add_u64 v[144:145], v[144:145], 1, s[4:5]
	v_lshlrev_b64 v[146:147], 11, v[142:143]
	v_cvt_pk_bf16_f32 v124, v124, v125
	v_cvt_pk_bf16_f32 v125, v126, v127
	v_cvt_pk_bf16_f32 v126, v120, v121
	v_cndmask_b32_e64 v120, 0, 1, s[6:7]
	v_lshl_add_u64 v[146:147], v[144:145], 0, v[146:147]
	v_cvt_pk_bf16_f32 v127, v122, v123
	v_cmp_ne_u32_e64 s[4:5], 1, v120
	s_andn2_b64 vcc, exec, s[6:7]
	global_store_dwordx4 v[146:147], v[124:127], off
	s_cbranch_vccnz .LBB0_1241
	s_waitcnt vmcnt(1)
	v_pk_add_f32 v[118:119], v[118:119], v[242:243]
	v_pk_add_f32 v[116:117], v[116:117], v[240:241]
	v_pk_add_f32 v[114:115], v[114:115], v[246:247]
	v_pk_add_f32 v[112:113], v[112:113], v[244:245]

.LBB0_1243:
	v_cvt_pk_bf16_f32 v116, v116, v117
	v_cvt_pk_bf16_f32 v117, v118, v119
	v_cvt_pk_bf16_f32 v118, v112, v113
	v_cvt_pk_bf16_f32 v119, v114, v115
	s_and_b64 vcc, exec, s[4:5]
	global_store_dwordx4 v[146:147], v[116:119], off offset:256
	s_cbranch_vccnz .LBB0_1245
	v_pk_add_f32 v[110:111], v[110:111], v[234:235]
	v_pk_add_f32 v[108:109], v[108:109], v[232:233]
	v_pk_add_f32 v[106:107], v[106:107], v[238:239]
	v_pk_add_f32 v[104:105], v[104:105], v[236:237]

.LBB0_1247:
	v_or_b32_e32 v112, 16, v142
	v_ashrrev_i32_e32 v113, 31, v112
	v_lshlrev_b64 v[112:113], 11, v[112:113]
	v_lshl_add_u64 v[112:113], v[144:145], 0, v[112:113]
	v_cvt_pk_bf16_f32 v108, v108, v109
	v_cvt_pk_bf16_f32 v109, v110, v111
	v_cvt_pk_bf16_f32 v110, v104, v105
	v_cvt_pk_bf16_f32 v111, v106, v107
	s_and_b64 vcc, exec, s[4:5]
	global_store_dwordx4 v[112:113], v[108:111], off
	s_cbranch_vccnz .LBB0_1249
	v_pk_add_f32 v[102:103], v[102:103], v[242:243]
	v_pk_add_f32 v[100:101], v[100:101], v[240:241]
	v_pk_add_f32 v[98:99], v[98:99], v[246:247]
	v_pk_add_f32 v[96:97], v[96:97], v[244:245]

.LBB0_1251:
	v_cvt_pk_bf16_f32 v100, v100, v101
	v_cvt_pk_bf16_f32 v101, v102, v103
	v_cvt_pk_bf16_f32 v102, v96, v97
	v_cvt_pk_bf16_f32 v103, v98, v99
	s_and_b64 vcc, exec, s[4:5]
	global_store_dwordx4 v[112:113], v[100:103], off offset:256
	s_cbranch_vccnz .LBB0_1253
	v_pk_add_f32 v[94:95], v[94:95], v[234:235]
	v_pk_add_f32 v[92:93], v[92:93], v[232:233]
	v_pk_add_f32 v[90:91], v[90:91], v[238:239]
	v_pk_add_f32 v[88:89], v[88:89], v[236:237]

.LBB0_1255:
	v_or_b32_e32 v96, 32, v142
	v_ashrrev_i32_e32 v97, 31, v96
	v_lshlrev_b64 v[96:97], 11, v[96:97]
	v_lshl_add_u64 v[96:97], v[144:145], 0, v[96:97]
	v_cvt_pk_bf16_f32 v92, v92, v93
	v_cvt_pk_bf16_f32 v93, v94, v95
	v_cvt_pk_bf16_f32 v94, v88, v89
	v_cvt_pk_bf16_f32 v95, v90, v91
	s_and_b64 vcc, exec, s[4:5]
	global_store_dwordx4 v[96:97], v[92:95], off
	s_cbranch_vccnz .LBB0_1257
	v_pk_add_f32 v[86:87], v[86:87], v[242:243]
	v_pk_add_f32 v[84:85], v[84:85], v[240:241]
	v_pk_add_f32 v[82:83], v[82:83], v[246:247]
	v_pk_add_f32 v[80:81], v[80:81], v[244:245]

.LBB0_1259:
	v_cvt_pk_bf16_f32 v84, v84, v85
	v_cvt_pk_bf16_f32 v85, v86, v87
	v_cvt_pk_bf16_f32 v86, v80, v81
	v_cvt_pk_bf16_f32 v87, v82, v83
	s_and_b64 vcc, exec, s[4:5]
	global_store_dwordx4 v[96:97], v[84:87], off offset:256
	s_cbranch_vccnz .LBB0_1261
	v_pk_add_f32 v[78:79], v[78:79], v[234:235]
	v_pk_add_f32 v[76:77], v[76:77], v[232:233]
	v_pk_add_f32 v[74:75], v[74:75], v[238:239]
	v_pk_add_f32 v[72:73], v[72:73], v[236:237]

.LBB0_1263:
	v_or_b32_e32 v80, 48, v142
	v_ashrrev_i32_e32 v81, 31, v80
	v_lshlrev_b64 v[80:81], 11, v[80:81]
	v_lshl_add_u64 v[80:81], v[144:145], 0, v[80:81]
	v_cvt_pk_bf16_f32 v76, v76, v77
	v_cvt_pk_bf16_f32 v77, v78, v79
	v_cvt_pk_bf16_f32 v78, v72, v73
	v_cvt_pk_bf16_f32 v79, v74, v75
	s_and_b64 vcc, exec, s[4:5]
	global_store_dwordx4 v[80:81], v[76:79], off
	s_cbranch_vccnz .LBB0_1265
	v_pk_add_f32 v[70:71], v[70:71], v[242:243]
	v_pk_add_f32 v[68:69], v[68:69], v[240:241]
	v_pk_add_f32 v[66:67], v[66:67], v[246:247]
	v_pk_add_f32 v[64:65], v[64:65], v[244:245]

.LBB0_1267:
	v_cvt_pk_bf16_f32 v68, v68, v69
	v_cvt_pk_bf16_f32 v69, v70, v71
	v_cvt_pk_bf16_f32 v70, v64, v65
	v_cvt_pk_bf16_f32 v71, v66, v67
	s_and_b64 vcc, exec, s[4:5]
	global_store_dwordx4 v[80:81], v[68:71], off offset:256
	s_cbranch_vccnz .LBB0_1269
	v_pk_add_f32 v[62:63], v[62:63], v[234:235]
	v_pk_add_f32 v[60:61], v[60:61], v[232:233]
	v_pk_add_f32 v[58:59], v[58:59], v[238:239]
	v_pk_add_f32 v[56:57], v[56:57], v[236:237]

.LBB0_1271:
	v_lshlrev_b64 v[64:65], 11, v[142:143]
	v_lshl_add_u64 v[64:65], v[144:145], 0, v[64:65]
	v_cvt_pk_bf16_f32 v60, v60, v61
	v_cvt_pk_bf16_f32 v61, v62, v63
	v_cvt_pk_bf16_f32 v62, v56, v57
	v_add_co_u32_e32 v56, vcc, 0x40000, v64
	v_cvt_pk_bf16_f32 v63, v58, v59
	s_nop 0
	v_addc_co_u32_e32 v57, vcc, 0, v65, vcc
	s_and_b64 vcc, exec, s[4:5]
	global_store_dwordx4 v[56:57], v[60:63], off
	s_cbranch_vccnz .LBB0_1273
	v_pk_add_f32 v[54:55], v[54:55], v[242:243]
	v_pk_add_f32 v[52:53], v[52:53], v[240:241]
	v_pk_add_f32 v[50:51], v[50:51], v[246:247]
	v_pk_add_f32 v[48:49], v[48:49], v[244:245]

.LBB0_1275:
	v_lshl_add_u64 v[56:57], v[64:65], 0, s[40:41]
	v_cvt_pk_bf16_f32 v52, v52, v53
	v_cvt_pk_bf16_f32 v53, v54, v55
	v_cvt_pk_bf16_f32 v54, v48, v49
	v_cvt_pk_bf16_f32 v55, v50, v51
	s_and_b64 vcc, exec, s[4:5]
	global_store_dwordx4 v[56:57], v[52:55], off offset:256
	s_cbranch_vccnz .LBB0_1277
	v_pk_add_f32 v[46:47], v[46:47], v[234:235]
	v_pk_add_f32 v[44:45], v[44:45], v[232:233]
	v_pk_add_f32 v[42:43], v[42:43], v[238:239]
	v_pk_add_f32 v[40:41], v[40:41], v[236:237]

.LBB0_1279:
	v_lshlrev_b64 v[48:49], 11, v[142:143]
	v_lshl_add_u64 v[48:49], v[144:145], 0, v[48:49]
	v_cvt_pk_bf16_f32 v44, v44, v45
	v_cvt_pk_bf16_f32 v45, v46, v47
	v_cvt_pk_bf16_f32 v46, v40, v41
	v_add_co_u32_e32 v40, vcc, 0x48000, v48
	v_cvt_pk_bf16_f32 v47, v42, v43
	s_nop 0
	v_addc_co_u32_e32 v41, vcc, 0, v49, vcc
	s_and_b64 vcc, exec, s[4:5]
	global_store_dwordx4 v[40:41], v[44:47], off
	s_cbranch_vccnz .LBB0_1281
	v_pk_add_f32 v[38:39], v[38:39], v[242:243]
	v_pk_add_f32 v[36:37], v[36:37], v[240:241]
	v_pk_add_f32 v[34:35], v[34:35], v[246:247]
	v_pk_add_f32 v[32:33], v[32:33], v[244:245]

.LBB0_1283:
	v_lshl_add_u64 v[40:41], v[48:49], 0, s[42:43]
	v_cvt_pk_bf16_f32 v36, v36, v37
	v_cvt_pk_bf16_f32 v37, v38, v39
	v_cvt_pk_bf16_f32 v38, v32, v33
	v_cvt_pk_bf16_f32 v39, v34, v35
	s_and_b64 vcc, exec, s[4:5]
	global_store_dwordx4 v[40:41], v[36:39], off offset:256
	s_cbranch_vccnz .LBB0_1285
	v_pk_add_f32 v[30:31], v[30:31], v[234:235]
	v_pk_add_f32 v[28:29], v[28:29], v[232:233]
	v_pk_add_f32 v[26:27], v[26:27], v[238:239]
	v_pk_add_f32 v[24:25], v[24:25], v[236:237]

.LBB0_1287:
	v_lshlrev_b64 v[32:33], 11, v[142:143]
	v_lshl_add_u64 v[32:33], v[144:145], 0, v[32:33]
	v_cvt_pk_bf16_f32 v28, v28, v29
	v_cvt_pk_bf16_f32 v29, v30, v31
	v_cvt_pk_bf16_f32 v30, v24, v25
	v_add_co_u32_e32 v24, vcc, 0x50000, v32
	v_cvt_pk_bf16_f32 v31, v26, v27
	s_nop 0
	v_addc_co_u32_e32 v25, vcc, 0, v33, vcc
	s_and_b64 vcc, exec, s[4:5]
	global_store_dwordx4 v[24:25], v[28:31], off
	s_cbranch_vccnz .LBB0_1289
	v_pk_add_f32 v[22:23], v[22:23], v[242:243]
	v_pk_add_f32 v[20:21], v[20:21], v[240:241]
	v_pk_add_f32 v[18:19], v[18:19], v[246:247]
	v_pk_add_f32 v[16:17], v[16:17], v[244:245]

.LBB0_1291:
	v_lshl_add_u64 v[24:25], v[32:33], 0, s[44:45]
	v_cvt_pk_bf16_f32 v20, v20, v21
	v_cvt_pk_bf16_f32 v21, v22, v23
	v_cvt_pk_bf16_f32 v22, v16, v17
	v_cvt_pk_bf16_f32 v23, v18, v19
	s_and_b64 vcc, exec, s[4:5]
	global_store_dwordx4 v[24:25], v[20:23], off offset:256
	s_cbranch_vccnz .LBB0_1293
	v_pk_add_f32 v[14:15], v[14:15], v[234:235]
	v_pk_add_f32 v[12:13], v[12:13], v[232:233]
	v_pk_add_f32 v[10:11], v[10:11], v[238:239]
	v_pk_add_f32 v[8:9], v[8:9], v[236:237]

.LBB0_1295:
	v_lshlrev_b64 v[16:17], 11, v[142:143]
	v_lshl_add_u64 v[16:17], v[144:145], 0, v[16:17]
	v_cvt_pk_bf16_f32 v12, v12, v13
	v_cvt_pk_bf16_f32 v13, v14, v15
	v_cvt_pk_bf16_f32 v14, v8, v9
	v_add_co_u32_e32 v8, vcc, 0x58000, v16
	v_cvt_pk_bf16_f32 v15, v10, v11
	s_nop 0
	v_addc_co_u32_e32 v9, vcc, 0, v17, vcc
	s_and_b64 vcc, exec, s[4:5]
	global_store_dwordx4 v[8:9], v[12:15], off
	s_cbranch_vccnz .LBB0_1297
	v_pk_add_f32 v[6:7], v[6:7], v[242:243]
	v_pk_add_f32 v[4:5], v[4:5], v[240:241]
	v_pk_add_f32 v[2:3], v[2:3], v[246:247]
	v_pk_add_f32 v[0:1], v[0:1], v[244:245]

.LBB0_1501:
	v_lshl_add_u32 v144, s4, 8, v152
	v_ashrrev_i32_e32 v145, 31, v144
	v_lshl_add_u64 v[150:151], v[144:145], 2, s[6:7]
	global_load_dword v240, v[150:151], off
	global_load_dword v241, v[150:151], off offset:64
	global_load_dword v242, v[150:151], off offset:128
	global_load_dword v243, v[150:151], off offset:192
	global_load_dword v244, v[150:151], off offset:512
	global_load_dword v245, v[150:151], off offset:576
	global_load_dword v246, v[150:151], off offset:640
	global_load_dword v247, v[150:151], off offset:704
	v_or_b32_e32 v162, 16, v144
	v_ashrrev_i32_e32 v163, 31, v162
	v_lshl_add_u64 v[164:165], v[162:163], 2, s[6:7]
	v_lshl_add_u32 v148, s5, 7, v154
	v_mov_b64_e32 v[146:147], s[14:15]
	v_ashrrev_i32_e32 v149, 31, v148
	v_mad_i64_i32 v[160:161], s[4:5], v144, s66, v[146:147]
	v_lshlrev_b64 v[148:149], 1, v[148:149]
	v_lshl_add_u64 v[160:161], v[160:161], 0, v[148:149]
	s_waitcnt vmcnt(7)
	v_fmamk_f32 v145, v240, 0x3a800000, v158
	v_mul_f32_e32 v159, 0x4b800000, v145
	v_cmp_gt_f32_e32 vcc, s65, v145
	s_nop 1
	v_cndmask_b32_e32 v145, v145, v159, vcc
	v_rsq_f32_e32 v145, v145
	s_nop 0
	v_mul_f32_e32 v159, 0x45800000, v145
	v_cndmask_b32_e32 v166, v145, v159, vcc
	v_pk_mul_f32 v[124:125], v[124:125], v[166:167] op_sel_hi:[1,0]
	v_pk_mul_f32 v[126:127], v[126:127], v[166:167] op_sel_hi:[1,0]
	v_pk_mul_f32 v[120:121], v[120:121], v[166:167] op_sel_hi:[1,0]
	v_pk_mul_f32 v[122:123], v[122:123], v[166:167] op_sel_hi:[1,0]
	v_pk_mul_f32 v[116:117], v[116:117], v[166:167] op_sel_hi:[1,0]
	v_pk_mul_f32 v[118:119], v[118:119], v[166:167] op_sel_hi:[1,0]
	v_pk_mul_f32 v[112:113], v[112:113], v[166:167] op_sel_hi:[1,0]
	v_pk_mul_f32 v[114:115], v[114:115], v[166:167] op_sel_hi:[1,0]
	v_mul_f32_e32 v145, 0xbfb8aa3b, v124
	v_mul_f32_e32 v159, 0xbfb8aa3b, v125
	v_mul_f32_e32 v163, 0xbfb8aa3b, v126
	v_mul_f32_e32 v166, 0xbfb8aa3b, v127
	v_mul_f32_e32 v167, 0xbfb8aa3b, v120
	v_mul_f32_e32 v168, 0xbfb8aa3b, v121
	v_mul_f32_e32 v169, 0xbfb8aa3b, v122
	v_mul_f32_e32 v170, 0xbfb8aa3b, v123
	v_exp_f32_e32 v145, v145
	v_exp_f32_e32 v159, v159
	v_exp_f32_e32 v163, v163
	v_exp_f32_e32 v166, v166
	v_exp_f32_e32 v167, v167
	v_exp_f32_e32 v168, v168
	v_exp_f32_e32 v169, v169
	v_exp_f32_e32 v170, v170
	v_add_f32_e32 v145, 1.0, v145
	v_add_f32_e32 v159, 1.0, v159
	v_add_f32_e32 v163, 1.0, v163
	v_add_f32_e32 v171, 1.0, v166
	v_add_f32_e32 v172, 1.0, v167
	v_add_f32_e32 v173, 1.0, v168
	v_add_f32_e32 v174, 1.0, v169
	v_add_f32_e32 v175, 1.0, v170
	v_rcp_f32_e32 v166, v145
	v_rcp_f32_e32 v167, v159
	v_rcp_f32_e32 v168, v163
	v_rcp_f32_e32 v169, v171
	v_rcp_f32_e32 v170, v172
	v_rcp_f32_e32 v171, v173
	v_rcp_f32_e32 v172, v174
	v_rcp_f32_e32 v173, v175
	v_pk_mul_f32 v[124:125], v[124:125], v[166:167]
	v_pk_mul_f32 v[126:127], v[126:127], v[168:169]
	v_pk_mul_f32 v[120:121], v[120:121], v[170:171]
	v_pk_mul_f32 v[122:123], v[122:123], v[172:173]
	v_pk_mul_f32 v[116:117], v[116:117], v[124:125]
	v_pk_mul_f32 v[118:119], v[118:119], v[126:127]
	v_pk_mul_f32 v[120:121], v[112:113], v[120:121]
	v_pk_mul_f32 v[122:123], v[114:115], v[122:123]
	v_cvt_pk_bf16_f32 v112, v116, v117
	v_cvt_pk_bf16_f32 v113, v118, v119
	v_cvt_pk_bf16_f32 v114, v120, v121
	v_cvt_pk_bf16_f32 v115, v122, v123
	global_store_dwordx4 v[160:161], v[112:115], off
	s_nop 0
	s_nop 0
	v_or_b32_e32 v112, 32, v144
	v_mad_i64_i32 v[114:115], s[4:5], v162, s66, v[146:147]
	v_lshl_add_u64 v[114:115], v[114:115], 0, v[148:149]
	s_waitcnt vmcnt(7)
	v_fmamk_f32 v113, v241, 0x3a800000, v158
	v_mul_f32_e32 v116, 0x4b800000, v113
	v_cmp_gt_f32_e32 vcc, s65, v113
	s_nop 1
	v_cndmask_b32_e32 v113, v113, v116, vcc
	v_rsq_f32_e32 v118, v113
	v_ashrrev_i32_e32 v113, 31, v112
	v_lshl_add_u64 v[116:117], v[112:113], 2, s[6:7]
	v_mul_f32_e32 v113, 0x45800000, v118
	v_cndmask_b32_e32 v118, v118, v113, vcc
	v_pk_mul_f32 v[108:109], v[108:109], v[118:119] op_sel_hi:[1,0]
	v_pk_mul_f32 v[110:111], v[110:111], v[118:119] op_sel_hi:[1,0]
	v_pk_mul_f32 v[104:105], v[104:105], v[118:119] op_sel_hi:[1,0]
	v_pk_mul_f32 v[106:107], v[106:107], v[118:119] op_sel_hi:[1,0]
	v_pk_mul_f32 v[100:101], v[100:101], v[118:119] op_sel_hi:[1,0]
	v_pk_mul_f32 v[102:103], v[102:103], v[118:119] op_sel_hi:[1,0]
	v_pk_mul_f32 v[96:97], v[96:97], v[118:119] op_sel_hi:[1,0]
	v_pk_mul_f32 v[98:99], v[98:99], v[118:119] op_sel_hi:[1,0]
	v_mul_f32_e32 v113, 0xbfb8aa3b, v108
	v_mul_f32_e32 v118, 0xbfb8aa3b, v109
	v_mul_f32_e32 v119, 0xbfb8aa3b, v110
	v_mul_f32_e32 v120, 0xbfb8aa3b, v111
	v_mul_f32_e32 v121, 0xbfb8aa3b, v104
	v_mul_f32_e32 v122, 0xbfb8aa3b, v105
	v_mul_f32_e32 v123, 0xbfb8aa3b, v106
	v_mul_f32_e32 v124, 0xbfb8aa3b, v107
	v_exp_f32_e32 v113, v113
	v_exp_f32_e32 v118, v118
	v_exp_f32_e32 v119, v119
	v_exp_f32_e32 v120, v120
	v_exp_f32_e32 v121, v121
	v_exp_f32_e32 v122, v122
	v_exp_f32_e32 v123, v123
	v_exp_f32_e32 v124, v124
	v_add_f32_e32 v113, 1.0, v113
	v_add_f32_e32 v125, 1.0, v118
	v_add_f32_e32 v126, 1.0, v119
	v_add_f32_e32 v127, 1.0, v120
	v_add_f32_e32 v145, 1.0, v121
	v_add_f32_e32 v159, 1.0, v122
	v_add_f32_e32 v160, 1.0, v123
	v_add_f32_e32 v161, 1.0, v124
	v_rcp_f32_e32 v118, v113
	v_rcp_f32_e32 v119, v125
	v_rcp_f32_e32 v120, v126
	v_rcp_f32_e32 v121, v127
	v_rcp_f32_e32 v122, v145
	v_rcp_f32_e32 v123, v159
	v_rcp_f32_e32 v124, v160
	v_rcp_f32_e32 v125, v161
	v_pk_mul_f32 v[108:109], v[108:109], v[118:119]
	v_pk_mul_f32 v[110:111], v[110:111], v[120:121]
	v_pk_mul_f32 v[104:105], v[104:105], v[122:123]
	v_pk_mul_f32 v[106:107], v[106:107], v[124:125]
	v_pk_mul_f32 v[100:101], v[100:101], v[108:109]
	v_pk_mul_f32 v[102:103], v[102:103], v[110:111]
	v_pk_mul_f32 v[104:105], v[96:97], v[104:105]
	v_pk_mul_f32 v[106:107], v[98:99], v[106:107]
	v_cvt_pk_bf16_f32 v96, v100, v101
	v_cvt_pk_bf16_f32 v97, v102, v103
	v_cvt_pk_bf16_f32 v98, v104, v105
	v_cvt_pk_bf16_f32 v99, v106, v107
	global_store_dwordx4 v[114:115], v[96:99], off
	s_nop 0
	s_nop 0
	v_or_b32_e32 v96, 48, v144
	v_mad_i64_i32 v[98:99], s[4:5], v112, s66, v[146:147]
	v_lshl_add_u64 v[98:99], v[98:99], 0, v[148:149]
	s_waitcnt vmcnt(7)
	v_fmamk_f32 v97, v242, 0x3a800000, v158
	v_mul_f32_e32 v100, 0x4b800000, v97
	v_cmp_gt_f32_e32 vcc, s65, v97
	s_nop 1
	v_cndmask_b32_e32 v97, v97, v100, vcc
	v_rsq_f32_e32 v102, v97
	v_ashrrev_i32_e32 v97, 31, v96
	v_lshl_add_u64 v[100:101], v[96:97], 2, s[6:7]
	v_mul_f32_e32 v97, 0x45800000, v102
	v_cndmask_b32_e32 v102, v102, v97, vcc
	v_pk_mul_f32 v[92:93], v[92:93], v[102:103] op_sel_hi:[1,0]
	v_pk_mul_f32 v[94:95], v[94:95], v[102:103] op_sel_hi:[1,0]
	v_pk_mul_f32 v[88:89], v[88:89], v[102:103] op_sel_hi:[1,0]
	v_pk_mul_f32 v[90:91], v[90:91], v[102:103] op_sel_hi:[1,0]
	v_pk_mul_f32 v[84:85], v[84:85], v[102:103] op_sel_hi:[1,0]
	v_pk_mul_f32 v[86:87], v[86:87], v[102:103] op_sel_hi:[1,0]
	v_pk_mul_f32 v[80:81], v[80:81], v[102:103] op_sel_hi:[1,0]
	v_pk_mul_f32 v[82:83], v[82:83], v[102:103] op_sel_hi:[1,0]
	v_mul_f32_e32 v97, 0xbfb8aa3b, v92
	v_mul_f32_e32 v102, 0xbfb8aa3b, v93
	v_mul_f32_e32 v103, 0xbfb8aa3b, v94
	v_mul_f32_e32 v104, 0xbfb8aa3b, v95
	v_mul_f32_e32 v105, 0xbfb8aa3b, v88
	v_mul_f32_e32 v106, 0xbfb8aa3b, v89
	v_mul_f32_e32 v107, 0xbfb8aa3b, v90
	v_mul_f32_e32 v108, 0xbfb8aa3b, v91
	v_exp_f32_e32 v97, v97
	v_exp_f32_e32 v102, v102
	v_exp_f32_e32 v103, v103
	v_exp_f32_e32 v104, v104
	v_exp_f32_e32 v105, v105
	v_exp_f32_e32 v106, v106
	v_exp_f32_e32 v107, v107
	v_exp_f32_e32 v108, v108
	v_add_f32_e32 v97, 1.0, v97
	v_add_f32_e32 v109, 1.0, v102
	v_add_f32_e32 v110, 1.0, v103
	v_add_f32_e32 v111, 1.0, v104
	v_add_f32_e32 v112, 1.0, v105
	v_add_f32_e32 v113, 1.0, v106
	v_add_f32_e32 v114, 1.0, v107
	v_add_f32_e32 v115, 1.0, v108
	v_rcp_f32_e32 v102, v97
	v_rcp_f32_e32 v103, v109
	v_rcp_f32_e32 v104, v110
	v_rcp_f32_e32 v105, v111
	v_rcp_f32_e32 v106, v112
	v_rcp_f32_e32 v107, v113
	v_rcp_f32_e32 v108, v114
	v_rcp_f32_e32 v109, v115
	v_pk_mul_f32 v[92:93], v[92:93], v[102:103]
	v_pk_mul_f32 v[94:95], v[94:95], v[104:105]
	v_pk_mul_f32 v[88:89], v[88:89], v[106:107]
	v_pk_mul_f32 v[90:91], v[90:91], v[108:109]
	v_pk_mul_f32 v[84:85], v[84:85], v[92:93]
	v_pk_mul_f32 v[86:87], v[86:87], v[94:95]
	v_pk_mul_f32 v[88:89], v[80:81], v[88:89]
	v_pk_mul_f32 v[90:91], v[82:83], v[90:91]
	v_cvt_pk_bf16_f32 v80, v84, v85
	v_cvt_pk_bf16_f32 v81, v86, v87
	v_cvt_pk_bf16_f32 v82, v88, v89
	v_cvt_pk_bf16_f32 v83, v90, v91
	global_store_dwordx4 v[98:99], v[80:83], off
	s_nop 0
	s_waitcnt vmcnt(7)
	v_fmamk_f32 v80, v243, 0x3a800000, v158
	v_mul_f32_e32 v81, 0x4b800000, v80
	v_cmp_gt_f32_e32 vcc, s65, v80
	s_nop 1
	v_cndmask_b32_e32 v80, v80, v81, vcc
	v_rsq_f32_e32 v82, v80
	v_mad_i64_i32 v[80:81], s[4:5], v96, s66, v[146:147]
	v_lshl_add_u64 v[80:81], v[80:81], 0, v[148:149]
	v_mul_f32_e32 v83, 0x45800000, v82
	v_cndmask_b32_e32 v82, v82, v83, vcc
	v_pk_mul_f32 v[76:77], v[76:77], v[82:83] op_sel_hi:[1,0]
	v_pk_mul_f32 v[78:79], v[78:79], v[82:83] op_sel_hi:[1,0]
	v_pk_mul_f32 v[72:73], v[72:73], v[82:83] op_sel_hi:[1,0]
	v_pk_mul_f32 v[74:75], v[74:75], v[82:83] op_sel_hi:[1,0]
	v_pk_mul_f32 v[68:69], v[68:69], v[82:83] op_sel_hi:[1,0]
	v_pk_mul_f32 v[70:71], v[70:71], v[82:83] op_sel_hi:[1,0]
	v_pk_mul_f32 v[64:65], v[64:65], v[82:83] op_sel_hi:[1,0]
	v_pk_mul_f32 v[66:67], v[66:67], v[82:83] op_sel_hi:[1,0]
	v_mul_f32_e32 v82, 0xbfb8aa3b, v76
	v_mul_f32_e32 v83, 0xbfb8aa3b, v77
	v_mul_f32_e32 v84, 0xbfb8aa3b, v78
	v_mul_f32_e32 v85, 0xbfb8aa3b, v79
	v_mul_f32_e32 v86, 0xbfb8aa3b, v72
	v_mul_f32_e32 v87, 0xbfb8aa3b, v73
	v_mul_f32_e32 v88, 0xbfb8aa3b, v74
	v_mul_f32_e32 v89, 0xbfb8aa3b, v75
	v_exp_f32_e32 v82, v82
	v_exp_f32_e32 v83, v83
	v_exp_f32_e32 v84, v84
	v_exp_f32_e32 v85, v85
	v_exp_f32_e32 v86, v86
	v_exp_f32_e32 v87, v87
	v_exp_f32_e32 v88, v88
	v_exp_f32_e32 v89, v89
	v_add_f32_e32 v82, 1.0, v82
	v_add_f32_e32 v83, 1.0, v83
	v_add_f32_e32 v84, 1.0, v84
	v_add_f32_e32 v85, 1.0, v85
	v_add_f32_e32 v86, 1.0, v86
	v_add_f32_e32 v87, 1.0, v87
	v_add_f32_e32 v88, 1.0, v88
	v_add_f32_e32 v89, 1.0, v89
	v_rcp_f32_e32 v82, v82
	v_rcp_f32_e32 v83, v83
	v_rcp_f32_e32 v84, v84
	v_rcp_f32_e32 v85, v85
	v_rcp_f32_e32 v86, v86
	v_rcp_f32_e32 v87, v87
	v_rcp_f32_e32 v88, v88
	v_rcp_f32_e32 v89, v89
	v_pk_mul_f32 v[76:77], v[76:77], v[82:83]
	v_pk_mul_f32 v[78:79], v[78:79], v[84:85]
	v_pk_mul_f32 v[72:73], v[72:73], v[86:87]
	v_pk_mul_f32 v[74:75], v[74:75], v[88:89]
	v_pk_mul_f32 v[68:69], v[68:69], v[76:77]
	v_pk_mul_f32 v[70:71], v[70:71], v[78:79]
	v_pk_mul_f32 v[72:73], v[64:65], v[72:73]
	v_pk_mul_f32 v[74:75], v[66:67], v[74:75]
	v_cvt_pk_bf16_f32 v64, v68, v69
	v_cvt_pk_bf16_f32 v65, v70, v71
	v_cvt_pk_bf16_f32 v66, v72, v73
	v_cvt_pk_bf16_f32 v67, v74, v75
	global_store_dwordx4 v[80:81], v[64:67], off
	s_nop 0
	s_nop 0
	v_add_u32_e32 v65, 0x80, v144
	s_waitcnt vmcnt(7)
	v_fmamk_f32 v64, v244, 0x3a800000, v158
	v_mul_f32_e32 v66, 0x4b800000, v64
	v_cmp_gt_f32_e32 vcc, s65, v64
	s_nop 1
	v_cndmask_b32_e32 v64, v64, v66, vcc
	v_rsq_f32_e32 v66, v64
	v_mad_i64_i32 v[64:65], s[4:5], v65, s66, v[146:147]
	v_lshl_add_u64 v[64:65], v[64:65], 0, v[148:149]
	v_mul_f32_e32 v67, 0x45800000, v66
	v_cndmask_b32_e32 v66, v66, v67, vcc
	v_pk_mul_f32 v[60:61], v[60:61], v[66:67] op_sel_hi:[1,0]
	v_pk_mul_f32 v[62:63], v[62:63], v[66:67] op_sel_hi:[1,0]
	v_pk_mul_f32 v[56:57], v[56:57], v[66:67] op_sel_hi:[1,0]
	v_pk_mul_f32 v[58:59], v[58:59], v[66:67] op_sel_hi:[1,0]
	v_pk_mul_f32 v[52:53], v[52:53], v[66:67] op_sel_hi:[1,0]
	v_pk_mul_f32 v[54:55], v[54:55], v[66:67] op_sel_hi:[1,0]
	v_pk_mul_f32 v[48:49], v[48:49], v[66:67] op_sel_hi:[1,0]
	v_pk_mul_f32 v[50:51], v[50:51], v[66:67] op_sel_hi:[1,0]
	v_mul_f32_e32 v66, 0xbfb8aa3b, v60
	v_mul_f32_e32 v67, 0xbfb8aa3b, v61
	v_mul_f32_e32 v68, 0xbfb8aa3b, v62
	v_mul_f32_e32 v69, 0xbfb8aa3b, v63
	v_mul_f32_e32 v70, 0xbfb8aa3b, v56
	v_mul_f32_e32 v71, 0xbfb8aa3b, v57
	v_mul_f32_e32 v72, 0xbfb8aa3b, v58
	v_mul_f32_e32 v73, 0xbfb8aa3b, v59
	v_exp_f32_e32 v66, v66
	v_exp_f32_e32 v67, v67
	v_exp_f32_e32 v68, v68
	v_exp_f32_e32 v69, v69
	v_exp_f32_e32 v70, v70
	v_exp_f32_e32 v71, v71
	v_exp_f32_e32 v72, v72
	v_exp_f32_e32 v73, v73
	v_add_f32_e32 v66, 1.0, v66
	v_add_f32_e32 v67, 1.0, v67
	v_add_f32_e32 v68, 1.0, v68
	v_add_f32_e32 v69, 1.0, v69
	v_add_f32_e32 v70, 1.0, v70
	v_add_f32_e32 v71, 1.0, v71
	v_add_f32_e32 v72, 1.0, v72
	v_add_f32_e32 v73, 1.0, v73
	v_rcp_f32_e32 v66, v66
	v_rcp_f32_e32 v67, v67
	v_rcp_f32_e32 v68, v68
	v_rcp_f32_e32 v69, v69
	v_rcp_f32_e32 v70, v70
	v_rcp_f32_e32 v71, v71
	v_rcp_f32_e32 v72, v72
	v_rcp_f32_e32 v73, v73
	v_pk_mul_f32 v[60:61], v[60:61], v[66:67]
	v_pk_mul_f32 v[62:63], v[62:63], v[68:69]
	v_pk_mul_f32 v[56:57], v[56:57], v[70:71]
	v_pk_mul_f32 v[58:59], v[58:59], v[72:73]
	v_pk_mul_f32 v[52:53], v[52:53], v[60:61]
	v_pk_mul_f32 v[54:55], v[54:55], v[62:63]
	v_pk_mul_f32 v[56:57], v[48:49], v[56:57]
	v_pk_mul_f32 v[58:59], v[50:51], v[58:59]
	v_cvt_pk_bf16_f32 v48, v52, v53
	v_cvt_pk_bf16_f32 v49, v54, v55
	v_cvt_pk_bf16_f32 v50, v56, v57
	v_cvt_pk_bf16_f32 v51, v58, v59
	global_store_dwordx4 v[64:65], v[48:51], off
	s_nop 0
	s_nop 0
	v_add_u32_e32 v49, 0x90, v144
	s_waitcnt vmcnt(7)
	v_fmamk_f32 v48, v245, 0x3a800000, v158
	v_mul_f32_e32 v50, 0x4b800000, v48
	v_cmp_gt_f32_e32 vcc, s65, v48
	s_nop 1
	v_cndmask_b32_e32 v48, v48, v50, vcc
	v_rsq_f32_e32 v50, v48
	v_mad_i64_i32 v[48:49], s[4:5], v49, s66, v[146:147]
	v_lshl_add_u64 v[48:49], v[48:49], 0, v[148:149]
	v_mul_f32_e32 v51, 0x45800000, v50
	v_cndmask_b32_e32 v50, v50, v51, vcc
	v_pk_mul_f32 v[44:45], v[44:45], v[50:51] op_sel_hi:[1,0]
	v_pk_mul_f32 v[46:47], v[46:47], v[50:51] op_sel_hi:[1,0]
	v_pk_mul_f32 v[40:41], v[40:41], v[50:51] op_sel_hi:[1,0]
	v_pk_mul_f32 v[42:43], v[42:43], v[50:51] op_sel_hi:[1,0]
	v_pk_mul_f32 v[36:37], v[36:37], v[50:51] op_sel_hi:[1,0]
	v_pk_mul_f32 v[38:39], v[38:39], v[50:51] op_sel_hi:[1,0]
	v_pk_mul_f32 v[32:33], v[32:33], v[50:51] op_sel_hi:[1,0]
	v_pk_mul_f32 v[34:35], v[34:35], v[50:51] op_sel_hi:[1,0]
	v_mul_f32_e32 v50, 0xbfb8aa3b, v44
	v_mul_f32_e32 v51, 0xbfb8aa3b, v45
	v_mul_f32_e32 v52, 0xbfb8aa3b, v46
	v_mul_f32_e32 v53, 0xbfb8aa3b, v47
	v_mul_f32_e32 v54, 0xbfb8aa3b, v40
	v_mul_f32_e32 v55, 0xbfb8aa3b, v41
	v_mul_f32_e32 v56, 0xbfb8aa3b, v42
	v_mul_f32_e32 v57, 0xbfb8aa3b, v43
	v_exp_f32_e32 v50, v50
	v_exp_f32_e32 v51, v51
	v_exp_f32_e32 v52, v52
	v_exp_f32_e32 v53, v53
	v_exp_f32_e32 v54, v54
	v_exp_f32_e32 v55, v55
	v_exp_f32_e32 v56, v56
	v_exp_f32_e32 v57, v57
	v_add_f32_e32 v50, 1.0, v50
	v_add_f32_e32 v51, 1.0, v51
	v_add_f32_e32 v52, 1.0, v52
	v_add_f32_e32 v53, 1.0, v53
	v_add_f32_e32 v54, 1.0, v54
	v_add_f32_e32 v55, 1.0, v55
	v_add_f32_e32 v56, 1.0, v56
	v_add_f32_e32 v57, 1.0, v57
	v_rcp_f32_e32 v50, v50
	v_rcp_f32_e32 v51, v51
	v_rcp_f32_e32 v52, v52
	v_rcp_f32_e32 v53, v53
	v_rcp_f32_e32 v54, v54
	v_rcp_f32_e32 v55, v55
	v_rcp_f32_e32 v56, v56
	v_rcp_f32_e32 v57, v57
	v_pk_mul_f32 v[44:45], v[44:45], v[50:51]
	v_pk_mul_f32 v[46:47], v[46:47], v[52:53]
	v_pk_mul_f32 v[40:41], v[40:41], v[54:55]
	v_pk_mul_f32 v[42:43], v[42:43], v[56:57]
	v_pk_mul_f32 v[36:37], v[36:37], v[44:45]
	v_pk_mul_f32 v[38:39], v[38:39], v[46:47]
	v_pk_mul_f32 v[40:41], v[32:33], v[40:41]
	v_pk_mul_f32 v[42:43], v[34:35], v[42:43]
	v_cvt_pk_bf16_f32 v32, v36, v37
	v_cvt_pk_bf16_f32 v33, v38, v39
	v_cvt_pk_bf16_f32 v34, v40, v41
	v_cvt_pk_bf16_f32 v35, v42, v43
	global_store_dwordx4 v[48:49], v[32:35], off
	s_nop 0
	s_nop 0
	v_add_u32_e32 v33, 0xa0, v144
	s_waitcnt vmcnt(7)
	v_fmamk_f32 v32, v246, 0x3a800000, v158
	v_mul_f32_e32 v34, 0x4b800000, v32
	v_cmp_gt_f32_e32 vcc, s65, v32
	s_nop 1
	v_cndmask_b32_e32 v32, v32, v34, vcc
	v_rsq_f32_e32 v34, v32
	v_mad_i64_i32 v[32:33], s[4:5], v33, s66, v[146:147]
	v_lshl_add_u64 v[32:33], v[32:33], 0, v[148:149]
	v_mul_f32_e32 v35, 0x45800000, v34
	v_cndmask_b32_e32 v34, v34, v35, vcc
	v_pk_mul_f32 v[28:29], v[28:29], v[34:35] op_sel_hi:[1,0]
	v_pk_mul_f32 v[30:31], v[30:31], v[34:35] op_sel_hi:[1,0]
	v_pk_mul_f32 v[24:25], v[24:25], v[34:35] op_sel_hi:[1,0]
	v_pk_mul_f32 v[26:27], v[26:27], v[34:35] op_sel_hi:[1,0]
	v_pk_mul_f32 v[20:21], v[20:21], v[34:35] op_sel_hi:[1,0]
	v_pk_mul_f32 v[22:23], v[22:23], v[34:35] op_sel_hi:[1,0]
	v_pk_mul_f32 v[16:17], v[16:17], v[34:35] op_sel_hi:[1,0]
	v_pk_mul_f32 v[18:19], v[18:19], v[34:35] op_sel_hi:[1,0]
	v_mul_f32_e32 v34, 0xbfb8aa3b, v28
	v_mul_f32_e32 v35, 0xbfb8aa3b, v29
	v_mul_f32_e32 v36, 0xbfb8aa3b, v30
	v_mul_f32_e32 v37, 0xbfb8aa3b, v31
	v_mul_f32_e32 v38, 0xbfb8aa3b, v24
	v_mul_f32_e32 v39, 0xbfb8aa3b, v25
	v_mul_f32_e32 v40, 0xbfb8aa3b, v26
	v_mul_f32_e32 v41, 0xbfb8aa3b, v27
	v_exp_f32_e32 v34, v34
	v_exp_f32_e32 v35, v35
	v_exp_f32_e32 v36, v36
	v_exp_f32_e32 v37, v37
	v_exp_f32_e32 v38, v38
	v_exp_f32_e32 v39, v39
	v_exp_f32_e32 v40, v40
	v_exp_f32_e32 v41, v41
	v_add_f32_e32 v34, 1.0, v34
	v_add_f32_e32 v35, 1.0, v35
	v_add_f32_e32 v36, 1.0, v36
	v_add_f32_e32 v37, 1.0, v37
	v_add_f32_e32 v38, 1.0, v38
	v_add_f32_e32 v39, 1.0, v39
	v_add_f32_e32 v40, 1.0, v40
	v_add_f32_e32 v41, 1.0, v41
	v_rcp_f32_e32 v34, v34
	v_rcp_f32_e32 v35, v35
	v_rcp_f32_e32 v36, v36
	v_rcp_f32_e32 v37, v37
	v_rcp_f32_e32 v38, v38
	v_rcp_f32_e32 v39, v39
	v_rcp_f32_e32 v40, v40
	v_rcp_f32_e32 v41, v41
	v_pk_mul_f32 v[28:29], v[28:29], v[34:35]
	v_pk_mul_f32 v[30:31], v[30:31], v[36:37]
	v_pk_mul_f32 v[24:25], v[24:25], v[38:39]
	v_pk_mul_f32 v[26:27], v[26:27], v[40:41]
	v_pk_mul_f32 v[20:21], v[20:21], v[28:29]
	v_pk_mul_f32 v[22:23], v[22:23], v[30:31]
	v_pk_mul_f32 v[24:25], v[16:17], v[24:25]
	v_pk_mul_f32 v[26:27], v[18:19], v[26:27]
	v_cvt_pk_bf16_f32 v16, v20, v21
	v_cvt_pk_bf16_f32 v17, v22, v23
	v_cvt_pk_bf16_f32 v18, v24, v25
	v_cvt_pk_bf16_f32 v19, v26, v27
	global_store_dwordx4 v[32:33], v[16:19], off
	s_nop 0
	s_andn2_b64 vcc, exec, s[2:3]
	v_add_u32_e32 v17, 0xb0, v144
	s_mov_b64 s[2:3], -1
	s_waitcnt vmcnt(7)
	v_fmamk_f32 v16, v247, 0x3a800000, v158
	v_mul_f32_e32 v18, 0x4b800000, v16
	v_cmp_gt_f32_e64 s[4:5], s65, v16
	s_nop 1
	v_cndmask_b32_e64 v16, v16, v18, s[4:5]
	v_rsq_f32_e32 v18, v16
	v_mad_i64_i32 v[16:17], s[40:41], v17, s66, v[146:147]
	v_lshl_add_u64 v[16:17], v[16:17], 0, v[148:149]
	v_mul_f32_e32 v19, 0x45800000, v18
	v_cndmask_b32_e64 v18, v18, v19, s[4:5]
	v_pk_mul_f32 v[12:13], v[12:13], v[18:19] op_sel_hi:[1,0]
	v_pk_mul_f32 v[14:15], v[14:15], v[18:19] op_sel_hi:[1,0]
	v_pk_mul_f32 v[8:9], v[8:9], v[18:19] op_sel_hi:[1,0]
	v_pk_mul_f32 v[10:11], v[10:11], v[18:19] op_sel_hi:[1,0]
	v_pk_mul_f32 v[4:5], v[4:5], v[18:19] op_sel_hi:[1,0]
	v_pk_mul_f32 v[6:7], v[6:7], v[18:19] op_sel_hi:[1,0]
	v_pk_mul_f32 v[0:1], v[0:1], v[18:19] op_sel_hi:[1,0]
	v_pk_mul_f32 v[2:3], v[2:3], v[18:19] op_sel_hi:[1,0]
	v_mul_f32_e32 v18, 0xbfb8aa3b, v12
	v_mul_f32_e32 v19, 0xbfb8aa3b, v13
	v_mul_f32_e32 v20, 0xbfb8aa3b, v14
	v_mul_f32_e32 v21, 0xbfb8aa3b, v15
	v_mul_f32_e32 v22, 0xbfb8aa3b, v8
	v_mul_f32_e32 v23, 0xbfb8aa3b, v9
	v_mul_f32_e32 v24, 0xbfb8aa3b, v10
	v_mul_f32_e32 v25, 0xbfb8aa3b, v11
	v_exp_f32_e32 v18, v18
	v_exp_f32_e32 v19, v19
	v_exp_f32_e32 v20, v20
	v_exp_f32_e32 v21, v21
	v_exp_f32_e32 v22, v22
	v_exp_f32_e32 v23, v23
	v_exp_f32_e32 v24, v24
	v_exp_f32_e32 v25, v25
	v_add_f32_e32 v18, 1.0, v18
	v_add_f32_e32 v19, 1.0, v19
	v_add_f32_e32 v20, 1.0, v20
	v_add_f32_e32 v21, 1.0, v21
	v_add_f32_e32 v22, 1.0, v22
	v_add_f32_e32 v23, 1.0, v23
	v_add_f32_e32 v24, 1.0, v24
	v_add_f32_e32 v25, 1.0, v25
	v_rcp_f32_e32 v18, v18
	v_rcp_f32_e32 v19, v19
	v_rcp_f32_e32 v20, v20
	v_rcp_f32_e32 v21, v21
	v_rcp_f32_e32 v22, v22
	v_rcp_f32_e32 v23, v23
	v_rcp_f32_e32 v24, v24
	v_rcp_f32_e32 v25, v25
	v_pk_mul_f32 v[12:13], v[12:13], v[18:19]
	v_pk_mul_f32 v[14:15], v[14:15], v[20:21]
	v_pk_mul_f32 v[8:9], v[8:9], v[22:23]
	v_pk_mul_f32 v[10:11], v[10:11], v[24:25]
	v_pk_mul_f32 v[4:5], v[4:5], v[12:13]
	v_pk_mul_f32 v[6:7], v[6:7], v[14:15]
	v_pk_mul_f32 v[8:9], v[0:1], v[8:9]
	v_pk_mul_f32 v[10:11], v[2:3], v[10:11]
	v_cvt_pk_bf16_f32 v0, v4, v5
	v_cvt_pk_bf16_f32 v1, v6, v7
	v_cvt_pk_bf16_f32 v2, v8, v9
	v_cvt_pk_bf16_f32 v3, v10, v11
	global_store_dwordx4 v[16:17], v[0:3], off
	s_cbranch_vccnz .LBB0_1494
	s_andn2_b64 vcc, exec, s[12:13]
	s_cbranch_vccnz .LBB0_1493
	s_barrier
	s_branch .LBB0_1493

.LBB0_1864:
	v_lshl_add_u32 v144, s4, 8, v152
	v_ashrrev_i32_e32 v145, 31, v144
	v_lshl_add_u64 v[150:151], v[144:145], 2, s[12:13]
	global_load_dword v240, v[150:151], off
	global_load_dword v241, v[150:151], off offset:64
	global_load_dword v242, v[150:151], off offset:128
	global_load_dword v243, v[150:151], off offset:192
	global_load_dword v244, v[150:151], off offset:512
	global_load_dword v245, v[150:151], off offset:576
	global_load_dword v246, v[150:151], off offset:640
	global_load_dword v247, v[150:151], off offset:704
	v_or_b32_e32 v162, 16, v144
	v_ashrrev_i32_e32 v163, 31, v162
	v_lshl_add_u64 v[164:165], v[162:163], 2, s[12:13]
	v_lshl_add_u32 v148, s5, 7, v154
	v_mov_b64_e32 v[146:147], s[28:29]
	v_ashrrev_i32_e32 v149, 31, v148
	v_mad_i64_i32 v[160:161], s[4:5], v144, s64, v[146:147]
	v_lshlrev_b64 v[148:149], 1, v[148:149]
	v_lshl_add_u64 v[160:161], v[160:161], 0, v[148:149]
	s_waitcnt vmcnt(7)
	v_fmamk_f32 v145, v240, 0x3a800000, v158
	v_mul_f32_e32 v159, 0x4b800000, v145
	v_cmp_gt_f32_e32 vcc, s63, v145
	s_nop 1
	v_cndmask_b32_e32 v145, v145, v159, vcc
	v_rsq_f32_e32 v145, v145
	s_nop 0
	v_mul_f32_e32 v159, 0x45800000, v145
	v_cndmask_b32_e32 v166, v145, v159, vcc
	v_pk_mul_f32 v[124:125], v[124:125], v[166:167] op_sel_hi:[1,0]
	v_pk_mul_f32 v[126:127], v[126:127], v[166:167] op_sel_hi:[1,0]
	v_pk_mul_f32 v[120:121], v[120:121], v[166:167] op_sel_hi:[1,0]
	v_pk_mul_f32 v[122:123], v[122:123], v[166:167] op_sel_hi:[1,0]
	v_pk_mul_f32 v[116:117], v[116:117], v[166:167] op_sel_hi:[1,0]
	v_pk_mul_f32 v[118:119], v[118:119], v[166:167] op_sel_hi:[1,0]
	v_pk_mul_f32 v[112:113], v[112:113], v[166:167] op_sel_hi:[1,0]
	v_pk_mul_f32 v[114:115], v[114:115], v[166:167] op_sel_hi:[1,0]
	v_mul_f32_e32 v145, 0xbfb8aa3b, v124
	v_mul_f32_e32 v159, 0xbfb8aa3b, v125
	v_mul_f32_e32 v163, 0xbfb8aa3b, v126
	v_mul_f32_e32 v166, 0xbfb8aa3b, v127
	v_mul_f32_e32 v167, 0xbfb8aa3b, v120
	v_mul_f32_e32 v168, 0xbfb8aa3b, v121
	v_mul_f32_e32 v169, 0xbfb8aa3b, v122
	v_mul_f32_e32 v170, 0xbfb8aa3b, v123
	v_exp_f32_e32 v145, v145
	v_exp_f32_e32 v159, v159
	v_exp_f32_e32 v163, v163
	v_exp_f32_e32 v166, v166
	v_exp_f32_e32 v167, v167
	v_exp_f32_e32 v168, v168
	v_exp_f32_e32 v169, v169
	v_exp_f32_e32 v170, v170
	v_add_f32_e32 v145, 1.0, v145
	v_add_f32_e32 v159, 1.0, v159
	v_add_f32_e32 v163, 1.0, v163
	v_add_f32_e32 v171, 1.0, v166
	v_add_f32_e32 v172, 1.0, v167
	v_add_f32_e32 v173, 1.0, v168
	v_add_f32_e32 v174, 1.0, v169
	v_add_f32_e32 v175, 1.0, v170
	v_rcp_f32_e32 v166, v145
	v_rcp_f32_e32 v167, v159
	v_rcp_f32_e32 v168, v163
	v_rcp_f32_e32 v169, v171
	v_rcp_f32_e32 v170, v172
	v_rcp_f32_e32 v171, v173
	v_rcp_f32_e32 v172, v174
	v_rcp_f32_e32 v173, v175
	v_pk_mul_f32 v[124:125], v[124:125], v[166:167]
	v_pk_mul_f32 v[126:127], v[126:127], v[168:169]
	v_pk_mul_f32 v[120:121], v[120:121], v[170:171]
	v_pk_mul_f32 v[122:123], v[122:123], v[172:173]
	v_pk_mul_f32 v[116:117], v[116:117], v[124:125]
	v_pk_mul_f32 v[118:119], v[118:119], v[126:127]
	v_pk_mul_f32 v[120:121], v[112:113], v[120:121]
	v_pk_mul_f32 v[122:123], v[114:115], v[122:123]
	v_cvt_pk_bf16_f32 v112, v116, v117
	v_cvt_pk_bf16_f32 v113, v118, v119
	v_cvt_pk_bf16_f32 v114, v120, v121
	v_cvt_pk_bf16_f32 v115, v122, v123
	global_store_dwordx4 v[160:161], v[112:115], off
	s_nop 0
	s_nop 0
	v_or_b32_e32 v112, 32, v144
	v_mad_i64_i32 v[114:115], s[4:5], v162, s64, v[146:147]
	v_lshl_add_u64 v[114:115], v[114:115], 0, v[148:149]
	s_waitcnt vmcnt(7)
	v_fmamk_f32 v113, v241, 0x3a800000, v158
	v_mul_f32_e32 v116, 0x4b800000, v113
	v_cmp_gt_f32_e32 vcc, s63, v113
	s_nop 1
	v_cndmask_b32_e32 v113, v113, v116, vcc
	v_rsq_f32_e32 v118, v113
	v_ashrrev_i32_e32 v113, 31, v112
	v_lshl_add_u64 v[116:117], v[112:113], 2, s[12:13]
	v_mul_f32_e32 v113, 0x45800000, v118
	v_cndmask_b32_e32 v118, v118, v113, vcc
	v_pk_mul_f32 v[108:109], v[108:109], v[118:119] op_sel_hi:[1,0]
	v_pk_mul_f32 v[110:111], v[110:111], v[118:119] op_sel_hi:[1,0]
	v_pk_mul_f32 v[104:105], v[104:105], v[118:119] op_sel_hi:[1,0]
	v_pk_mul_f32 v[106:107], v[106:107], v[118:119] op_sel_hi:[1,0]
	v_pk_mul_f32 v[100:101], v[100:101], v[118:119] op_sel_hi:[1,0]
	v_pk_mul_f32 v[102:103], v[102:103], v[118:119] op_sel_hi:[1,0]
	v_pk_mul_f32 v[96:97], v[96:97], v[118:119] op_sel_hi:[1,0]
	v_pk_mul_f32 v[98:99], v[98:99], v[118:119] op_sel_hi:[1,0]
	v_mul_f32_e32 v113, 0xbfb8aa3b, v108
	v_mul_f32_e32 v118, 0xbfb8aa3b, v109
	v_mul_f32_e32 v119, 0xbfb8aa3b, v110
	v_mul_f32_e32 v120, 0xbfb8aa3b, v111
	v_mul_f32_e32 v121, 0xbfb8aa3b, v104
	v_mul_f32_e32 v122, 0xbfb8aa3b, v105
	v_mul_f32_e32 v123, 0xbfb8aa3b, v106
	v_mul_f32_e32 v124, 0xbfb8aa3b, v107
	v_exp_f32_e32 v113, v113
	v_exp_f32_e32 v118, v118
	v_exp_f32_e32 v119, v119
	v_exp_f32_e32 v120, v120
	v_exp_f32_e32 v121, v121
	v_exp_f32_e32 v122, v122
	v_exp_f32_e32 v123, v123
	v_exp_f32_e32 v124, v124
	v_add_f32_e32 v113, 1.0, v113
	v_add_f32_e32 v125, 1.0, v118
	v_add_f32_e32 v126, 1.0, v119
	v_add_f32_e32 v127, 1.0, v120
	v_add_f32_e32 v145, 1.0, v121
	v_add_f32_e32 v159, 1.0, v122
	v_add_f32_e32 v160, 1.0, v123
	v_add_f32_e32 v161, 1.0, v124
	v_rcp_f32_e32 v118, v113
	v_rcp_f32_e32 v119, v125
	v_rcp_f32_e32 v120, v126
	v_rcp_f32_e32 v121, v127
	v_rcp_f32_e32 v122, v145
	v_rcp_f32_e32 v123, v159
	v_rcp_f32_e32 v124, v160
	v_rcp_f32_e32 v125, v161
	v_pk_mul_f32 v[108:109], v[108:109], v[118:119]
	v_pk_mul_f32 v[110:111], v[110:111], v[120:121]
	v_pk_mul_f32 v[104:105], v[104:105], v[122:123]
	v_pk_mul_f32 v[106:107], v[106:107], v[124:125]
	v_pk_mul_f32 v[100:101], v[100:101], v[108:109]
	v_pk_mul_f32 v[102:103], v[102:103], v[110:111]
	v_pk_mul_f32 v[104:105], v[96:97], v[104:105]
	v_pk_mul_f32 v[106:107], v[98:99], v[106:107]
	v_cvt_pk_bf16_f32 v96, v100, v101
	v_cvt_pk_bf16_f32 v97, v102, v103
	v_cvt_pk_bf16_f32 v98, v104, v105
	v_cvt_pk_bf16_f32 v99, v106, v107
	global_store_dwordx4 v[114:115], v[96:99], off
	s_nop 0
	s_nop 0
	v_or_b32_e32 v96, 48, v144
	v_mad_i64_i32 v[98:99], s[4:5], v112, s64, v[146:147]
	v_lshl_add_u64 v[98:99], v[98:99], 0, v[148:149]
	s_waitcnt vmcnt(7)
	v_fmamk_f32 v97, v242, 0x3a800000, v158
	v_mul_f32_e32 v100, 0x4b800000, v97
	v_cmp_gt_f32_e32 vcc, s63, v97
	s_nop 1
	v_cndmask_b32_e32 v97, v97, v100, vcc
	v_rsq_f32_e32 v102, v97
	v_ashrrev_i32_e32 v97, 31, v96
	v_lshl_add_u64 v[100:101], v[96:97], 2, s[12:13]
	v_mul_f32_e32 v97, 0x45800000, v102
	v_cndmask_b32_e32 v102, v102, v97, vcc
	v_pk_mul_f32 v[92:93], v[92:93], v[102:103] op_sel_hi:[1,0]
	v_pk_mul_f32 v[94:95], v[94:95], v[102:103] op_sel_hi:[1,0]
	v_pk_mul_f32 v[88:89], v[88:89], v[102:103] op_sel_hi:[1,0]
	v_pk_mul_f32 v[90:91], v[90:91], v[102:103] op_sel_hi:[1,0]
	v_pk_mul_f32 v[84:85], v[84:85], v[102:103] op_sel_hi:[1,0]
	v_pk_mul_f32 v[86:87], v[86:87], v[102:103] op_sel_hi:[1,0]
	v_pk_mul_f32 v[80:81], v[80:81], v[102:103] op_sel_hi:[1,0]
	v_pk_mul_f32 v[82:83], v[82:83], v[102:103] op_sel_hi:[1,0]
	v_mul_f32_e32 v97, 0xbfb8aa3b, v92
	v_mul_f32_e32 v102, 0xbfb8aa3b, v93
	v_mul_f32_e32 v103, 0xbfb8aa3b, v94
	v_mul_f32_e32 v104, 0xbfb8aa3b, v95
	v_mul_f32_e32 v105, 0xbfb8aa3b, v88
	v_mul_f32_e32 v106, 0xbfb8aa3b, v89
	v_mul_f32_e32 v107, 0xbfb8aa3b, v90
	v_mul_f32_e32 v108, 0xbfb8aa3b, v91
	v_exp_f32_e32 v97, v97
	v_exp_f32_e32 v102, v102
	v_exp_f32_e32 v103, v103
	v_exp_f32_e32 v104, v104
	v_exp_f32_e32 v105, v105
	v_exp_f32_e32 v106, v106
	v_exp_f32_e32 v107, v107
	v_exp_f32_e32 v108, v108
	v_add_f32_e32 v97, 1.0, v97
	v_add_f32_e32 v109, 1.0, v102
	v_add_f32_e32 v110, 1.0, v103
	v_add_f32_e32 v111, 1.0, v104
	v_add_f32_e32 v112, 1.0, v105
	v_add_f32_e32 v113, 1.0, v106
	v_add_f32_e32 v114, 1.0, v107
	v_add_f32_e32 v115, 1.0, v108
	v_rcp_f32_e32 v102, v97
	v_rcp_f32_e32 v103, v109
	v_rcp_f32_e32 v104, v110
	v_rcp_f32_e32 v105, v111
	v_rcp_f32_e32 v106, v112
	v_rcp_f32_e32 v107, v113
	v_rcp_f32_e32 v108, v114
	v_rcp_f32_e32 v109, v115
	v_pk_mul_f32 v[92:93], v[92:93], v[102:103]
	v_pk_mul_f32 v[94:95], v[94:95], v[104:105]
	v_pk_mul_f32 v[88:89], v[88:89], v[106:107]
	v_pk_mul_f32 v[90:91], v[90:91], v[108:109]
	v_pk_mul_f32 v[84:85], v[84:85], v[92:93]
	v_pk_mul_f32 v[86:87], v[86:87], v[94:95]
	v_pk_mul_f32 v[88:89], v[80:81], v[88:89]
	v_pk_mul_f32 v[90:91], v[82:83], v[90:91]
	v_cvt_pk_bf16_f32 v80, v84, v85
	v_cvt_pk_bf16_f32 v81, v86, v87
	v_cvt_pk_bf16_f32 v82, v88, v89
	v_cvt_pk_bf16_f32 v83, v90, v91
	global_store_dwordx4 v[98:99], v[80:83], off
	s_nop 0
	s_waitcnt vmcnt(7)
	v_fmamk_f32 v80, v243, 0x3a800000, v158
	v_mul_f32_e32 v81, 0x4b800000, v80
	v_cmp_gt_f32_e32 vcc, s63, v80
	s_nop 1
	v_cndmask_b32_e32 v80, v80, v81, vcc
	v_rsq_f32_e32 v82, v80
	v_mad_i64_i32 v[80:81], s[4:5], v96, s64, v[146:147]
	v_lshl_add_u64 v[80:81], v[80:81], 0, v[148:149]
	v_mul_f32_e32 v83, 0x45800000, v82
	v_cndmask_b32_e32 v82, v82, v83, vcc
	v_pk_mul_f32 v[76:77], v[76:77], v[82:83] op_sel_hi:[1,0]
	v_pk_mul_f32 v[78:79], v[78:79], v[82:83] op_sel_hi:[1,0]
	v_pk_mul_f32 v[72:73], v[72:73], v[82:83] op_sel_hi:[1,0]
	v_pk_mul_f32 v[74:75], v[74:75], v[82:83] op_sel_hi:[1,0]
	v_pk_mul_f32 v[68:69], v[68:69], v[82:83] op_sel_hi:[1,0]
	v_pk_mul_f32 v[70:71], v[70:71], v[82:83] op_sel_hi:[1,0]
	v_pk_mul_f32 v[64:65], v[64:65], v[82:83] op_sel_hi:[1,0]
	v_pk_mul_f32 v[66:67], v[66:67], v[82:83] op_sel_hi:[1,0]
	v_mul_f32_e32 v82, 0xbfb8aa3b, v76
	v_mul_f32_e32 v83, 0xbfb8aa3b, v77
	v_mul_f32_e32 v84, 0xbfb8aa3b, v78
	v_mul_f32_e32 v85, 0xbfb8aa3b, v79
	v_mul_f32_e32 v86, 0xbfb8aa3b, v72
	v_mul_f32_e32 v87, 0xbfb8aa3b, v73
	v_mul_f32_e32 v88, 0xbfb8aa3b, v74
	v_mul_f32_e32 v89, 0xbfb8aa3b, v75
	v_exp_f32_e32 v82, v82
	v_exp_f32_e32 v83, v83
	v_exp_f32_e32 v84, v84
	v_exp_f32_e32 v85, v85
	v_exp_f32_e32 v86, v86
	v_exp_f32_e32 v87, v87
	v_exp_f32_e32 v88, v88
	v_exp_f32_e32 v89, v89
	v_add_f32_e32 v82, 1.0, v82
	v_add_f32_e32 v83, 1.0, v83
	v_add_f32_e32 v84, 1.0, v84
	v_add_f32_e32 v85, 1.0, v85
	v_add_f32_e32 v86, 1.0, v86
	v_add_f32_e32 v87, 1.0, v87
	v_add_f32_e32 v88, 1.0, v88
	v_add_f32_e32 v89, 1.0, v89
	v_rcp_f32_e32 v82, v82
	v_rcp_f32_e32 v83, v83
	v_rcp_f32_e32 v84, v84
	v_rcp_f32_e32 v85, v85
	v_rcp_f32_e32 v86, v86
	v_rcp_f32_e32 v87, v87
	v_rcp_f32_e32 v88, v88
	v_rcp_f32_e32 v89, v89
	v_pk_mul_f32 v[76:77], v[76:77], v[82:83]
	v_pk_mul_f32 v[78:79], v[78:79], v[84:85]
	v_pk_mul_f32 v[72:73], v[72:73], v[86:87]
	v_pk_mul_f32 v[74:75], v[74:75], v[88:89]
	v_pk_mul_f32 v[68:69], v[68:69], v[76:77]
	v_pk_mul_f32 v[70:71], v[70:71], v[78:79]
	v_pk_mul_f32 v[72:73], v[64:65], v[72:73]
	v_pk_mul_f32 v[74:75], v[66:67], v[74:75]
	v_cvt_pk_bf16_f32 v64, v68, v69
	v_cvt_pk_bf16_f32 v65, v70, v71
	v_cvt_pk_bf16_f32 v66, v72, v73
	v_cvt_pk_bf16_f32 v67, v74, v75
	global_store_dwordx4 v[80:81], v[64:67], off
	s_nop 0
	s_nop 0
	v_add_u32_e32 v65, 0x80, v144
	s_waitcnt vmcnt(7)
	v_fmamk_f32 v64, v244, 0x3a800000, v158
	v_mul_f32_e32 v66, 0x4b800000, v64
	v_cmp_gt_f32_e32 vcc, s63, v64
	s_nop 1
	v_cndmask_b32_e32 v64, v64, v66, vcc
	v_rsq_f32_e32 v66, v64
	v_mad_i64_i32 v[64:65], s[4:5], v65, s64, v[146:147]
	v_lshl_add_u64 v[64:65], v[64:65], 0, v[148:149]
	v_mul_f32_e32 v67, 0x45800000, v66
	v_cndmask_b32_e32 v66, v66, v67, vcc
	v_pk_mul_f32 v[60:61], v[60:61], v[66:67] op_sel_hi:[1,0]
	v_pk_mul_f32 v[62:63], v[62:63], v[66:67] op_sel_hi:[1,0]
	v_pk_mul_f32 v[56:57], v[56:57], v[66:67] op_sel_hi:[1,0]
	v_pk_mul_f32 v[58:59], v[58:59], v[66:67] op_sel_hi:[1,0]
	v_pk_mul_f32 v[52:53], v[52:53], v[66:67] op_sel_hi:[1,0]
	v_pk_mul_f32 v[54:55], v[54:55], v[66:67] op_sel_hi:[1,0]
	v_pk_mul_f32 v[48:49], v[48:49], v[66:67] op_sel_hi:[1,0]
	v_pk_mul_f32 v[50:51], v[50:51], v[66:67] op_sel_hi:[1,0]
	v_mul_f32_e32 v66, 0xbfb8aa3b, v60
	v_mul_f32_e32 v67, 0xbfb8aa3b, v61
	v_mul_f32_e32 v68, 0xbfb8aa3b, v62
	v_mul_f32_e32 v69, 0xbfb8aa3b, v63
	v_mul_f32_e32 v70, 0xbfb8aa3b, v56
	v_mul_f32_e32 v71, 0xbfb8aa3b, v57
	v_mul_f32_e32 v72, 0xbfb8aa3b, v58
	v_mul_f32_e32 v73, 0xbfb8aa3b, v59
	v_exp_f32_e32 v66, v66
	v_exp_f32_e32 v67, v67
	v_exp_f32_e32 v68, v68
	v_exp_f32_e32 v69, v69
	v_exp_f32_e32 v70, v70
	v_exp_f32_e32 v71, v71
	v_exp_f32_e32 v72, v72
	v_exp_f32_e32 v73, v73
	v_add_f32_e32 v66, 1.0, v66
	v_add_f32_e32 v67, 1.0, v67
	v_add_f32_e32 v68, 1.0, v68
	v_add_f32_e32 v69, 1.0, v69
	v_add_f32_e32 v70, 1.0, v70
	v_add_f32_e32 v71, 1.0, v71
	v_add_f32_e32 v72, 1.0, v72
	v_add_f32_e32 v73, 1.0, v73
	v_rcp_f32_e32 v66, v66
	v_rcp_f32_e32 v67, v67
	v_rcp_f32_e32 v68, v68
	v_rcp_f32_e32 v69, v69
	v_rcp_f32_e32 v70, v70
	v_rcp_f32_e32 v71, v71
	v_rcp_f32_e32 v72, v72
	v_rcp_f32_e32 v73, v73
	v_pk_mul_f32 v[60:61], v[60:61], v[66:67]
	v_pk_mul_f32 v[62:63], v[62:63], v[68:69]
	v_pk_mul_f32 v[56:57], v[56:57], v[70:71]
	v_pk_mul_f32 v[58:59], v[58:59], v[72:73]
	v_pk_mul_f32 v[52:53], v[52:53], v[60:61]
	v_pk_mul_f32 v[54:55], v[54:55], v[62:63]
	v_pk_mul_f32 v[56:57], v[48:49], v[56:57]
	v_pk_mul_f32 v[58:59], v[50:51], v[58:59]
	v_cvt_pk_bf16_f32 v48, v52, v53
	v_cvt_pk_bf16_f32 v49, v54, v55
	v_cvt_pk_bf16_f32 v50, v56, v57
	v_cvt_pk_bf16_f32 v51, v58, v59
	global_store_dwordx4 v[64:65], v[48:51], off
	s_nop 0
	s_nop 0
	v_add_u32_e32 v49, 0x90, v144
	s_waitcnt vmcnt(7)
	v_fmamk_f32 v48, v245, 0x3a800000, v158
	v_mul_f32_e32 v50, 0x4b800000, v48
	v_cmp_gt_f32_e32 vcc, s63, v48
	s_nop 1
	v_cndmask_b32_e32 v48, v48, v50, vcc
	v_rsq_f32_e32 v50, v48
	v_mad_i64_i32 v[48:49], s[4:5], v49, s64, v[146:147]
	v_lshl_add_u64 v[48:49], v[48:49], 0, v[148:149]
	v_mul_f32_e32 v51, 0x45800000, v50
	v_cndmask_b32_e32 v50, v50, v51, vcc
	v_pk_mul_f32 v[44:45], v[44:45], v[50:51] op_sel_hi:[1,0]
	v_pk_mul_f32 v[46:47], v[46:47], v[50:51] op_sel_hi:[1,0]
	v_pk_mul_f32 v[40:41], v[40:41], v[50:51] op_sel_hi:[1,0]
	v_pk_mul_f32 v[42:43], v[42:43], v[50:51] op_sel_hi:[1,0]
	v_pk_mul_f32 v[36:37], v[36:37], v[50:51] op_sel_hi:[1,0]
	v_pk_mul_f32 v[38:39], v[38:39], v[50:51] op_sel_hi:[1,0]
	v_pk_mul_f32 v[32:33], v[32:33], v[50:51] op_sel_hi:[1,0]
	v_pk_mul_f32 v[34:35], v[34:35], v[50:51] op_sel_hi:[1,0]
	v_mul_f32_e32 v50, 0xbfb8aa3b, v44
	v_mul_f32_e32 v51, 0xbfb8aa3b, v45
	v_mul_f32_e32 v52, 0xbfb8aa3b, v46
	v_mul_f32_e32 v53, 0xbfb8aa3b, v47
	v_mul_f32_e32 v54, 0xbfb8aa3b, v40
	v_mul_f32_e32 v55, 0xbfb8aa3b, v41
	v_mul_f32_e32 v56, 0xbfb8aa3b, v42
	v_mul_f32_e32 v57, 0xbfb8aa3b, v43
	v_exp_f32_e32 v50, v50
	v_exp_f32_e32 v51, v51
	v_exp_f32_e32 v52, v52
	v_exp_f32_e32 v53, v53
	v_exp_f32_e32 v54, v54
	v_exp_f32_e32 v55, v55
	v_exp_f32_e32 v56, v56
	v_exp_f32_e32 v57, v57
	v_add_f32_e32 v50, 1.0, v50
	v_add_f32_e32 v51, 1.0, v51
	v_add_f32_e32 v52, 1.0, v52
	v_add_f32_e32 v53, 1.0, v53
	v_add_f32_e32 v54, 1.0, v54
	v_add_f32_e32 v55, 1.0, v55
	v_add_f32_e32 v56, 1.0, v56
	v_add_f32_e32 v57, 1.0, v57
	v_rcp_f32_e32 v50, v50
	v_rcp_f32_e32 v51, v51
	v_rcp_f32_e32 v52, v52
	v_rcp_f32_e32 v53, v53
	v_rcp_f32_e32 v54, v54
	v_rcp_f32_e32 v55, v55
	v_rcp_f32_e32 v56, v56
	v_rcp_f32_e32 v57, v57
	v_pk_mul_f32 v[44:45], v[44:45], v[50:51]
	v_pk_mul_f32 v[46:47], v[46:47], v[52:53]
	v_pk_mul_f32 v[40:41], v[40:41], v[54:55]
	v_pk_mul_f32 v[42:43], v[42:43], v[56:57]
	v_pk_mul_f32 v[36:37], v[36:37], v[44:45]
	v_pk_mul_f32 v[38:39], v[38:39], v[46:47]
	v_pk_mul_f32 v[40:41], v[32:33], v[40:41]
	v_pk_mul_f32 v[42:43], v[34:35], v[42:43]
	v_cvt_pk_bf16_f32 v32, v36, v37
	v_cvt_pk_bf16_f32 v33, v38, v39
	v_cvt_pk_bf16_f32 v34, v40, v41
	v_cvt_pk_bf16_f32 v35, v42, v43
	global_store_dwordx4 v[48:49], v[32:35], off
	s_nop 0
	s_nop 0
	v_add_u32_e32 v33, 0xa0, v144
	s_waitcnt vmcnt(7)
	v_fmamk_f32 v32, v246, 0x3a800000, v158
	v_mul_f32_e32 v34, 0x4b800000, v32
	v_cmp_gt_f32_e32 vcc, s63, v32
	s_nop 1
	v_cndmask_b32_e32 v32, v32, v34, vcc
	v_rsq_f32_e32 v34, v32
	v_mad_i64_i32 v[32:33], s[4:5], v33, s64, v[146:147]
	v_lshl_add_u64 v[32:33], v[32:33], 0, v[148:149]
	v_mul_f32_e32 v35, 0x45800000, v34
	v_cndmask_b32_e32 v34, v34, v35, vcc
	v_pk_mul_f32 v[28:29], v[28:29], v[34:35] op_sel_hi:[1,0]
	v_pk_mul_f32 v[30:31], v[30:31], v[34:35] op_sel_hi:[1,0]
	v_pk_mul_f32 v[24:25], v[24:25], v[34:35] op_sel_hi:[1,0]
	v_pk_mul_f32 v[26:27], v[26:27], v[34:35] op_sel_hi:[1,0]
	v_pk_mul_f32 v[20:21], v[20:21], v[34:35] op_sel_hi:[1,0]
	v_pk_mul_f32 v[22:23], v[22:23], v[34:35] op_sel_hi:[1,0]
	v_pk_mul_f32 v[16:17], v[16:17], v[34:35] op_sel_hi:[1,0]
	v_pk_mul_f32 v[18:19], v[18:19], v[34:35] op_sel_hi:[1,0]
	v_mul_f32_e32 v34, 0xbfb8aa3b, v28
	v_mul_f32_e32 v35, 0xbfb8aa3b, v29
	v_mul_f32_e32 v36, 0xbfb8aa3b, v30
	v_mul_f32_e32 v37, 0xbfb8aa3b, v31
	v_mul_f32_e32 v38, 0xbfb8aa3b, v24
	v_mul_f32_e32 v39, 0xbfb8aa3b, v25
	v_mul_f32_e32 v40, 0xbfb8aa3b, v26
	v_mul_f32_e32 v41, 0xbfb8aa3b, v27
	v_exp_f32_e32 v34, v34
	v_exp_f32_e32 v35, v35
	v_exp_f32_e32 v36, v36
	v_exp_f32_e32 v37, v37
	v_exp_f32_e32 v38, v38
	v_exp_f32_e32 v39, v39
	v_exp_f32_e32 v40, v40
	v_exp_f32_e32 v41, v41
	v_add_f32_e32 v34, 1.0, v34
	v_add_f32_e32 v35, 1.0, v35
	v_add_f32_e32 v36, 1.0, v36
	v_add_f32_e32 v37, 1.0, v37
	v_add_f32_e32 v38, 1.0, v38
	v_add_f32_e32 v39, 1.0, v39
	v_add_f32_e32 v40, 1.0, v40
	v_add_f32_e32 v41, 1.0, v41
	v_rcp_f32_e32 v34, v34
	v_rcp_f32_e32 v35, v35
	v_rcp_f32_e32 v36, v36
	v_rcp_f32_e32 v37, v37
	v_rcp_f32_e32 v38, v38
	v_rcp_f32_e32 v39, v39
	v_rcp_f32_e32 v40, v40
	v_rcp_f32_e32 v41, v41
	v_pk_mul_f32 v[28:29], v[28:29], v[34:35]
	v_pk_mul_f32 v[30:31], v[30:31], v[36:37]
	v_pk_mul_f32 v[24:25], v[24:25], v[38:39]
	v_pk_mul_f32 v[26:27], v[26:27], v[40:41]
	v_pk_mul_f32 v[20:21], v[20:21], v[28:29]
	v_pk_mul_f32 v[22:23], v[22:23], v[30:31]
	v_pk_mul_f32 v[24:25], v[16:17], v[24:25]
	v_pk_mul_f32 v[26:27], v[18:19], v[26:27]
	v_cvt_pk_bf16_f32 v16, v20, v21
	v_cvt_pk_bf16_f32 v17, v22, v23
	v_cvt_pk_bf16_f32 v18, v24, v25
	v_cvt_pk_bf16_f32 v19, v26, v27
	global_store_dwordx4 v[32:33], v[16:19], off
	s_nop 0
	s_andn2_b64 vcc, exec, s[2:3]
	v_add_u32_e32 v17, 0xb0, v144
	s_mov_b64 s[2:3], -1
	s_waitcnt vmcnt(7)
	v_fmamk_f32 v16, v247, 0x3a800000, v158
	v_mul_f32_e32 v18, 0x4b800000, v16
	v_cmp_gt_f32_e64 s[4:5], s63, v16
	s_nop 1
	v_cndmask_b32_e64 v16, v16, v18, s[4:5]
	v_rsq_f32_e32 v18, v16
	v_mad_i64_i32 v[16:17], s[38:39], v17, s64, v[146:147]
	v_lshl_add_u64 v[16:17], v[16:17], 0, v[148:149]
	v_mul_f32_e32 v19, 0x45800000, v18
	v_cndmask_b32_e64 v18, v18, v19, s[4:5]
	v_pk_mul_f32 v[12:13], v[12:13], v[18:19] op_sel_hi:[1,0]
	v_pk_mul_f32 v[14:15], v[14:15], v[18:19] op_sel_hi:[1,0]
	v_pk_mul_f32 v[8:9], v[8:9], v[18:19] op_sel_hi:[1,0]
	v_pk_mul_f32 v[10:11], v[10:11], v[18:19] op_sel_hi:[1,0]
	v_pk_mul_f32 v[4:5], v[4:5], v[18:19] op_sel_hi:[1,0]
	v_pk_mul_f32 v[6:7], v[6:7], v[18:19] op_sel_hi:[1,0]
	v_pk_mul_f32 v[0:1], v[0:1], v[18:19] op_sel_hi:[1,0]
	v_pk_mul_f32 v[2:3], v[2:3], v[18:19] op_sel_hi:[1,0]
	v_mul_f32_e32 v18, 0xbfb8aa3b, v12
	v_mul_f32_e32 v19, 0xbfb8aa3b, v13
	v_mul_f32_e32 v20, 0xbfb8aa3b, v14
	v_mul_f32_e32 v21, 0xbfb8aa3b, v15
	v_mul_f32_e32 v22, 0xbfb8aa3b, v8
	v_mul_f32_e32 v23, 0xbfb8aa3b, v9
	v_mul_f32_e32 v24, 0xbfb8aa3b, v10
	v_mul_f32_e32 v25, 0xbfb8aa3b, v11
	v_exp_f32_e32 v18, v18
	v_exp_f32_e32 v19, v19
	v_exp_f32_e32 v20, v20
	v_exp_f32_e32 v21, v21
	v_exp_f32_e32 v22, v22
	v_exp_f32_e32 v23, v23
	v_exp_f32_e32 v24, v24
	v_exp_f32_e32 v25, v25
	v_add_f32_e32 v18, 1.0, v18
	v_add_f32_e32 v19, 1.0, v19
	v_add_f32_e32 v20, 1.0, v20
	v_add_f32_e32 v21, 1.0, v21
	v_add_f32_e32 v22, 1.0, v22
	v_add_f32_e32 v23, 1.0, v23
	v_add_f32_e32 v24, 1.0, v24
	v_add_f32_e32 v25, 1.0, v25
	v_rcp_f32_e32 v18, v18
	v_rcp_f32_e32 v19, v19
	v_rcp_f32_e32 v20, v20
	v_rcp_f32_e32 v21, v21
	v_rcp_f32_e32 v22, v22
	v_rcp_f32_e32 v23, v23
	v_rcp_f32_e32 v24, v24
	v_rcp_f32_e32 v25, v25
	v_pk_mul_f32 v[12:13], v[12:13], v[18:19]
	v_pk_mul_f32 v[14:15], v[14:15], v[20:21]
	v_pk_mul_f32 v[8:9], v[8:9], v[22:23]
	v_pk_mul_f32 v[10:11], v[10:11], v[24:25]
	v_pk_mul_f32 v[4:5], v[4:5], v[12:13]
	v_pk_mul_f32 v[6:7], v[6:7], v[14:15]
	v_pk_mul_f32 v[8:9], v[0:1], v[8:9]
	v_pk_mul_f32 v[10:11], v[2:3], v[10:11]
	v_cvt_pk_bf16_f32 v0, v4, v5
	v_cvt_pk_bf16_f32 v1, v6, v7
	v_cvt_pk_bf16_f32 v2, v8, v9
	v_cvt_pk_bf16_f32 v3, v10, v11
	global_store_dwordx4 v[16:17], v[0:3], off
	s_cbranch_vccnz .LBB0_1857
	s_andn2_b64 vcc, exec, s[10:11]
	s_cbranch_vccnz .LBB0_1856
	s_barrier
	s_branch .LBB0_1856
